# v21 + GEMM K-loops: B-fragment ds_read addresses from four loop-invariant base registers + offset field instead of 16 VALU address ops per loop trip
# speedup vs baseline: 1.0346x; 1.0076x over previous
;   static DI int bmap(bool perm, int R) { return perm ? ((R & ~31) + perm32(R & 31)) : R; }
; #define G_STAGE(bufoff, gbase, v0, v1) do { \
;     __builtin_amdgcn_global_load_lds((const unsigned*)((const char*)(gbase) + (v0)), (LAS unsigned*)(lds + (bufoff) + ldsw), 16, 0, 0); \
;     __builtin_amdgcn_global_load_lds((const unsigned*)((const char*)(gbase) + (v1)), (LAS unsigned*)(lds + (bufoff) + ldsw + 8192), 16, 0, 0); } while (0)
; #define G_WAIT_V(n) asm volatile("s_waitcnt vmcnt(" #n ")" ::: "memory")
; #define G_BAR __builtin_amdgcn_s_barrier()
;   static DI int bmap(bool, int R) { return ((R >> 4) & 1) * 1024 + (R >> 5) * 16 + (R & 15); }
; template <bool PERM, class Sched, class Epi>
; DI void gemm256(LAS unsigned char* lds, const Sched& S, const Epi& E, int wv_) {
;   const int tid = tid_opaque(wv_), wid = __builtin_amdgcn_readfirstlane(tid >> 6), lane = tid & 63, wr = wid >> 2, wc = wid & 3, fr = lane & 15, fq = lane >> 4;
;   unsigned cvA0, cvA1, cvB0, cvB1;
;   { int R, C;
;     stage_rc(tid * 16, R, C); cvA0 = (unsigned)R * S.lda2 + C * 2; cvB0 = (unsigned)Sched::bmap(PERM, R) * S.ldb2 + C * 2;
;     stage_rc(tid * 16 + 8192, R, C); cvA1 = (unsigned)R * S.lda2 + C * 2; cvB1 = (unsigned)Sched::bmap(PERM, R) * S.ldb2 + C * 2; }
;   const size_t chA = (size_t)HALF * S.lda2, chB = (size_t)Sched::BHALF * S.ldb2;
;   const size_t kstep = (size_t)(BK * 2);
;   const unsigned ldsw = (unsigned)wid * 1024u;
;   const int aoff = lds_byte(wr * 64 + fr, fq * 8), boff = lds_byte(wc * 32 + fr, fq * 8);
;     ...
;   G_STAGE(G_SB(0, 0), cB, cvB0, cvB1); G_STAGE(G_SA(0, 0), cA, cvA0, cvA1); G_STAGE(G_SB(0, 1), cB + chB, cvB0, cvB1); G_STAGE(G_SA(0, 1), cA + chA, cvA0, cvA1);
;   if (wr == 1) G_BAR;
;   G_WAIT_V(4); G_BAR;
;   G_STAGE(G_SB(1, 0), cB + kstep, cvB0, cvB1); G_STAGE(G_SA(1, 0), cA + kstep, cvA0, cvA1); G_STAGE(G_SB(1, 1), cB + chB + kstep, cvB0, cvB1);
;   G_WAIT_V(6); G_BAR;
.LBB0_1491:
	v_mov_b32_e32 v133, v0
	v_lshl_add_u64 v[10:11], s[12:13], 0, v[132:133]
	v_mov_b32_e32 v137, v0
	s_lshl_b32 s3, s3, 5
	s_add_i32 s29, s19, 0x18000
	v_lshl_add_u64 v[12:13], s[12:13], 0, v[136:137]
	v_mov_b32_e32 v131, v0
	v_and_b32_e32 v9, 15, v2
	v_and_b32_e32 v1, 48, v2
	v_lshlrev_b32_e32 v2, 2, v2
	s_and_b32 s28, s3, 0x60
	v_lshl_add_u64 v[10:11], v[10:11], 0, s[86:87]
	s_mov_b32 m0, s29
	s_add_i32 s30, s19, 0x1a000
	v_lshl_add_u64 v[14:15], s[10:11], 0, v[130:131]
	v_mov_b32_e32 v135, v0
	s_lshl_b32 s27, s2, 6
	s_lshl_b32 s4, s2, 13
	v_lshl_or_b32 v18, v9, 6, v1
	v_and_b32_e32 v2, 32, v2
	s_lshl_b32 s3, s28, 7
	s_waitcnt vmcnt(4)
	s_barrier
	global_load_lds_dwordx4 v[10:11], off
	v_lshl_add_u64 v[10:11], v[12:13], 0, s[86:87]
	s_mov_b32 m0, s30
	s_add_i32 s31, s19, 0x8000
	s_add_i32 s34, s19, 0xa000
	v_lshl_add_u64 v[16:17], s[10:11], 0, v[134:135]
	v_bitop3_b32 v142, v18, s4, v2 bitop3:0xde
	global_load_lds_dwordx4 v[10:11], off
	v_lshl_add_u64 v[10:11], v[14:15], 0, s[86:87]
	s_mov_b32 m0, s31
	s_add_u32 s4, s12, 0x40080
	global_load_lds_dwordx4 v[10:11], off
	v_lshl_add_u64 v[10:11], v[16:17], 0, s[86:87]
	s_mov_b32 m0, s34
	s_addc_u32 s5, s13, 0
	s_add_i32 s35, s19, 0x1c000
	global_load_lds_dwordx4 v[10:11], off
	v_lshl_add_u64 v[10:11], s[4:5], 0, v[132:133]
	s_mov_b32 m0, s35
	s_add_i32 s36, s19, 0x1e000
	global_load_lds_dwordx4 v[10:11], off
	v_lshl_add_u64 v[10:11], s[4:5], 0, v[136:137]
	s_mov_b32 m0, s36
	v_bitop3_b32 v143, s3, v18, v2 bitop3:0xf6
	v_add_u32_e32 v218, 0x10000, v143
	v_add_u32_e32 v219, 0x14000, v143
	v_add_u32_e32 v220, 0x18000, v143
	v_add_u32_e32 v221, 0x1c000, v143
	global_load_lds_dwordx4 v[10:11], off
	v_mul_u32_u24_e32 v2, 0x1200, v9
	v_or_b32_e32 v144, v2, v1
	v_lshlrev_b32_e32 v2, 14, v3
	v_and_b32_e32 v2, 0xffff8000, v2
	v_lshl_add_u32 v2, v4, 11, v2
	v_and_b32_e32 v3, 1, v3
	v_lshl_or_b32 v2, v3, 6, v2
	v_lshl_add_u32 v138, v5, 1, v2
	v_lshlrev_b32_e32 v2, 14, v6
	v_and_b32_e32 v2, 0xffff8000, v2
	s_waitcnt vmcnt(6)
	s_mul_i32 s37, s2, 0x48000
	v_readlane_b32 s2, v254, 63
	v_lshl_add_u32 v2, v7, 11, v2
	v_and_b32_e32 v3, 1, v6
	v_readlane_b32 s3, v255, 0
	s_add_u32 s52, s2, 0x380000
	v_lshl_or_b32 v2, v3, 6, v2
	v_lshlrev_b32_e32 v145, 1, v9
	s_addc_u32 s53, s3, 0
	v_mov_b32_e32 v139, v0
	v_lshl_add_u32 v140, v8, 1, v2
	v_mov_b32_e32 v141, v0
	s_mov_b32 s58, 0
	s_add_i32 s59, s19, 0xc000
	s_add_i32 s60, s19, 0xe000
	s_lshl_b32 s61, s28, 1
	s_barrier
	s_branch .LBB0_1493

; #define G_STAGE(bufoff, gbase, v0, v1) do { \
;     __builtin_amdgcn_global_load_lds((const unsigned*)((const char*)(gbase) + (v0)), (LAS unsigned*)(lds + (bufoff) + ldsw), 16, 0, 0); \
;     __builtin_amdgcn_global_load_lds((const unsigned*)((const char*)(gbase) + (v1)), (LAS unsigned*)(lds + (bufoff) + ldsw + 8192), 16, 0, 0); } while (0)
; #define G_LDA(dst, b, h) do { _Pragma("unroll") for (int m = 0; m < 4; ++m) _Pragma("unroll") for (int k = 0; k < 2; ++k) dst[m][k] = *(const LAS h8*)(lds + G_SA(b, h) + aoff + m * 2048 + k * 1024); } while (0)
; #define G_LDB(dst, b, h) do { _Pragma("unroll") for (int n = 0; n < 2; ++n) _Pragma("unroll") for (int k = 0; k < 2; ++k) dst[n][k] = *(const LAS h8*)(lds + G_SB(b, h) + boff + n * 2048 + k * 1024); } while (0)
; #define G_MMA(ai, bj, At, Bt) do { __builtin_amdgcn_s_setprio(1); _Pragma("unroll") for (int m = 0; m < 4; ++m) _Pragma("unroll") for (int n = 0; n < 2; ++n) _Pragma("unroll") for (int k = 0; k < 2; ++k) \
;     acc[ai][bj][m][n] = __builtin_amdgcn_mfma_f32_16x16x32_f16(Bt[n][k], At[m][k], acc[ai][bj][m][n], 0, 0, 0); __builtin_amdgcn_s_setprio(0); } while (0)
; #define G_WAIT_V(n) asm volatile("s_waitcnt vmcnt(" #n ")" ::: "memory")
; #define G_WAIT_L(n) asm volatile("s_waitcnt lgkmcnt(" #n ")" ::: "memory")
; #define G_BAR __builtin_amdgcn_s_barrier()
; #define G_SCHED __builtin_amdgcn_sched_barrier(0)
; template <bool PERM, class Sched, class Epi>
; DI void gemm256(LAS unsigned char* lds, const Sched& S, const Epi& E, int wv_) {
;     ...
;       G_LDB(B0, 0, 0); G_SCHED; G_LDA(At, 0, 0); G_STAGE(G_SA(1, 1), a1 + chA, cvA0, cvA1);
;       G_WAIT_L(8); G_BAR; G_WAIT_L(0); G_MMA(0, 0, At, B0); G_BAR; G_SCHED;
;       G_LDB(B1, 0, 1); G_STAGE(G_SB(0, 0), b2, cvB0, cvB1);
;       G_BAR; G_WAIT_L(0); G_MMA(0, 1, At, B1); G_BAR;
;       G_LDA(At, 0, 1); G_STAGE(G_SA(0, 0), a2, cvA0, cvA1);
;       G_BAR; G_WAIT_L(0); G_MMA(1, 0, At, B0); G_BAR; G_SCHED;
;       G_STAGE(G_SB(0, 1), b2 + chB, cvB0, cvB1);
;       G_WAIT_V(6); G_BAR; G_MMA(1, 1, At, B1); G_BAR;
;       G_LDB(B0, 1, 0); G_SCHED; G_LDA(At, 1, 0); G_STAGE(G_SA(0, 1), a2 + chA, cvA0, cvA1);
;       G_WAIT_L(8); G_BAR; G_WAIT_L(0); G_MMA(0, 0, At, B0); G_BAR; G_SCHED;
.LBB0_1503:
	s_add_i32 s91, s12, 2
	ds_read_b128 v[146:149], v218
	ds_read_b128 v[150:153], v218 offset:1024
	ds_read_b128 v[154:157], v218 offset:2048
	ds_read_b128 v[158:161], v218 offset:3072
	s_add_u32 s13, s10, 0xfffc0080
	s_addc_u32 s14, s11, -1
	s_cmp_eq_u32 s75, s12
	s_cselect_b32 s12, s90, s46
	s_cselect_b32 s15, s16, s14
	s_cselect_b32 s14, s17, s13
	s_cselect_b32 s13, s85, s74
	s_mov_b32 m0, s59
	v_lshl_add_u64 v[194:195], s[10:11], 0, v[138:139]
	ds_read_b128 v[162:165], v142
	ds_read_b128 v[166:169], v142 offset:1024
	ds_read_b128 v[170:173], v142 offset:2048
	ds_read_b128 v[174:177], v142 offset:3072
	ds_read_b128 v[178:181], v142 offset:4096
	ds_read_b128 v[182:185], v142 offset:5120
	ds_read_b128 v[186:189], v142 offset:6144
	ds_read_b128 v[190:193], v142 offset:7168
	global_load_lds_dwordx4 v[194:195], off
	v_lshl_add_u64 v[194:195], s[10:11], 0, v[140:141]
	s_mov_b32 m0, s60
	s_nop 0
	global_load_lds_dwordx4 v[194:195], off
	s_waitcnt lgkmcnt(8)
	s_barrier
	s_waitcnt lgkmcnt(0)
	s_waitcnt lgkmcnt(0)
	v_mfma_f32_16x16x32_f16 v[122:125], v[146:149], v[162:165], v[122:125]
	v_mfma_f32_16x16x32_f16 v[126:129], v[154:157], v[162:165], v[126:129]
	v_mfma_f32_16x16x32_f16 v[114:117], v[146:149], v[170:173], v[114:117]
	v_mfma_f32_16x16x32_f16 v[118:121], v[154:157], v[170:173], v[118:121]
	v_mfma_f32_16x16x32_f16 v[106:109], v[146:149], v[178:181], v[106:109]
	v_mfma_f32_16x16x32_f16 v[110:113], v[154:157], v[178:181], v[110:113]
	v_mfma_f32_16x16x32_f16 v[98:101], v[146:149], v[186:189], v[98:101]
	v_mfma_f32_16x16x32_f16 v[102:105], v[154:157], v[186:189], v[102:105]
	v_mfma_f32_16x16x32_f16 v[122:125], v[150:153], v[166:169], v[122:125]
	v_mfma_f32_16x16x32_f16 v[126:129], v[158:161], v[166:169], v[126:129]
	v_mfma_f32_16x16x32_f16 v[114:117], v[150:153], v[174:177], v[114:117]
	v_mfma_f32_16x16x32_f16 v[118:121], v[158:161], v[174:177], v[118:121]
	v_mfma_f32_16x16x32_f16 v[106:109], v[150:153], v[182:185], v[106:109]
	v_mfma_f32_16x16x32_f16 v[110:113], v[158:161], v[182:185], v[110:113]
	v_mfma_f32_16x16x32_f16 v[98:101], v[150:153], v[190:193], v[98:101]
	v_mfma_f32_16x16x32_f16 v[102:105], v[158:161], v[190:193], v[102:105]
	s_barrier
	s_mov_b32 m0, s20
	v_lshl_add_u64 v[210:211], s[12:13], 0, v[132:133]
	ds_read_b128 v[194:197], v219
	ds_read_b128 v[198:201], v219 offset:1024
	ds_read_b128 v[202:205], v219 offset:2048
	ds_read_b128 v[206:209], v219 offset:3072
	global_load_lds_dwordx4 v[210:211], off
	v_lshl_add_u64 v[212:213], s[12:13], 0, v[136:137]
	s_mov_b32 m0, s21
	s_nop 0
	global_load_lds_dwordx4 v[212:213], off
	s_barrier
	s_waitcnt lgkmcnt(0)
	s_waitcnt lgkmcnt(0)
	v_mfma_f32_16x16x32_f16 v[58:61], v[194:197], v[162:165], v[58:61]
	v_mfma_f32_16x16x32_f16 v[62:65], v[202:205], v[162:165], v[62:65]
	v_mfma_f32_16x16x32_f16 v[50:53], v[194:197], v[170:173], v[50:53]
	v_mfma_f32_16x16x32_f16 v[54:57], v[202:205], v[170:173], v[54:57]
	v_mfma_f32_16x16x32_f16 v[42:45], v[194:197], v[178:181], v[42:45]
	v_mfma_f32_16x16x32_f16 v[46:49], v[202:205], v[178:181], v[46:49]
	v_mfma_f32_16x16x32_f16 v[34:37], v[194:197], v[186:189], v[34:37]
	v_mfma_f32_16x16x32_f16 v[38:41], v[202:205], v[186:189], v[38:41]
	v_mfma_f32_16x16x32_f16 v[58:61], v[198:201], v[166:169], v[58:61]
	v_mfma_f32_16x16x32_f16 v[62:65], v[206:209], v[166:169], v[62:65]
	v_mfma_f32_16x16x32_f16 v[50:53], v[198:201], v[174:177], v[50:53]
	v_mfma_f32_16x16x32_f16 v[54:57], v[206:209], v[174:177], v[54:57]
	v_mfma_f32_16x16x32_f16 v[42:45], v[198:201], v[182:185], v[42:45]
	v_mfma_f32_16x16x32_f16 v[46:49], v[206:209], v[182:185], v[46:49]
	v_mfma_f32_16x16x32_f16 v[34:37], v[198:201], v[190:193], v[34:37]
	v_mfma_f32_16x16x32_f16 v[38:41], v[206:209], v[190:193], v[38:41]
	s_mov_b32 m0, s19
	v_lshl_add_u64 v[214:215], s[14:15], 0, v[130:131]
	s_barrier
	ds_read_b128 v[162:165], v142 offset:16384
	ds_read_b128 v[166:169], v142 offset:17408
	ds_read_b128 v[170:173], v142 offset:18432
	ds_read_b128 v[174:177], v142 offset:19456
	ds_read_b128 v[178:181], v142 offset:20480
	ds_read_b128 v[182:185], v142 offset:21504
	ds_read_b128 v[186:189], v142 offset:22528
	ds_read_b128 v[190:193], v142 offset:23552
	global_load_lds_dwordx4 v[214:215], off
	v_lshl_add_u64 v[216:217], s[14:15], 0, v[134:135]
	s_mov_b32 m0, s22
	s_nop 0
	global_load_lds_dwordx4 v[216:217], off
	s_barrier
	s_waitcnt lgkmcnt(0)
	s_waitcnt lgkmcnt(0)
	v_mfma_f32_16x16x32_f16 v[90:93], v[146:149], v[162:165], v[90:93]
	v_mfma_f32_16x16x32_f16 v[94:97], v[154:157], v[162:165], v[94:97]
	v_mfma_f32_16x16x32_f16 v[82:85], v[146:149], v[170:173], v[82:85]
	v_mfma_f32_16x16x32_f16 v[86:89], v[154:157], v[170:173], v[86:89]
	v_mfma_f32_16x16x32_f16 v[74:77], v[146:149], v[178:181], v[74:77]
	v_mfma_f32_16x16x32_f16 v[78:81], v[154:157], v[178:181], v[78:81]
	v_mfma_f32_16x16x32_f16 v[66:69], v[146:149], v[186:189], v[66:69]
	v_mfma_f32_16x16x32_f16 v[70:73], v[154:157], v[186:189], v[70:73]
	v_mfma_f32_16x16x32_f16 v[90:93], v[150:153], v[166:169], v[90:93]
	v_mfma_f32_16x16x32_f16 v[94:97], v[158:161], v[166:169], v[94:97]
	v_mfma_f32_16x16x32_f16 v[82:85], v[150:153], v[174:177], v[82:85]
	v_mfma_f32_16x16x32_f16 v[86:89], v[158:161], v[174:177], v[86:89]
	v_mfma_f32_16x16x32_f16 v[74:77], v[150:153], v[182:185], v[74:77]
	v_mfma_f32_16x16x32_f16 v[78:81], v[158:161], v[182:185], v[78:81]
	v_mfma_f32_16x16x32_f16 v[66:69], v[150:153], v[190:193], v[66:69]
	v_mfma_f32_16x16x32_f16 v[70:73], v[158:161], v[190:193], v[70:73]
	s_barrier
	s_add_u32 vcc_lo, s12, 0x40000
	s_addc_u32 vcc_hi, s13, 0
	s_mov_b32 m0, s23
	v_lshl_add_u64 v[146:147], vcc, 0, v[132:133]
	global_load_lds_dwordx4 v[146:147], off
	v_lshl_add_u64 v[146:147], vcc, 0, v[136:137]
	s_mov_b32 m0, s24
	s_nop 0
	global_load_lds_dwordx4 v[146:147], off
	s_waitcnt vmcnt(6)
	s_barrier
; #define G_STAGE(bufoff, gbase, v0, v1) do { \
;     __builtin_amdgcn_global_load_lds((const unsigned*)((const char*)(gbase) + (v0)), (LAS unsigned*)(lds + (bufoff) + ldsw), 16, 0, 0); \
;     __builtin_amdgcn_global_load_lds((const unsigned*)((const char*)(gbase) + (v1)), (LAS unsigned*)(lds + (bufoff) + ldsw + 8192), 16, 0, 0); } while (0)
; #define G_LDA(dst, b, h) do { _Pragma("unroll") for (int m = 0; m < 4; ++m) _Pragma("unroll") for (int k = 0; k < 2; ++k) dst[m][k] = *(const LAS h8*)(lds + G_SA(b, h) + aoff + m * 2048 + k * 1024); } while (0)
; #define G_LDB(dst, b, h) do { _Pragma("unroll") for (int n = 0; n < 2; ++n) _Pragma("unroll") for (int k = 0; k < 2; ++k) dst[n][k] = *(const LAS h8*)(lds + G_SB(b, h) + boff + n * 2048 + k * 1024); } while (0)
; #define G_MMA(ai, bj, At, Bt) do { __builtin_amdgcn_s_setprio(1); _Pragma("unroll") for (int m = 0; m < 4; ++m) _Pragma("unroll") for (int n = 0; n < 2; ++n) _Pragma("unroll") for (int k = 0; k < 2; ++k) \
;     acc[ai][bj][m][n] = __builtin_amdgcn_mfma_f32_16x16x32_f16(Bt[n][k], At[m][k], acc[ai][bj][m][n], 0, 0, 0); __builtin_amdgcn_s_setprio(0); } while (0)
; #define G_WAIT_V(n) asm volatile("s_waitcnt vmcnt(" #n ")" ::: "memory")
; #define G_WAIT_L(n) asm volatile("s_waitcnt lgkmcnt(" #n ")" ::: "memory")
; #define G_BAR __builtin_amdgcn_s_barrier()
; #define G_SCHED __builtin_amdgcn_sched_barrier(0)
; template <bool PERM, class Sched, class Epi>
; DI void gemm256(LAS unsigned char* lds, const Sched& S, const Epi& E, int wv_) {
;     ...
;       G_STAGE(G_SB(0, 1), b2 + chB, cvB0, cvB1);
;       G_WAIT_V(6); G_BAR; G_MMA(1, 1, At, B1); G_BAR;
;       G_LDB(B0, 1, 0); G_SCHED; G_LDA(At, 1, 0); G_STAGE(G_SA(0, 1), a2 + chA, cvA0, cvA1);
;       G_WAIT_L(8); G_BAR; G_WAIT_L(0); G_MMA(0, 0, At, B0); G_BAR; G_SCHED;
;       G_LDB(B1, 1, 1); G_STAGE(G_SB(1, 0), b3, cvB0, cvB1);
;       G_BAR; G_WAIT_L(0); G_MMA(0, 1, At, B1); G_BAR;
;       G_LDA(At, 1, 1); G_STAGE(G_SA(1, 0), a3, cvA0, cvA1);
;       G_BAR; G_WAIT_L(0); G_MMA(1, 0, At, B0); G_BAR; G_SCHED;
	v_mfma_f32_16x16x32_f16 v[26:29], v[194:197], v[162:165], v[26:29]
	v_mfma_f32_16x16x32_f16 v[30:33], v[202:205], v[162:165], v[30:33]
	v_mfma_f32_16x16x32_f16 v[18:21], v[194:197], v[170:173], v[18:21]
	v_mfma_f32_16x16x32_f16 v[22:25], v[202:205], v[170:173], v[22:25]
	v_mfma_f32_16x16x32_f16 v[10:13], v[194:197], v[178:181], v[10:13]
	v_mfma_f32_16x16x32_f16 v[14:17], v[202:205], v[178:181], v[14:17]
	v_mfma_f32_16x16x32_f16 v[6:9], v[194:197], v[186:189], v[6:9]
	v_mfma_f32_16x16x32_f16 v[2:5], v[202:205], v[186:189], v[2:5]
	v_mfma_f32_16x16x32_f16 v[26:29], v[198:201], v[166:169], v[26:29]
	v_mfma_f32_16x16x32_f16 v[30:33], v[206:209], v[166:169], v[30:33]
	v_mfma_f32_16x16x32_f16 v[18:21], v[198:201], v[174:177], v[18:21]
	v_mfma_f32_16x16x32_f16 v[22:25], v[206:209], v[174:177], v[22:25]
	v_mfma_f32_16x16x32_f16 v[10:13], v[198:201], v[182:185], v[10:13]
	v_mfma_f32_16x16x32_f16 v[14:17], v[206:209], v[182:185], v[14:17]
	v_mfma_f32_16x16x32_f16 v[6:9], v[198:201], v[190:193], v[6:9]
	v_mfma_f32_16x16x32_f16 v[2:5], v[206:209], v[190:193], v[2:5]
	s_barrier
	ds_read_b128 v[146:149], v220
	ds_read_b128 v[150:153], v220 offset:1024
	ds_read_b128 v[154:157], v220 offset:2048
	ds_read_b128 v[158:161], v220 offset:3072
	s_add_u32 s14, s14, 0x40000
	s_addc_u32 s15, s15, 0
	s_mov_b32 m0, s25
	v_lshl_add_u64 v[194:195], s[14:15], 0, v[130:131]
	ds_read_b128 v[162:165], v142 offset:32768
	ds_read_b128 v[166:169], v142 offset:33792
	ds_read_b128 v[170:173], v142 offset:34816
	ds_read_b128 v[174:177], v142 offset:35840
	ds_read_b128 v[178:181], v142 offset:36864
	ds_read_b128 v[182:185], v142 offset:37888
	ds_read_b128 v[186:189], v142 offset:38912
	ds_read_b128 v[190:193], v142 offset:39936
	global_load_lds_dwordx4 v[194:195], off
	v_lshl_add_u64 v[194:195], s[14:15], 0, v[134:135]
	s_mov_b32 m0, s26
	s_nop 0
	global_load_lds_dwordx4 v[194:195], off
	s_waitcnt lgkmcnt(8)
	s_barrier
	s_waitcnt lgkmcnt(0)
	s_waitcnt lgkmcnt(0)
	v_mfma_f32_16x16x32_f16 v[122:125], v[146:149], v[162:165], v[122:125]
	v_mfma_f32_16x16x32_f16 v[126:129], v[154:157], v[162:165], v[126:129]
	v_mfma_f32_16x16x32_f16 v[114:117], v[146:149], v[170:173], v[114:117]
	v_mfma_f32_16x16x32_f16 v[118:121], v[154:157], v[170:173], v[118:121]
	v_mfma_f32_16x16x32_f16 v[106:109], v[146:149], v[178:181], v[106:109]
	v_mfma_f32_16x16x32_f16 v[110:113], v[154:157], v[178:181], v[110:113]
	v_mfma_f32_16x16x32_f16 v[98:101], v[146:149], v[186:189], v[98:101]
	v_mfma_f32_16x16x32_f16 v[102:105], v[154:157], v[186:189], v[102:105]
	v_mfma_f32_16x16x32_f16 v[122:125], v[150:153], v[166:169], v[122:125]
	v_mfma_f32_16x16x32_f16 v[126:129], v[158:161], v[166:169], v[126:129]
	v_mfma_f32_16x16x32_f16 v[114:117], v[150:153], v[174:177], v[114:117]
	v_mfma_f32_16x16x32_f16 v[118:121], v[158:161], v[174:177], v[118:121]
	v_mfma_f32_16x16x32_f16 v[106:109], v[150:153], v[182:185], v[106:109]
	v_mfma_f32_16x16x32_f16 v[110:113], v[158:161], v[182:185], v[110:113]
	v_mfma_f32_16x16x32_f16 v[98:101], v[150:153], v[190:193], v[98:101]
	v_mfma_f32_16x16x32_f16 v[102:105], v[158:161], v[190:193], v[102:105]
	s_barrier
	s_mov_b32 m0, s29
	v_lshl_add_u64 v[210:211], v[210:211], 0, s[86:87]
	ds_read_b128 v[194:197], v221
	ds_read_b128 v[198:201], v221 offset:1024
	ds_read_b128 v[202:205], v221 offset:2048
	ds_read_b128 v[206:209], v221 offset:3072
	global_load_lds_dwordx4 v[210:211], off
	v_lshl_add_u64 v[210:211], v[212:213], 0, s[86:87]
	s_mov_b32 m0, s30
	s_nop 0
	global_load_lds_dwordx4 v[210:211], off
	s_barrier
; #define G_STAGE(bufoff, gbase, v0, v1) do { \
;     __builtin_amdgcn_global_load_lds((const unsigned*)((const char*)(gbase) + (v0)), (LAS unsigned*)(lds + (bufoff) + ldsw), 16, 0, 0); \
;     __builtin_amdgcn_global_load_lds((const unsigned*)((const char*)(gbase) + (v1)), (LAS unsigned*)(lds + (bufoff) + ldsw + 8192), 16, 0, 0); } while (0)
; #define G_LDA(dst, b, h) do { _Pragma("unroll") for (int m = 0; m < 4; ++m) _Pragma("unroll") for (int k = 0; k < 2; ++k) dst[m][k] = *(const LAS h8*)(lds + G_SA(b, h) + aoff + m * 2048 + k * 1024); } while (0)
; #define G_MMA(ai, bj, At, Bt) do { __builtin_amdgcn_s_setprio(1); _Pragma("unroll") for (int m = 0; m < 4; ++m) _Pragma("unroll") for (int n = 0; n < 2; ++n) _Pragma("unroll") for (int k = 0; k < 2; ++k) \
;     acc[ai][bj][m][n] = __builtin_amdgcn_mfma_f32_16x16x32_f16(Bt[n][k], At[m][k], acc[ai][bj][m][n], 0, 0, 0); __builtin_amdgcn_s_setprio(0); } while (0)
; #define G_WAIT_V(n) asm volatile("s_waitcnt vmcnt(" #n ")" ::: "memory")
; #define G_WAIT_L(n) asm volatile("s_waitcnt lgkmcnt(" #n ")" ::: "memory")
; #define G_BAR __builtin_amdgcn_s_barrier()
; #define G_SCHED __builtin_amdgcn_sched_barrier(0)
; template <bool PERM, class Sched, class Epi>
; DI void gemm256(LAS unsigned char* lds, const Sched& S, const Epi& E, int wv_) {
;     ...
;       G_LDA(At, 1, 1); G_STAGE(G_SA(1, 0), a3, cvA0, cvA1);
;       G_BAR; G_WAIT_L(0); G_MMA(1, 0, At, B0); G_BAR; G_SCHED;
;       G_STAGE(G_SB(1, 1), b3 + chB, cvB0, cvB1);
;       G_WAIT_V(6); G_BAR; G_MMA(1, 1, At, B1); G_BAR;
;     }
;     bool keep = false;
;     if constexpr (Sched::CHAIN) keep = E(acc, cur, wr, wc, fr, fq); else E(acc, cur, wr, wc, fr, fq);
	s_waitcnt lgkmcnt(0)
	s_waitcnt lgkmcnt(0)
	v_mfma_f32_16x16x32_f16 v[58:61], v[194:197], v[162:165], v[58:61]
	v_mfma_f32_16x16x32_f16 v[62:65], v[202:205], v[162:165], v[62:65]
	v_mfma_f32_16x16x32_f16 v[50:53], v[194:197], v[170:173], v[50:53]
	v_mfma_f32_16x16x32_f16 v[54:57], v[202:205], v[170:173], v[54:57]
	v_mfma_f32_16x16x32_f16 v[42:45], v[194:197], v[178:181], v[42:45]
	v_mfma_f32_16x16x32_f16 v[46:49], v[202:205], v[178:181], v[46:49]
	v_mfma_f32_16x16x32_f16 v[34:37], v[194:197], v[186:189], v[34:37]
	v_mfma_f32_16x16x32_f16 v[38:41], v[202:205], v[186:189], v[38:41]
	v_mfma_f32_16x16x32_f16 v[58:61], v[198:201], v[166:169], v[58:61]
	v_mfma_f32_16x16x32_f16 v[62:65], v[206:209], v[166:169], v[62:65]
	v_mfma_f32_16x16x32_f16 v[50:53], v[198:201], v[174:177], v[50:53]
	v_mfma_f32_16x16x32_f16 v[54:57], v[206:209], v[174:177], v[54:57]
	v_mfma_f32_16x16x32_f16 v[42:45], v[198:201], v[182:185], v[42:45]
	v_mfma_f32_16x16x32_f16 v[46:49], v[206:209], v[182:185], v[46:49]
	v_mfma_f32_16x16x32_f16 v[34:37], v[198:201], v[190:193], v[34:37]
	v_mfma_f32_16x16x32_f16 v[38:41], v[206:209], v[190:193], v[38:41]
	s_mov_b32 m0, s31
	v_lshl_add_u64 v[210:211], v[214:215], 0, s[86:87]
	s_barrier
	ds_read_b128 v[162:165], v142 offset:49152
	ds_read_b128 v[166:169], v142 offset:50176
	ds_read_b128 v[170:173], v142 offset:51200
	ds_read_b128 v[174:177], v142 offset:52224
	ds_read_b128 v[178:181], v142 offset:53248
	ds_read_b128 v[182:185], v142 offset:54272
	ds_read_b128 v[186:189], v142 offset:55296
	ds_read_b128 v[190:193], v142 offset:56320
	global_load_lds_dwordx4 v[210:211], off
	v_lshl_add_u64 v[210:211], v[216:217], 0, s[86:87]
	s_mov_b32 m0, s34
	s_nop 0
	global_load_lds_dwordx4 v[210:211], off
	s_barrier
	s_waitcnt lgkmcnt(0)
	s_waitcnt lgkmcnt(0)
	v_mfma_f32_16x16x32_f16 v[90:93], v[146:149], v[162:165], v[90:93]
	v_mfma_f32_16x16x32_f16 v[94:97], v[154:157], v[162:165], v[94:97]
	v_mfma_f32_16x16x32_f16 v[82:85], v[146:149], v[170:173], v[82:85]
	v_mfma_f32_16x16x32_f16 v[86:89], v[154:157], v[170:173], v[86:89]
	v_mfma_f32_16x16x32_f16 v[74:77], v[146:149], v[178:181], v[74:77]
	v_mfma_f32_16x16x32_f16 v[78:81], v[154:157], v[178:181], v[78:81]
	v_mfma_f32_16x16x32_f16 v[66:69], v[146:149], v[186:189], v[66:69]
	v_mfma_f32_16x16x32_f16 v[70:73], v[154:157], v[186:189], v[70:73]
	v_mfma_f32_16x16x32_f16 v[90:93], v[150:153], v[166:169], v[90:93]
	v_mfma_f32_16x16x32_f16 v[94:97], v[158:161], v[166:169], v[94:97]
	v_mfma_f32_16x16x32_f16 v[82:85], v[150:153], v[174:177], v[82:85]
	v_mfma_f32_16x16x32_f16 v[86:89], v[158:161], v[174:177], v[86:89]
	v_mfma_f32_16x16x32_f16 v[74:77], v[150:153], v[182:185], v[74:77]
	v_mfma_f32_16x16x32_f16 v[78:81], v[158:161], v[182:185], v[78:81]
	v_mfma_f32_16x16x32_f16 v[66:69], v[150:153], v[190:193], v[66:69]
	v_mfma_f32_16x16x32_f16 v[70:73], v[158:161], v[190:193], v[70:73]
	s_barrier
	s_add_u32 s12, s12, 0x40080
	s_addc_u32 s13, s13, 0
	s_mov_b32 m0, s35
	v_lshl_add_u64 v[146:147], s[12:13], 0, v[132:133]
	global_load_lds_dwordx4 v[146:147], off
	v_lshl_add_u64 v[146:147], s[12:13], 0, v[136:137]
	s_mov_b32 m0, s36
	s_nop 0
	global_load_lds_dwordx4 v[146:147], off
	s_waitcnt vmcnt(6)
	s_barrier
	v_mfma_f32_16x16x32_f16 v[26:29], v[194:197], v[162:165], v[26:29]
	v_mfma_f32_16x16x32_f16 v[30:33], v[202:205], v[162:165], v[30:33]
	v_mfma_f32_16x16x32_f16 v[18:21], v[194:197], v[170:173], v[18:21]
	v_mfma_f32_16x16x32_f16 v[22:25], v[202:205], v[170:173], v[22:25]
	v_mfma_f32_16x16x32_f16 v[10:13], v[194:197], v[178:181], v[10:13]
	v_mfma_f32_16x16x32_f16 v[14:17], v[202:205], v[178:181], v[14:17]
	v_mfma_f32_16x16x32_f16 v[6:9], v[194:197], v[186:189], v[6:9]
	v_mfma_f32_16x16x32_f16 v[2:5], v[202:205], v[186:189], v[2:5]
	v_mfma_f32_16x16x32_f16 v[26:29], v[198:201], v[166:169], v[26:29]
	v_mfma_f32_16x16x32_f16 v[30:33], v[206:209], v[166:169], v[30:33]
	v_mfma_f32_16x16x32_f16 v[18:21], v[198:201], v[174:177], v[18:21]
	v_mfma_f32_16x16x32_f16 v[22:25], v[206:209], v[174:177], v[22:25]
	v_mfma_f32_16x16x32_f16 v[10:13], v[198:201], v[182:185], v[10:13]
	v_mfma_f32_16x16x32_f16 v[14:17], v[206:209], v[182:185], v[14:17]
	v_mfma_f32_16x16x32_f16 v[6:9], v[198:201], v[190:193], v[6:9]
	v_mfma_f32_16x16x32_f16 v[2:5], v[206:209], v[190:193], v[2:5]
	s_add_u32 s10, s10, 0x100
	s_addc_u32 s11, s11, 0
	s_add_u32 s46, s46, 0x100
	s_addc_u32 s74, s74, 0
	s_cmp_ge_i32 s91, s7
	s_mov_b32 s12, s91
	s_barrier
	s_cbranch_scc0 .LBB0_1503
	v_readlane_b32 s91, v254, 47
	s_movk_i32 s85, 0x800
	s_xor_b64 s[8:9], s[8:9], -1
	s_cmp_lg_u32 s84, 0
	s_cbranch_scc0 .LBB0_1509

;   static DI int bmap(bool perm, int R) { return perm ? ((R & ~31) + perm32(R & 31)) : R; }
; #define G_STAGE(bufoff, gbase, v0, v1) do { \
;     __builtin_amdgcn_global_load_lds((const unsigned*)((const char*)(gbase) + (v0)), (LAS unsigned*)(lds + (bufoff) + ldsw), 16, 0, 0); \
;     __builtin_amdgcn_global_load_lds((const unsigned*)((const char*)(gbase) + (v1)), (LAS unsigned*)(lds + (bufoff) + ldsw + 8192), 16, 0, 0); } while (0)
; #define G_WAIT_V(n) asm volatile("s_waitcnt vmcnt(" #n ")" ::: "memory")
; #define G_BAR __builtin_amdgcn_s_barrier()
;   static DI int bmap(bool, int R) { return ((R >> 4) & 1) * 1024 + (R >> 5) * 16 + (R & 15); }
; template <bool PERM, class Sched, class Epi>
; DI void gemm256(LAS unsigned char* lds, const Sched& S, const Epi& E, int wv_) {
;   const int tid = tid_opaque(wv_), wid = __builtin_amdgcn_readfirstlane(tid >> 6), lane = tid & 63, wr = wid >> 2, wc = wid & 3, fr = lane & 15, fq = lane >> 4;
;   unsigned cvA0, cvA1, cvB0, cvB1;
;   { int R, C;
;     stage_rc(tid * 16, R, C); cvA0 = (unsigned)R * S.lda2 + C * 2; cvB0 = (unsigned)Sched::bmap(PERM, R) * S.ldb2 + C * 2;
;     stage_rc(tid * 16 + 8192, R, C); cvA1 = (unsigned)R * S.lda2 + C * 2; cvB1 = (unsigned)Sched::bmap(PERM, R) * S.ldb2 + C * 2; }
;   const size_t chA = (size_t)HALF * S.lda2, chB = (size_t)Sched::BHALF * S.ldb2;
;   const size_t kstep = (size_t)(BK * 2);
;   const unsigned ldsw = (unsigned)wid * 1024u;
;   const int aoff = lds_byte(wr * 64 + fr, fq * 8), boff = lds_byte(wc * 32 + fr, fq * 8);
;     ...
;   GUnit cur, nxt;
;   int ui = 0;
;   if (!S.next(0, cur)) return;
;   f4 acc[2][2][4][2];
; #pragma unroll
;   for (int a = 0; a < 2; ++a)
; #pragma unroll
;     for (int b = 0; b < 2; ++b)
; #pragma unroll
;       for (int m = 0; m < 4; ++m)
; #pragma unroll
;         for (int n = 0; n < 2; ++n) acc[a][b][m][n] = f4{0.f, 0.f, 0.f, 0.f};
;   h8 At[4][2], B0[2][2], B1[2][2];
;   const char* cA = cur.A;
;   const char* cB = cur.B;
;   G_STAGE(G_SB(0, 0), cB, cvB0, cvB1); G_STAGE(G_SA(0, 0), cA, cvA0, cvA1); G_STAGE(G_SB(0, 1), cB + chB, cvB0, cvB1); G_STAGE(G_SA(0, 1), cA + chA, cvA0, cvA1);
;   if (wr == 1) G_BAR;
;   G_WAIT_V(4); G_BAR;
;   G_STAGE(G_SB(1, 0), cB + kstep, cvB0, cvB1); G_STAGE(G_SA(1, 0), cA + kstep, cvA0, cvA1); G_STAGE(G_SB(1, 1), cB + chB + kstep, cvB0, cvB1);
;   G_WAIT_V(6); G_BAR;
.LBB0_1709:
	v_and_b32_e32 v16, 15, v1
	v_and_b32_e32 v17, 48, v1
	v_lshlrev_b32_e32 v1, 2, v1
	v_mov_b32_e32 v133, v0
	s_lshl_b32 s27, s2, 6
	s_lshl_b32 s2, s2, 13
	v_lshl_or_b32 v18, v16, 6, v17
	v_and_b32_e32 v19, 32, v1
	v_lshl_add_u64 v[8:9], s[12:13], 0, v[132:133]
	v_mov_b32_e32 v137, v0
	v_bitop3_b32 v1, v18, s2, v19 bitop3:0xde
	s_lshl_b32 s2, s4, 5
	s_add_i32 s29, s19, 0x18000
	v_lshl_add_u64 v[10:11], s[12:13], 0, v[136:137]
	v_mov_b32_e32 v131, v0
	s_and_b32 s28, s2, 0x60
	v_lshl_add_u64 v[8:9], v[8:9], 0, s[86:87]
	s_mov_b32 m0, s29
	s_add_i32 s30, s19, 0x1a000
	v_lshl_add_u64 v[12:13], s[10:11], 0, v[130:131]
	v_mov_b32_e32 v135, v0
	s_lshl_b32 s2, s28, 7
	s_waitcnt vmcnt(4)
	s_barrier
	global_load_lds_dwordx4 v[8:9], off
	v_lshl_add_u64 v[8:9], v[10:11], 0, s[86:87]
	s_mov_b32 m0, s30
	s_add_i32 s31, s19, 0x8000
	s_add_i32 s34, s19, 0xa000
	v_lshl_add_u64 v[14:15], s[10:11], 0, v[134:135]
	v_bitop3_b32 v142, s2, v18, v19 bitop3:0xf6
	v_add_u32_e32 v216, 0x10000, v142
	v_add_u32_e32 v217, 0x14000, v142
	v_add_u32_e32 v218, 0x18000, v142
	v_add_u32_e32 v219, 0x1c000, v142
	global_load_lds_dwordx4 v[8:9], off
	v_lshl_add_u64 v[8:9], v[12:13], 0, s[86:87]
	s_mov_b32 m0, s31
	s_add_u32 s2, s12, 0x10080
	global_load_lds_dwordx4 v[8:9], off
	v_lshl_add_u64 v[8:9], v[14:15], 0, s[86:87]
	s_mov_b32 m0, s34
	s_addc_u32 s3, s13, 0
	s_add_i32 s35, s19, 0x1c000
	global_load_lds_dwordx4 v[8:9], off
	v_lshl_add_u64 v[8:9], s[2:3], 0, v[132:133]
	s_mov_b32 m0, s35
	s_add_i32 s37, s19, 0x1e000
	global_load_lds_dwordx4 v[8:9], off
	v_lshl_add_u64 v[8:9], s[2:3], 0, v[136:137]
	s_mov_b32 m0, s37
	v_readlane_b32 s6, v254, 63
	global_load_lds_dwordx4 v[8:9], off
	v_readlane_b32 s7, v255, 0
	s_add_u32 s2, s6, 0x2140000
	s_addc_u32 s3, s7, 0
	s_add_u32 s52, s6, 0x2100000
	v_mul_u32_u24_e32 v8, 0xc0, v16
	s_addc_u32 s53, s7, 0
	s_lshl_b32 s4, s4, 6
	v_or_b32_e32 v143, v8, v17
	s_and_b32 s4, s4, 64
	v_lshrrev_b32_e32 v9, 1, v2
	v_mul_lo_u32 v8, v3, s8
	s_movk_i32 s6, 0x2c00
	v_and_b32_e32 v2, 1, v2
	s_add_u32 s56, s94, s4
	v_mad_u64_u32 v[8:9], s[4:5], v9, s6, v[8:9]
	v_lshlrev_b32_e32 v2, 6, v2
	v_lshlrev_b32_e32 v3, 1, v4
	v_add3_u32 v138, v8, v2, v3
	v_lshrrev_b32_e32 v3, 1, v5
	v_mul_lo_u32 v2, v6, s8
	v_mad_u64_u32 v[2:3], s[4:5], v3, s6, v[2:3]
	s_waitcnt vmcnt(6)
	v_and_b32_e32 v3, 1, v5
	v_lshlrev_b32_e32 v3, 6, v3
	v_lshlrev_b32_e32 v4, 1, v7
	s_addc_u32 s58, s95, 0
	v_mov_b32_e32 v139, v0
	v_add3_u32 v140, v2, v3, v4
	v_mov_b32_e32 v141, v0
	s_mov_b32 s59, 0
	s_barrier
	s_branch .LBB0_1711

; #define G_STAGE(bufoff, gbase, v0, v1) do { \
;     __builtin_amdgcn_global_load_lds((const unsigned*)((const char*)(gbase) + (v0)), (LAS unsigned*)(lds + (bufoff) + ldsw), 16, 0, 0); \
;     __builtin_amdgcn_global_load_lds((const unsigned*)((const char*)(gbase) + (v1)), (LAS unsigned*)(lds + (bufoff) + ldsw + 8192), 16, 0, 0); } while (0)
; #define G_LDA(dst, b, h) do { _Pragma("unroll") for (int m = 0; m < 4; ++m) _Pragma("unroll") for (int k = 0; k < 2; ++k) dst[m][k] = *(const LAS h8*)(lds + G_SA(b, h) + aoff + m * 2048 + k * 1024); } while (0)
; #define G_LDB(dst, b, h) do { _Pragma("unroll") for (int n = 0; n < 2; ++n) _Pragma("unroll") for (int k = 0; k < 2; ++k) dst[n][k] = *(const LAS h8*)(lds + G_SB(b, h) + boff + n * 2048 + k * 1024); } while (0)
; #define G_MMA(ai, bj, At, Bt) do { __builtin_amdgcn_s_setprio(1); _Pragma("unroll") for (int m = 0; m < 4; ++m) _Pragma("unroll") for (int n = 0; n < 2; ++n) _Pragma("unroll") for (int k = 0; k < 2; ++k) \
;     acc[ai][bj][m][n] = __builtin_amdgcn_mfma_f32_16x16x32_f16(Bt[n][k], At[m][k], acc[ai][bj][m][n], 0, 0, 0); __builtin_amdgcn_s_setprio(0); } while (0)
; #define G_WAIT_V(n) asm volatile("s_waitcnt vmcnt(" #n ")" ::: "memory")
; #define G_WAIT_L(n) asm volatile("s_waitcnt lgkmcnt(" #n ")" ::: "memory")
; #define G_BAR __builtin_amdgcn_s_barrier()
; #define G_SCHED __builtin_amdgcn_sched_barrier(0)
; template <bool PERM, class Sched, class Epi>
; DI void gemm256(LAS unsigned char* lds, const Sched& S, const Epi& E, int wv_) {
;     ...
;       const bool last = (t == nt - 2);
;       const char* a1 = cA + (size_t)(t + 1) * kstep;
;       const char* a2 = last ? nA : cA + (size_t)(t + 2) * kstep;
;       const char* b2 = last ? nB : cB + (size_t)(t + 2) * kstep;
;       const char* a3 = a2 + kstep;
;       const char* b3 = b2 + kstep;
;       G_LDB(B0, 0, 0); G_SCHED; G_LDA(At, 0, 0); G_STAGE(G_SA(1, 1), a1 + chA, cvA0, cvA1);
;       G_WAIT_L(8); G_BAR; G_WAIT_L(0); G_MMA(0, 0, At, B0); G_BAR; G_SCHED;
;       G_LDB(B1, 0, 1); G_STAGE(G_SB(0, 0), b2, cvB0, cvB1);
;       G_BAR; G_WAIT_L(0); G_MMA(0, 1, At, B1); G_BAR;
;       G_LDA(At, 0, 1); G_STAGE(G_SA(0, 0), a2, cvA0, cvA1);
;       G_BAR; G_WAIT_L(0); G_MMA(1, 0, At, B0); G_BAR; G_SCHED;
;       G_STAGE(G_SB(0, 1), b2 + chB, cvB0, cvB1);
;       G_WAIT_V(6); G_BAR; G_MMA(1, 1, At, B1); G_BAR;
.LBB0_1718:
	s_add_i32 s74, s12, 2
	ds_read_b128 v[144:147], v216
	ds_read_b128 v[148:151], v216 offset:1024
	ds_read_b128 v[152:155], v216 offset:2048
	ds_read_b128 v[156:159], v216 offset:3072
	s_add_u32 s13, s10, 0xfffea080
	s_addc_u32 s14, s11, -1
	s_cmp_eq_u32 vcc_lo, s12
	s_cselect_b32 s12, s93, s75
	s_cselect_b32 s15, s84, s14
	s_cselect_b32 s14, s85, s13
	s_cselect_b32 s13, s90, s46
	v_lshl_add_u64 v[192:193], s[10:11], 0, v[138:139]
	s_add_i32 m0, s19, 0xc000
	ds_read_b128 v[160:163], v1
	ds_read_b128 v[164:167], v1 offset:1024
	ds_read_b128 v[168:171], v1 offset:2048
	ds_read_b128 v[172:175], v1 offset:3072
	ds_read_b128 v[176:179], v1 offset:4096
	ds_read_b128 v[180:183], v1 offset:5120
	ds_read_b128 v[184:187], v1 offset:6144
	ds_read_b128 v[188:191], v1 offset:7168
	global_load_lds_dwordx4 v[192:193], off
	v_lshl_add_u64 v[192:193], s[10:11], 0, v[140:141]
	s_add_i32 m0, s19, 0xe000
	s_nop 0
	global_load_lds_dwordx4 v[192:193], off
	s_waitcnt lgkmcnt(8)
	s_barrier
	s_waitcnt lgkmcnt(0)
	s_waitcnt lgkmcnt(0)
	v_mfma_f32_16x16x32_f16 v[122:125], v[144:147], v[160:163], v[122:125]
	v_mfma_f32_16x16x32_f16 v[126:129], v[152:155], v[160:163], v[126:129]
	v_mfma_f32_16x16x32_f16 v[114:117], v[144:147], v[168:171], v[114:117]
	v_mfma_f32_16x16x32_f16 v[118:121], v[152:155], v[168:171], v[118:121]
	v_mfma_f32_16x16x32_f16 v[106:109], v[144:147], v[176:179], v[106:109]
	v_mfma_f32_16x16x32_f16 v[110:113], v[152:155], v[176:179], v[110:113]
	v_mfma_f32_16x16x32_f16 v[98:101], v[144:147], v[184:187], v[98:101]
	v_mfma_f32_16x16x32_f16 v[102:105], v[152:155], v[184:187], v[102:105]
	v_mfma_f32_16x16x32_f16 v[122:125], v[148:151], v[164:167], v[122:125]
	v_mfma_f32_16x16x32_f16 v[126:129], v[156:159], v[164:167], v[126:129]
	v_mfma_f32_16x16x32_f16 v[114:117], v[148:151], v[172:175], v[114:117]
	v_mfma_f32_16x16x32_f16 v[118:121], v[156:159], v[172:175], v[118:121]
	v_mfma_f32_16x16x32_f16 v[106:109], v[148:151], v[180:183], v[106:109]
	v_mfma_f32_16x16x32_f16 v[110:113], v[156:159], v[180:183], v[110:113]
	v_mfma_f32_16x16x32_f16 v[98:101], v[148:151], v[188:191], v[98:101]
	v_mfma_f32_16x16x32_f16 v[102:105], v[156:159], v[188:191], v[102:105]
	s_barrier
	s_mov_b32 m0, s20
	v_lshl_add_u64 v[208:209], s[12:13], 0, v[132:133]
	ds_read_b128 v[192:195], v217
	ds_read_b128 v[196:199], v217 offset:1024
	ds_read_b128 v[200:203], v217 offset:2048
	ds_read_b128 v[204:207], v217 offset:3072
	global_load_lds_dwordx4 v[208:209], off
	v_lshl_add_u64 v[210:211], s[12:13], 0, v[136:137]
	s_mov_b32 m0, s21
	s_nop 0
	global_load_lds_dwordx4 v[210:211], off
	s_barrier
	s_waitcnt lgkmcnt(0)
	s_waitcnt lgkmcnt(0)
	v_mfma_f32_16x16x32_f16 v[58:61], v[192:195], v[160:163], v[58:61]
	v_mfma_f32_16x16x32_f16 v[62:65], v[200:203], v[160:163], v[62:65]
	v_mfma_f32_16x16x32_f16 v[50:53], v[192:195], v[168:171], v[50:53]
	v_mfma_f32_16x16x32_f16 v[54:57], v[200:203], v[168:171], v[54:57]
	v_mfma_f32_16x16x32_f16 v[42:45], v[192:195], v[176:179], v[42:45]
	v_mfma_f32_16x16x32_f16 v[46:49], v[200:203], v[176:179], v[46:49]
	v_mfma_f32_16x16x32_f16 v[34:37], v[192:195], v[184:187], v[34:37]
	v_mfma_f32_16x16x32_f16 v[38:41], v[200:203], v[184:187], v[38:41]
	v_mfma_f32_16x16x32_f16 v[58:61], v[196:199], v[164:167], v[58:61]
	v_mfma_f32_16x16x32_f16 v[62:65], v[204:207], v[164:167], v[62:65]
	v_mfma_f32_16x16x32_f16 v[50:53], v[196:199], v[172:175], v[50:53]
	v_mfma_f32_16x16x32_f16 v[54:57], v[204:207], v[172:175], v[54:57]
	v_mfma_f32_16x16x32_f16 v[42:45], v[196:199], v[180:183], v[42:45]
	v_mfma_f32_16x16x32_f16 v[46:49], v[204:207], v[180:183], v[46:49]
	v_mfma_f32_16x16x32_f16 v[34:37], v[196:199], v[188:191], v[34:37]
	v_mfma_f32_16x16x32_f16 v[38:41], v[204:207], v[188:191], v[38:41]
	s_mov_b32 m0, s19
	v_lshl_add_u64 v[212:213], s[14:15], 0, v[130:131]
	s_barrier
	ds_read_b128 v[160:163], v1 offset:16384
	ds_read_b128 v[164:167], v1 offset:17408
	ds_read_b128 v[168:171], v1 offset:18432
	ds_read_b128 v[172:175], v1 offset:19456
	ds_read_b128 v[176:179], v1 offset:20480
	ds_read_b128 v[180:183], v1 offset:21504
	ds_read_b128 v[184:187], v1 offset:22528
	ds_read_b128 v[188:191], v1 offset:23552
	global_load_lds_dwordx4 v[212:213], off
	v_lshl_add_u64 v[214:215], s[14:15], 0, v[134:135]
	s_mov_b32 m0, s22
	s_nop 0
	global_load_lds_dwordx4 v[214:215], off
	s_barrier
	s_waitcnt lgkmcnt(0)
	s_waitcnt lgkmcnt(0)
	v_mfma_f32_16x16x32_f16 v[90:93], v[144:147], v[160:163], v[90:93]
	v_mfma_f32_16x16x32_f16 v[94:97], v[152:155], v[160:163], v[94:97]
	v_mfma_f32_16x16x32_f16 v[82:85], v[144:147], v[168:171], v[82:85]
	v_mfma_f32_16x16x32_f16 v[86:89], v[152:155], v[168:171], v[86:89]
	v_mfma_f32_16x16x32_f16 v[74:77], v[144:147], v[176:179], v[74:77]
	v_mfma_f32_16x16x32_f16 v[78:81], v[152:155], v[176:179], v[78:81]
	v_mfma_f32_16x16x32_f16 v[66:69], v[144:147], v[184:187], v[66:69]
	v_mfma_f32_16x16x32_f16 v[70:73], v[152:155], v[184:187], v[70:73]
	v_mfma_f32_16x16x32_f16 v[90:93], v[148:151], v[164:167], v[90:93]
	v_mfma_f32_16x16x32_f16 v[94:97], v[156:159], v[164:167], v[94:97]
	v_mfma_f32_16x16x32_f16 v[82:85], v[148:151], v[172:175], v[82:85]
	v_mfma_f32_16x16x32_f16 v[86:89], v[156:159], v[172:175], v[86:89]
	v_mfma_f32_16x16x32_f16 v[74:77], v[148:151], v[180:183], v[74:77]
	v_mfma_f32_16x16x32_f16 v[78:81], v[156:159], v[180:183], v[78:81]
	v_mfma_f32_16x16x32_f16 v[66:69], v[148:151], v[188:191], v[66:69]
	v_mfma_f32_16x16x32_f16 v[70:73], v[156:159], v[188:191], v[70:73]
	s_barrier
	s_add_u32 s68, s12, 0x10000
	s_addc_u32 s69, s13, 0
	s_mov_b32 m0, s23
	v_lshl_add_u64 v[144:145], s[68:69], 0, v[132:133]
	global_load_lds_dwordx4 v[144:145], off
	v_lshl_add_u64 v[144:145], s[68:69], 0, v[136:137]
	s_mov_b32 m0, s24
	s_nop 0
	global_load_lds_dwordx4 v[144:145], off
	s_waitcnt vmcnt(6)
	s_barrier
; #define G_STAGE(bufoff, gbase, v0, v1) do { \
;     __builtin_amdgcn_global_load_lds((const unsigned*)((const char*)(gbase) + (v0)), (LAS unsigned*)(lds + (bufoff) + ldsw), 16, 0, 0); \
;     __builtin_amdgcn_global_load_lds((const unsigned*)((const char*)(gbase) + (v1)), (LAS unsigned*)(lds + (bufoff) + ldsw + 8192), 16, 0, 0); } while (0)
; #define G_LDA(dst, b, h) do { _Pragma("unroll") for (int m = 0; m < 4; ++m) _Pragma("unroll") for (int k = 0; k < 2; ++k) dst[m][k] = *(const LAS h8*)(lds + G_SA(b, h) + aoff + m * 2048 + k * 1024); } while (0)
; #define G_LDB(dst, b, h) do { _Pragma("unroll") for (int n = 0; n < 2; ++n) _Pragma("unroll") for (int k = 0; k < 2; ++k) dst[n][k] = *(const LAS h8*)(lds + G_SB(b, h) + boff + n * 2048 + k * 1024); } while (0)
; #define G_MMA(ai, bj, At, Bt) do { __builtin_amdgcn_s_setprio(1); _Pragma("unroll") for (int m = 0; m < 4; ++m) _Pragma("unroll") for (int n = 0; n < 2; ++n) _Pragma("unroll") for (int k = 0; k < 2; ++k) \
;     acc[ai][bj][m][n] = __builtin_amdgcn_mfma_f32_16x16x32_f16(Bt[n][k], At[m][k], acc[ai][bj][m][n], 0, 0, 0); __builtin_amdgcn_s_setprio(0); } while (0)
; #define G_WAIT_V(n) asm volatile("s_waitcnt vmcnt(" #n ")" ::: "memory")
; #define G_WAIT_L(n) asm volatile("s_waitcnt lgkmcnt(" #n ")" ::: "memory")
; #define G_BAR __builtin_amdgcn_s_barrier()
; #define G_SCHED __builtin_amdgcn_sched_barrier(0)
; template <bool PERM, class Sched, class Epi>
; DI void gemm256(LAS unsigned char* lds, const Sched& S, const Epi& E, int wv_) {
;     ...
;       G_WAIT_V(6); G_BAR; G_MMA(1, 1, At, B1); G_BAR;
;       G_LDB(B0, 1, 0); G_SCHED; G_LDA(At, 1, 0); G_STAGE(G_SA(0, 1), a2 + chA, cvA0, cvA1);
;       G_WAIT_L(8); G_BAR; G_WAIT_L(0); G_MMA(0, 0, At, B0); G_BAR; G_SCHED;
;       G_LDB(B1, 1, 1); G_STAGE(G_SB(1, 0), b3, cvB0, cvB1);
;       G_BAR; G_WAIT_L(0); G_MMA(0, 1, At, B1); G_BAR;
	v_mfma_f32_16x16x32_f16 v[26:29], v[192:195], v[160:163], v[26:29]
	v_mfma_f32_16x16x32_f16 v[30:33], v[200:203], v[160:163], v[30:33]
	v_mfma_f32_16x16x32_f16 v[18:21], v[192:195], v[168:171], v[18:21]
	v_mfma_f32_16x16x32_f16 v[22:25], v[200:203], v[168:171], v[22:25]
	v_mfma_f32_16x16x32_f16 v[10:13], v[192:195], v[176:179], v[10:13]
	v_mfma_f32_16x16x32_f16 v[14:17], v[200:203], v[176:179], v[14:17]
	v_mfma_f32_16x16x32_f16 v[6:9], v[192:195], v[184:187], v[6:9]
	v_mfma_f32_16x16x32_f16 v[2:5], v[200:203], v[184:187], v[2:5]
	v_mfma_f32_16x16x32_f16 v[26:29], v[196:199], v[164:167], v[26:29]
	v_mfma_f32_16x16x32_f16 v[30:33], v[204:207], v[164:167], v[30:33]
	v_mfma_f32_16x16x32_f16 v[18:21], v[196:199], v[172:175], v[18:21]
	v_mfma_f32_16x16x32_f16 v[22:25], v[204:207], v[172:175], v[22:25]
	v_mfma_f32_16x16x32_f16 v[10:13], v[196:199], v[180:183], v[10:13]
	v_mfma_f32_16x16x32_f16 v[14:17], v[204:207], v[180:183], v[14:17]
	v_mfma_f32_16x16x32_f16 v[6:9], v[196:199], v[188:191], v[6:9]
	v_mfma_f32_16x16x32_f16 v[2:5], v[204:207], v[188:191], v[2:5]
	s_barrier
	ds_read_b128 v[144:147], v218
	ds_read_b128 v[148:151], v218 offset:1024
	ds_read_b128 v[152:155], v218 offset:2048
	ds_read_b128 v[156:159], v218 offset:3072
	s_add_u32 s14, s14, 0x16000
	s_addc_u32 s15, s15, 0
	s_mov_b32 m0, s25
	v_lshl_add_u64 v[192:193], s[14:15], 0, v[130:131]
	ds_read_b128 v[160:163], v1 offset:32768
	ds_read_b128 v[164:167], v1 offset:33792
	ds_read_b128 v[168:171], v1 offset:34816
	ds_read_b128 v[172:175], v1 offset:35840
	ds_read_b128 v[176:179], v1 offset:36864
	ds_read_b128 v[180:183], v1 offset:37888
	ds_read_b128 v[184:187], v1 offset:38912
	ds_read_b128 v[188:191], v1 offset:39936
	global_load_lds_dwordx4 v[192:193], off
	v_lshl_add_u64 v[192:193], s[14:15], 0, v[134:135]
	s_mov_b32 m0, s26
	s_nop 0
	global_load_lds_dwordx4 v[192:193], off
	s_waitcnt lgkmcnt(8)
	s_barrier
	s_waitcnt lgkmcnt(0)
	s_waitcnt lgkmcnt(0)
	v_mfma_f32_16x16x32_f16 v[122:125], v[144:147], v[160:163], v[122:125]
	v_mfma_f32_16x16x32_f16 v[126:129], v[152:155], v[160:163], v[126:129]
	v_mfma_f32_16x16x32_f16 v[114:117], v[144:147], v[168:171], v[114:117]
	v_mfma_f32_16x16x32_f16 v[118:121], v[152:155], v[168:171], v[118:121]
	v_mfma_f32_16x16x32_f16 v[106:109], v[144:147], v[176:179], v[106:109]
	v_mfma_f32_16x16x32_f16 v[110:113], v[152:155], v[176:179], v[110:113]
	v_mfma_f32_16x16x32_f16 v[98:101], v[144:147], v[184:187], v[98:101]
	v_mfma_f32_16x16x32_f16 v[102:105], v[152:155], v[184:187], v[102:105]
	v_mfma_f32_16x16x32_f16 v[122:125], v[148:151], v[164:167], v[122:125]
	v_mfma_f32_16x16x32_f16 v[126:129], v[156:159], v[164:167], v[126:129]
	v_mfma_f32_16x16x32_f16 v[114:117], v[148:151], v[172:175], v[114:117]
	v_mfma_f32_16x16x32_f16 v[118:121], v[156:159], v[172:175], v[118:121]
	v_mfma_f32_16x16x32_f16 v[106:109], v[148:151], v[180:183], v[106:109]
	v_mfma_f32_16x16x32_f16 v[110:113], v[156:159], v[180:183], v[110:113]
	v_mfma_f32_16x16x32_f16 v[98:101], v[148:151], v[188:191], v[98:101]
	v_mfma_f32_16x16x32_f16 v[102:105], v[156:159], v[188:191], v[102:105]
	s_barrier
	s_mov_b32 m0, s29
	v_lshl_add_u64 v[208:209], v[208:209], 0, s[86:87]
	ds_read_b128 v[192:195], v219
	ds_read_b128 v[196:199], v219 offset:1024
	ds_read_b128 v[200:203], v219 offset:2048
	ds_read_b128 v[204:207], v219 offset:3072
	global_load_lds_dwordx4 v[208:209], off
	v_lshl_add_u64 v[208:209], v[210:211], 0, s[86:87]
	s_mov_b32 m0, s30
	s_nop 0
	global_load_lds_dwordx4 v[208:209], off
	s_barrier
; #define G_STAGE(bufoff, gbase, v0, v1) do { \
;     __builtin_amdgcn_global_load_lds((const unsigned*)((const char*)(gbase) + (v0)), (LAS unsigned*)(lds + (bufoff) + ldsw), 16, 0, 0); \
;     __builtin_amdgcn_global_load_lds((const unsigned*)((const char*)(gbase) + (v1)), (LAS unsigned*)(lds + (bufoff) + ldsw + 8192), 16, 0, 0); } while (0)
; #define G_LDA(dst, b, h) do { _Pragma("unroll") for (int m = 0; m < 4; ++m) _Pragma("unroll") for (int k = 0; k < 2; ++k) dst[m][k] = *(const LAS h8*)(lds + G_SA(b, h) + aoff + m * 2048 + k * 1024); } while (0)
; #define G_MMA(ai, bj, At, Bt) do { __builtin_amdgcn_s_setprio(1); _Pragma("unroll") for (int m = 0; m < 4; ++m) _Pragma("unroll") for (int n = 0; n < 2; ++n) _Pragma("unroll") for (int k = 0; k < 2; ++k) \
;     acc[ai][bj][m][n] = __builtin_amdgcn_mfma_f32_16x16x32_f16(Bt[n][k], At[m][k], acc[ai][bj][m][n], 0, 0, 0); __builtin_amdgcn_s_setprio(0); } while (0)
; #define G_WAIT_V(n) asm volatile("s_waitcnt vmcnt(" #n ")" ::: "memory")
; #define G_WAIT_L(n) asm volatile("s_waitcnt lgkmcnt(" #n ")" ::: "memory")
; #define G_BAR __builtin_amdgcn_s_barrier()
; #define G_SCHED __builtin_amdgcn_sched_barrier(0)
; template <bool PERM, class Sched, class Epi>
; DI void gemm256(LAS unsigned char* lds, const Sched& S, const Epi& E, int wv_) {
;     ...
;     for (int t = 0; t < nt; t += 2) {
;     ...
;       G_BAR; G_WAIT_L(0); G_MMA(0, 1, At, B1); G_BAR;
;       G_LDA(At, 1, 1); G_STAGE(G_SA(1, 0), a3, cvA0, cvA1);
;       G_BAR; G_WAIT_L(0); G_MMA(1, 0, At, B0); G_BAR; G_SCHED;
;       G_STAGE(G_SB(1, 1), b3 + chB, cvB0, cvB1);
;       G_WAIT_V(6); G_BAR; G_MMA(1, 1, At, B1); G_BAR;
	s_waitcnt lgkmcnt(0)
	s_waitcnt lgkmcnt(0)
	v_mfma_f32_16x16x32_f16 v[58:61], v[192:195], v[160:163], v[58:61]
	v_mfma_f32_16x16x32_f16 v[62:65], v[200:203], v[160:163], v[62:65]
	v_mfma_f32_16x16x32_f16 v[50:53], v[192:195], v[168:171], v[50:53]
	v_mfma_f32_16x16x32_f16 v[54:57], v[200:203], v[168:171], v[54:57]
	v_mfma_f32_16x16x32_f16 v[42:45], v[192:195], v[176:179], v[42:45]
	v_mfma_f32_16x16x32_f16 v[46:49], v[200:203], v[176:179], v[46:49]
	v_mfma_f32_16x16x32_f16 v[34:37], v[192:195], v[184:187], v[34:37]
	v_mfma_f32_16x16x32_f16 v[38:41], v[200:203], v[184:187], v[38:41]
	v_mfma_f32_16x16x32_f16 v[58:61], v[196:199], v[164:167], v[58:61]
	v_mfma_f32_16x16x32_f16 v[62:65], v[204:207], v[164:167], v[62:65]
	v_mfma_f32_16x16x32_f16 v[50:53], v[196:199], v[172:175], v[50:53]
	v_mfma_f32_16x16x32_f16 v[54:57], v[204:207], v[172:175], v[54:57]
	v_mfma_f32_16x16x32_f16 v[42:45], v[196:199], v[180:183], v[42:45]
	v_mfma_f32_16x16x32_f16 v[46:49], v[204:207], v[180:183], v[46:49]
	v_mfma_f32_16x16x32_f16 v[34:37], v[196:199], v[188:191], v[34:37]
	v_mfma_f32_16x16x32_f16 v[38:41], v[204:207], v[188:191], v[38:41]
	s_mov_b32 m0, s31
	v_lshl_add_u64 v[208:209], v[212:213], 0, s[86:87]
	s_barrier
	ds_read_b128 v[160:163], v1 offset:49152
	ds_read_b128 v[164:167], v1 offset:50176
	ds_read_b128 v[168:171], v1 offset:51200
	ds_read_b128 v[172:175], v1 offset:52224
	ds_read_b128 v[176:179], v1 offset:53248
	ds_read_b128 v[180:183], v1 offset:54272
	ds_read_b128 v[184:187], v1 offset:55296
	ds_read_b128 v[188:191], v1 offset:56320
	global_load_lds_dwordx4 v[208:209], off
	v_lshl_add_u64 v[208:209], v[214:215], 0, s[86:87]
	s_mov_b32 m0, s34
	s_nop 0
	global_load_lds_dwordx4 v[208:209], off
	s_barrier
	s_waitcnt lgkmcnt(0)
	s_waitcnt lgkmcnt(0)
	v_mfma_f32_16x16x32_f16 v[90:93], v[144:147], v[160:163], v[90:93]
	v_mfma_f32_16x16x32_f16 v[94:97], v[152:155], v[160:163], v[94:97]
	v_mfma_f32_16x16x32_f16 v[82:85], v[144:147], v[168:171], v[82:85]
	v_mfma_f32_16x16x32_f16 v[86:89], v[152:155], v[168:171], v[86:89]
	v_mfma_f32_16x16x32_f16 v[74:77], v[144:147], v[176:179], v[74:77]
	v_mfma_f32_16x16x32_f16 v[78:81], v[152:155], v[176:179], v[78:81]
	v_mfma_f32_16x16x32_f16 v[66:69], v[144:147], v[184:187], v[66:69]
	v_mfma_f32_16x16x32_f16 v[70:73], v[152:155], v[184:187], v[70:73]
	v_mfma_f32_16x16x32_f16 v[90:93], v[148:151], v[164:167], v[90:93]
	v_mfma_f32_16x16x32_f16 v[94:97], v[156:159], v[164:167], v[94:97]
	v_mfma_f32_16x16x32_f16 v[82:85], v[148:151], v[172:175], v[82:85]
	v_mfma_f32_16x16x32_f16 v[86:89], v[156:159], v[172:175], v[86:89]
	v_mfma_f32_16x16x32_f16 v[74:77], v[148:151], v[180:183], v[74:77]
	v_mfma_f32_16x16x32_f16 v[78:81], v[156:159], v[180:183], v[78:81]
	v_mfma_f32_16x16x32_f16 v[66:69], v[148:151], v[188:191], v[66:69]
	v_mfma_f32_16x16x32_f16 v[70:73], v[156:159], v[188:191], v[70:73]
	s_barrier
	s_add_u32 s12, s12, 0x10080
	s_addc_u32 s13, s13, 0
	s_mov_b32 m0, s35
	v_lshl_add_u64 v[144:145], s[12:13], 0, v[132:133]
	global_load_lds_dwordx4 v[144:145], off
	v_lshl_add_u64 v[144:145], s[12:13], 0, v[136:137]
	s_mov_b32 m0, s37
	s_nop 0
	global_load_lds_dwordx4 v[144:145], off
	s_waitcnt vmcnt(6)
	s_barrier
	v_mfma_f32_16x16x32_f16 v[26:29], v[192:195], v[160:163], v[26:29]
	v_mfma_f32_16x16x32_f16 v[30:33], v[200:203], v[160:163], v[30:33]
	v_mfma_f32_16x16x32_f16 v[18:21], v[192:195], v[168:171], v[18:21]
	v_mfma_f32_16x16x32_f16 v[22:25], v[200:203], v[168:171], v[22:25]
	v_mfma_f32_16x16x32_f16 v[10:13], v[192:195], v[176:179], v[10:13]
	v_mfma_f32_16x16x32_f16 v[14:17], v[200:203], v[176:179], v[14:17]
	v_mfma_f32_16x16x32_f16 v[6:9], v[192:195], v[184:187], v[6:9]
	v_mfma_f32_16x16x32_f16 v[2:5], v[200:203], v[184:187], v[2:5]
	v_mfma_f32_16x16x32_f16 v[26:29], v[196:199], v[164:167], v[26:29]
	v_mfma_f32_16x16x32_f16 v[30:33], v[204:207], v[164:167], v[30:33]
	v_mfma_f32_16x16x32_f16 v[18:21], v[196:199], v[172:175], v[18:21]
	v_mfma_f32_16x16x32_f16 v[22:25], v[204:207], v[172:175], v[22:25]
	v_mfma_f32_16x16x32_f16 v[10:13], v[196:199], v[180:183], v[10:13]
	v_mfma_f32_16x16x32_f16 v[14:17], v[204:207], v[180:183], v[14:17]
	v_mfma_f32_16x16x32_f16 v[6:9], v[196:199], v[188:191], v[6:9]
	v_mfma_f32_16x16x32_f16 v[2:5], v[204:207], v[188:191], v[2:5]
	s_add_u32 s10, s10, 0x100
	s_addc_u32 s11, s11, 0
	s_add_u32 s75, s75, 0x100
	s_addc_u32 s46, s46, 0
	s_cmp_ge_i32 s74, s79
	s_mov_b32 s12, s74
	s_barrier
	s_cbranch_scc0 .LBB0_1718
	s_mov_b32 s93, 0x23fff
	s_movk_i32 s85, 0x800
	s_branch .LBB0_1721

;   static DI int bmap(bool perm, int R) { return perm ? ((R & ~31) + perm32(R & 31)) : R; }
; #define G_STAGE(bufoff, gbase, v0, v1) do { \
;     __builtin_amdgcn_global_load_lds((const unsigned*)((const char*)(gbase) + (v0)), (LAS unsigned*)(lds + (bufoff) + ldsw), 16, 0, 0); \
;     __builtin_amdgcn_global_load_lds((const unsigned*)((const char*)(gbase) + (v1)), (LAS unsigned*)(lds + (bufoff) + ldsw + 8192), 16, 0, 0); } while (0)
; #define G_WAIT_V(n) asm volatile("s_waitcnt vmcnt(" #n ")" ::: "memory")
; #define G_BAR __builtin_amdgcn_s_barrier()
;   static DI int bmap(bool, int R) { return ((R >> 4) & 1) * 1024 + (R >> 5) * 16 + (R & 15); }
; template <bool PERM, class Sched, class Epi>
; DI void gemm256(LAS unsigned char* lds, const Sched& S, const Epi& E, int wv_) {
;   const int tid = tid_opaque(wv_), wid = __builtin_amdgcn_readfirstlane(tid >> 6), lane = tid & 63, wr = wid >> 2, wc = wid & 3, fr = lane & 15, fq = lane >> 4;
;   unsigned cvA0, cvA1, cvB0, cvB1;
;   { int R, C;
;     stage_rc(tid * 16, R, C); cvA0 = (unsigned)R * S.lda2 + C * 2; cvB0 = (unsigned)Sched::bmap(PERM, R) * S.ldb2 + C * 2;
;     stage_rc(tid * 16 + 8192, R, C); cvA1 = (unsigned)R * S.lda2 + C * 2; cvB1 = (unsigned)Sched::bmap(PERM, R) * S.ldb2 + C * 2; }
;   const size_t chA = (size_t)HALF * S.lda2, chB = (size_t)Sched::BHALF * S.ldb2;
;   const size_t kstep = (size_t)(BK * 2);
;   const unsigned ldsw = (unsigned)wid * 1024u;
;   const int aoff = lds_byte(wr * 64 + fr, fq * 8), boff = lds_byte(wc * 32 + fr, fq * 8);
;     ...
;   GUnit cur, nxt;
;   int ui = 0;
;   if (!S.next(0, cur)) return;
;   f4 acc[2][2][4][2];
; #pragma unroll
;   for (int a = 0; a < 2; ++a)
; #pragma unroll
;     for (int b = 0; b < 2; ++b)
; #pragma unroll
;       for (int m = 0; m < 4; ++m)
; #pragma unroll
;         for (int n = 0; n < 2; ++n) acc[a][b][m][n] = f4{0.f, 0.f, 0.f, 0.f};
;   h8 At[4][2], B0[2][2], B1[2][2];
;   const char* cA = cur.A;
;   const char* cB = cur.B;
;   G_STAGE(G_SB(0, 0), cB, cvB0, cvB1); G_STAGE(G_SA(0, 0), cA, cvA0, cvA1); G_STAGE(G_SB(0, 1), cB + chB, cvB0, cvB1); G_STAGE(G_SA(0, 1), cA + chA, cvA0, cvA1);
;   if (wr == 1) G_BAR;
;   G_WAIT_V(4); G_BAR;
;   G_STAGE(G_SB(1, 0), cB + kstep, cvB0, cvB1); G_STAGE(G_SA(1, 0), cA + kstep, cvA0, cvA1); G_STAGE(G_SB(1, 1), cB + chB + kstep, cvB0, cvB1);
;   G_WAIT_V(6); G_BAR;
.LBB0_1741:
	v_readlane_b32 s10, v254, 1
	v_and_b32_e32 v12, 15, v1
	v_and_b32_e32 v13, 48, v1
	v_lshlrev_b32_e32 v1, 2, v1
	s_lshl_b32 s5, s5, 5
	v_mov_b32_e32 v135, v0
	v_readlane_b32 s11, v254, 2
	s_lshl_b32 s6, s4, 13
	v_lshl_or_b32 v14, v12, 6, v13
	v_and_b32_e32 v15, 32, v1
	s_and_b32 s9, s5, 0x60
	v_lshl_add_u64 v[8:9], s[10:11], 0, v[134:135]
	v_mov_b32_e32 v131, v0
	s_lshl_b32 s8, s4, 6
	v_bitop3_b32 v1, v14, s6, v15 bitop3:0xde
	s_lshl_b32 s5, s9, 7
	s_add_i32 s25, s17, 0x18000
	s_add_i32 s26, s17, 0x1a000
	v_readlane_b32 s6, v254, 63
	v_lshl_add_u64 v[10:11], s[10:11], 0, v[130:131]
	v_lshl_add_u64 v[8:9], v[8:9], 0, s[86:87]
	s_mov_b32 m0, s25
	v_readlane_b32 s7, v255, 0
	s_add_u32 s6, s6, 0x2160080
	v_mov_b32_e32 v137, v0
	s_waitcnt vmcnt(4)
	s_barrier
	global_load_lds_dwordx4 v[8:9], off
	v_lshl_add_u64 v[8:9], v[10:11], 0, s[86:87]
	s_mov_b32 m0, s26
	s_addc_u32 s7, s7, 0
	s_add_i32 s27, s17, 0x8000
	v_mov_b32_e32 v133, v0
	global_load_lds_dwordx4 v[8:9], off
	v_lshl_add_u64 v[8:9], s[6:7], 0, v[136:137]
	s_mov_b32 m0, s27
	s_add_i32 s28, s17, 0xa000
	global_load_lds_dwordx4 v[8:9], off
	v_lshl_add_u64 v[8:9], s[6:7], 0, v[132:133]
	v_readlane_b32 s6, v254, 3
	s_mov_b32 m0, s28
	v_readlane_b32 s7, v254, 4
	s_add_i32 s29, s17, 0x1c000
	global_load_lds_dwordx4 v[8:9], off
	v_lshl_add_u64 v[8:9], s[6:7], 0, v[134:135]
	s_mov_b32 m0, s29
	s_add_i32 s30, s17, 0x1e000
	global_load_lds_dwordx4 v[8:9], off
	v_lshl_add_u64 v[8:9], s[6:7], 0, v[130:131]
	s_mov_b32 m0, s30
	s_mul_i32 s4, s4, 0x48000
	global_load_lds_dwordx4 v[8:9], off
	v_mul_u32_u24_e32 v8, 0x1200, v12
	v_or_b32_e32 v143, v8, v13
	v_lshlrev_b32_e32 v8, 12, v6
	v_and_b32_e32 v8, 0xffffe000, v8
	v_lshl_add_u32 v5, v5, 9, v8
	v_and_b32_e32 v6, 1, v6
	v_lshl_or_b32 v5, v6, 6, v5
	v_readlane_b32 s6, v254, 5
	v_lshl_add_u32 v6, v7, 1, v5
	v_lshlrev_b32_e32 v5, 12, v2
	v_bitop3_b32 v142, s5, v14, v15 bitop3:0xf6
	v_add_u32_e32 v216, 0x10000, v142
	v_add_u32_e32 v217, 0x14000, v142
	v_add_u32_e32 v218, 0x18000, v142
	v_add_u32_e32 v219, 0x1c000, v142
	s_mul_hi_i32 s5, s8, 0x1200
	v_readlane_b32 s7, v254, 6
	s_add_u32 s31, s6, s4
	v_and_b32_e32 v5, 0xffffe000, v5
	s_addc_u32 s34, s7, s5
	v_readlane_b32 s4, v254, 43
	v_readlane_b32 s5, v254, 62
	v_lshl_add_u32 v3, v3, 9, v5
	v_and_b32_e32 v2, 1, v2
	s_waitcnt vmcnt(6)
	s_add_u32 s4, s4, s5
	v_readlane_b32 s5, v254, 44
	v_lshl_or_b32 v2, v2, 6, v3
	v_mov_b32_e32 v7, v0
	s_addc_u32 s5, s5, 0
	v_lshl_add_u32 v2, v4, 1, v2
	v_mov_b32_e32 v3, v0
	v_lshl_add_u64 v[138:139], s[4:5], 0, v[6:7]
	v_lshl_add_u64 v[140:141], s[4:5], 0, v[2:3]
	s_mov_b32 s35, 0
	s_lshl_b32 s37, s9, 1
	s_mov_b32 s53, s33
	s_mov_b64 s[8:9], s[10:11]
	s_mov_b64 s[4:5], s[10:11]
	s_barrier
	s_branch .LBB0_1744

; #define G_STAGE(bufoff, gbase, v0, v1) do { \
;     __builtin_amdgcn_global_load_lds((const unsigned*)((const char*)(gbase) + (v0)), (LAS unsigned*)(lds + (bufoff) + ldsw), 16, 0, 0); \
;     __builtin_amdgcn_global_load_lds((const unsigned*)((const char*)(gbase) + (v1)), (LAS unsigned*)(lds + (bufoff) + ldsw + 8192), 16, 0, 0); } while (0)
; #define G_LDA(dst, b, h) do { _Pragma("unroll") for (int m = 0; m < 4; ++m) _Pragma("unroll") for (int k = 0; k < 2; ++k) dst[m][k] = *(const LAS h8*)(lds + G_SA(b, h) + aoff + m * 2048 + k * 1024); } while (0)
; #define G_LDB(dst, b, h) do { _Pragma("unroll") for (int n = 0; n < 2; ++n) _Pragma("unroll") for (int k = 0; k < 2; ++k) dst[n][k] = *(const LAS h8*)(lds + G_SB(b, h) + boff + n * 2048 + k * 1024); } while (0)
; #define G_MMA(ai, bj, At, Bt) do { __builtin_amdgcn_s_setprio(1); _Pragma("unroll") for (int m = 0; m < 4; ++m) _Pragma("unroll") for (int n = 0; n < 2; ++n) _Pragma("unroll") for (int k = 0; k < 2; ++k) \
;     acc[ai][bj][m][n] = __builtin_amdgcn_mfma_f32_16x16x32_f16(Bt[n][k], At[m][k], acc[ai][bj][m][n], 0, 0, 0); __builtin_amdgcn_s_setprio(0); } while (0)
; #define G_WAIT_V(n) asm volatile("s_waitcnt vmcnt(" #n ")" ::: "memory")
; #define G_WAIT_L(n) asm volatile("s_waitcnt lgkmcnt(" #n ")" ::: "memory")
; #define G_BAR __builtin_amdgcn_s_barrier()
; #define G_SCHED __builtin_amdgcn_sched_barrier(0)
; template <bool PERM, class Sched, class Epi>
; DI void gemm256(LAS unsigned char* lds, const Sched& S, const Epi& E, int wv_) {
;     ...
;       const bool last = (t == nt - 2);
;       const char* a1 = cA + (size_t)(t + 1) * kstep;
;       const char* a2 = last ? nA : cA + (size_t)(t + 2) * kstep;
;       const char* b2 = last ? nB : cB + (size_t)(t + 2) * kstep;
;       const char* a3 = a2 + kstep;
;       const char* b3 = b2 + kstep;
;       G_LDB(B0, 0, 0); G_SCHED; G_LDA(At, 0, 0); G_STAGE(G_SA(1, 1), a1 + chA, cvA0, cvA1);
;       G_WAIT_L(8); G_BAR; G_WAIT_L(0); G_MMA(0, 0, At, B0); G_BAR; G_SCHED;
;       G_LDB(B1, 0, 1); G_STAGE(G_SB(0, 0), b2, cvB0, cvB1);
;       G_BAR; G_WAIT_L(0); G_MMA(0, 1, At, B1); G_BAR;
;       G_LDA(At, 0, 1); G_STAGE(G_SA(0, 0), a2, cvA0, cvA1);
;       G_BAR; G_WAIT_L(0); G_MMA(1, 0, At, B0); G_BAR; G_SCHED;
;       G_STAGE(G_SB(0, 1), b2 + chB, cvB0, cvB1);
;       G_WAIT_V(6); G_BAR; G_MMA(1, 1, At, B1); G_BAR;
.LBB0_1748:
	s_add_i32 s60, s12, 2
	s_add_u32 s10, s8, 0x100
	s_addc_u32 s11, s9, 0
	s_add_u32 s13, s58, s8
	ds_read_b128 v[144:147], v216
	ds_read_b128 v[148:151], v216 offset:1024
	ds_read_b128 v[152:155], v216 offset:2048
	ds_read_b128 v[156:159], v216 offset:3072
	s_addc_u32 s14, s59, s9
	s_cmp_eq_u32 s56, s12
	s_cselect_b32 s40, 0, s10
	s_cselect_b32 s15, 0, s11
	s_cselect_b32 s12, s4, s13
	s_cselect_b32 s13, s5, s14
	s_add_u32 s14, s2, s40
	s_addc_u32 s15, s3, s15
	v_lshl_add_u64 v[192:193], v[138:139], 0, s[8:9]
	s_add_i32 m0, s17, 0xc000
	ds_read_b128 v[160:163], v1
	ds_read_b128 v[164:167], v1 offset:1024
	ds_read_b128 v[168:171], v1 offset:2048
	ds_read_b128 v[172:175], v1 offset:3072
	ds_read_b128 v[176:179], v1 offset:4096
	ds_read_b128 v[180:183], v1 offset:5120
	ds_read_b128 v[184:187], v1 offset:6144
	ds_read_b128 v[188:191], v1 offset:7168
	global_load_lds_dwordx4 v[192:193], off
	v_lshl_add_u64 v[192:193], v[140:141], 0, s[8:9]
	s_add_i32 m0, s17, 0xe000
	s_nop 0
	global_load_lds_dwordx4 v[192:193], off
	s_waitcnt lgkmcnt(8)
	s_barrier
	s_waitcnt lgkmcnt(0)
	s_waitcnt lgkmcnt(0)
	v_mfma_f32_16x16x32_f16 v[122:125], v[144:147], v[160:163], v[122:125]
	v_mfma_f32_16x16x32_f16 v[126:129], v[152:155], v[160:163], v[126:129]
	v_mfma_f32_16x16x32_f16 v[106:109], v[144:147], v[168:171], v[106:109]
	v_mfma_f32_16x16x32_f16 v[110:113], v[152:155], v[168:171], v[110:113]
	v_mfma_f32_16x16x32_f16 v[90:93], v[144:147], v[176:179], v[90:93]
	v_mfma_f32_16x16x32_f16 v[94:97], v[152:155], v[176:179], v[94:97]
	v_mfma_f32_16x16x32_f16 v[74:77], v[144:147], v[184:187], v[74:77]
	v_mfma_f32_16x16x32_f16 v[78:81], v[152:155], v[184:187], v[78:81]
	v_mfma_f32_16x16x32_f16 v[122:125], v[148:151], v[164:167], v[122:125]
	v_mfma_f32_16x16x32_f16 v[126:129], v[156:159], v[164:167], v[126:129]
	v_mfma_f32_16x16x32_f16 v[106:109], v[148:151], v[172:175], v[106:109]
	v_mfma_f32_16x16x32_f16 v[110:113], v[156:159], v[172:175], v[110:113]
	v_mfma_f32_16x16x32_f16 v[90:93], v[148:151], v[180:183], v[90:93]
	v_mfma_f32_16x16x32_f16 v[94:97], v[156:159], v[180:183], v[94:97]
	v_mfma_f32_16x16x32_f16 v[74:77], v[148:151], v[188:191], v[74:77]
	v_mfma_f32_16x16x32_f16 v[78:81], v[156:159], v[188:191], v[78:81]
	s_barrier
	s_mov_b32 m0, s18
	v_lshl_add_u64 v[208:209], s[12:13], 0, v[134:135]
	ds_read_b128 v[192:195], v217
	ds_read_b128 v[196:199], v217 offset:1024
	ds_read_b128 v[200:203], v217 offset:2048
	ds_read_b128 v[204:207], v217 offset:3072
	global_load_lds_dwordx4 v[208:209], off
	v_lshl_add_u64 v[210:211], s[12:13], 0, v[130:131]
	s_mov_b32 m0, s19
	s_nop 0
	global_load_lds_dwordx4 v[210:211], off
	s_barrier
	s_waitcnt lgkmcnt(0)
	s_waitcnt lgkmcnt(0)
	v_mfma_f32_16x16x32_f16 v[114:117], v[192:195], v[160:163], v[114:117]
	v_mfma_f32_16x16x32_f16 v[118:121], v[200:203], v[160:163], v[118:121]
	v_mfma_f32_16x16x32_f16 v[98:101], v[192:195], v[168:171], v[98:101]
	v_mfma_f32_16x16x32_f16 v[102:105], v[200:203], v[168:171], v[102:105]
	v_mfma_f32_16x16x32_f16 v[82:85], v[192:195], v[176:179], v[82:85]
	v_mfma_f32_16x16x32_f16 v[86:89], v[200:203], v[176:179], v[86:89]
	v_mfma_f32_16x16x32_f16 v[66:69], v[192:195], v[184:187], v[66:69]
	v_mfma_f32_16x16x32_f16 v[70:73], v[200:203], v[184:187], v[70:73]
	v_mfma_f32_16x16x32_f16 v[114:117], v[196:199], v[164:167], v[114:117]
	v_mfma_f32_16x16x32_f16 v[118:121], v[204:207], v[164:167], v[118:121]
	v_mfma_f32_16x16x32_f16 v[98:101], v[196:199], v[172:175], v[98:101]
	v_mfma_f32_16x16x32_f16 v[102:105], v[204:207], v[172:175], v[102:105]
	v_mfma_f32_16x16x32_f16 v[82:85], v[196:199], v[180:183], v[82:85]
	v_mfma_f32_16x16x32_f16 v[86:89], v[204:207], v[180:183], v[86:89]
	v_mfma_f32_16x16x32_f16 v[66:69], v[196:199], v[188:191], v[66:69]
	v_mfma_f32_16x16x32_f16 v[70:73], v[204:207], v[188:191], v[70:73]
	s_mov_b32 m0, s17
	v_lshl_add_u64 v[212:213], s[14:15], 0, v[136:137]
	s_barrier
	ds_read_b128 v[160:163], v1 offset:16384
	ds_read_b128 v[164:167], v1 offset:17408
	ds_read_b128 v[168:171], v1 offset:18432
	ds_read_b128 v[172:175], v1 offset:19456
	ds_read_b128 v[176:179], v1 offset:20480
	ds_read_b128 v[180:183], v1 offset:21504
	ds_read_b128 v[184:187], v1 offset:22528
	ds_read_b128 v[188:191], v1 offset:23552
	global_load_lds_dwordx4 v[212:213], off
	v_lshl_add_u64 v[214:215], s[14:15], 0, v[132:133]
	s_mov_b32 m0, s20
	s_nop 0
	global_load_lds_dwordx4 v[214:215], off
	s_barrier
	s_waitcnt lgkmcnt(0)
	s_waitcnt lgkmcnt(0)
	v_mfma_f32_16x16x32_f16 v[58:61], v[144:147], v[160:163], v[58:61]
	v_mfma_f32_16x16x32_f16 v[62:65], v[152:155], v[160:163], v[62:65]
	v_mfma_f32_16x16x32_f16 v[42:45], v[144:147], v[168:171], v[42:45]
	v_mfma_f32_16x16x32_f16 v[46:49], v[152:155], v[168:171], v[46:49]
	v_mfma_f32_16x16x32_f16 v[26:29], v[144:147], v[176:179], v[26:29]
	v_mfma_f32_16x16x32_f16 v[30:33], v[152:155], v[176:179], v[30:33]
	v_mfma_f32_16x16x32_f16 v[10:13], v[144:147], v[184:187], v[10:13]
	v_mfma_f32_16x16x32_f16 v[14:17], v[152:155], v[184:187], v[14:17]
	v_mfma_f32_16x16x32_f16 v[58:61], v[148:151], v[164:167], v[58:61]
	v_mfma_f32_16x16x32_f16 v[62:65], v[156:159], v[164:167], v[62:65]
	v_mfma_f32_16x16x32_f16 v[42:45], v[148:151], v[172:175], v[42:45]
	v_mfma_f32_16x16x32_f16 v[46:49], v[156:159], v[172:175], v[46:49]
	v_mfma_f32_16x16x32_f16 v[26:29], v[148:151], v[180:183], v[26:29]
	v_mfma_f32_16x16x32_f16 v[30:33], v[156:159], v[180:183], v[30:33]
	v_mfma_f32_16x16x32_f16 v[10:13], v[148:151], v[188:191], v[10:13]
	v_mfma_f32_16x16x32_f16 v[14:17], v[156:159], v[188:191], v[14:17]
	s_barrier
; #define G_STAGE(bufoff, gbase, v0, v1) do { \
;     __builtin_amdgcn_global_load_lds((const unsigned*)((const char*)(gbase) + (v0)), (LAS unsigned*)(lds + (bufoff) + ldsw), 16, 0, 0); \
;     __builtin_amdgcn_global_load_lds((const unsigned*)((const char*)(gbase) + (v1)), (LAS unsigned*)(lds + (bufoff) + ldsw + 8192), 16, 0, 0); } while (0)
; #define G_LDA(dst, b, h) do { _Pragma("unroll") for (int m = 0; m < 4; ++m) _Pragma("unroll") for (int k = 0; k < 2; ++k) dst[m][k] = *(const LAS h8*)(lds + G_SA(b, h) + aoff + m * 2048 + k * 1024); } while (0)
; #define G_LDB(dst, b, h) do { _Pragma("unroll") for (int n = 0; n < 2; ++n) _Pragma("unroll") for (int k = 0; k < 2; ++k) dst[n][k] = *(const LAS h8*)(lds + G_SB(b, h) + boff + n * 2048 + k * 1024); } while (0)
; #define G_MMA(ai, bj, At, Bt) do { __builtin_amdgcn_s_setprio(1); _Pragma("unroll") for (int m = 0; m < 4; ++m) _Pragma("unroll") for (int n = 0; n < 2; ++n) _Pragma("unroll") for (int k = 0; k < 2; ++k) \
;     acc[ai][bj][m][n] = __builtin_amdgcn_mfma_f32_16x16x32_f16(Bt[n][k], At[m][k], acc[ai][bj][m][n], 0, 0, 0); __builtin_amdgcn_s_setprio(0); } while (0)
; #define G_WAIT_V(n) asm volatile("s_waitcnt vmcnt(" #n ")" ::: "memory")
; #define G_WAIT_L(n) asm volatile("s_waitcnt lgkmcnt(" #n ")" ::: "memory")
; #define G_BAR __builtin_amdgcn_s_barrier()
; #define G_SCHED __builtin_amdgcn_sched_barrier(0)
; template <bool PERM, class Sched, class Epi>
; DI void gemm256(LAS unsigned char* lds, const Sched& S, const Epi& E, int wv_) {
;     ...
;       G_WAIT_V(6); G_BAR; G_MMA(1, 1, At, B1); G_BAR;
;       G_LDB(B0, 1, 0); G_SCHED; G_LDA(At, 1, 0); G_STAGE(G_SA(0, 1), a2 + chA, cvA0, cvA1);
;       G_WAIT_L(8); G_BAR; G_WAIT_L(0); G_MMA(0, 0, At, B0); G_BAR; G_SCHED;
;       G_LDB(B1, 1, 1); G_STAGE(G_SB(1, 0), b3, cvB0, cvB1);
;       G_BAR; G_WAIT_L(0); G_MMA(0, 1, At, B1); G_BAR;
	s_add_u32 s8, s12, 0x16000
	s_addc_u32 s9, s13, 0
	s_mov_b32 m0, s21
	v_lshl_add_u64 v[144:145], s[8:9], 0, v[134:135]
	global_load_lds_dwordx4 v[144:145], off
	v_lshl_add_u64 v[144:145], s[8:9], 0, v[130:131]
	s_mov_b32 m0, s22
	s_nop 0
	global_load_lds_dwordx4 v[144:145], off
	s_waitcnt vmcnt(6)
	s_barrier
	v_mfma_f32_16x16x32_f16 v[50:53], v[192:195], v[160:163], v[50:53]
	v_mfma_f32_16x16x32_f16 v[54:57], v[200:203], v[160:163], v[54:57]
	v_mfma_f32_16x16x32_f16 v[34:37], v[192:195], v[168:171], v[34:37]
	v_mfma_f32_16x16x32_f16 v[38:41], v[200:203], v[168:171], v[38:41]
	v_mfma_f32_16x16x32_f16 v[18:21], v[192:195], v[176:179], v[18:21]
	v_mfma_f32_16x16x32_f16 v[22:25], v[200:203], v[176:179], v[22:25]
	v_mfma_f32_16x16x32_f16 v[6:9], v[192:195], v[184:187], v[6:9]
	v_mfma_f32_16x16x32_f16 v[2:5], v[200:203], v[184:187], v[2:5]
	v_mfma_f32_16x16x32_f16 v[50:53], v[196:199], v[164:167], v[50:53]
	v_mfma_f32_16x16x32_f16 v[54:57], v[204:207], v[164:167], v[54:57]
	v_mfma_f32_16x16x32_f16 v[34:37], v[196:199], v[172:175], v[34:37]
	v_mfma_f32_16x16x32_f16 v[38:41], v[204:207], v[172:175], v[38:41]
	v_mfma_f32_16x16x32_f16 v[18:21], v[196:199], v[180:183], v[18:21]
	v_mfma_f32_16x16x32_f16 v[22:25], v[204:207], v[180:183], v[22:25]
	v_mfma_f32_16x16x32_f16 v[6:9], v[196:199], v[188:191], v[6:9]
	v_mfma_f32_16x16x32_f16 v[2:5], v[204:207], v[188:191], v[2:5]
	s_barrier
	ds_read_b128 v[144:147], v218
	ds_read_b128 v[148:151], v218 offset:1024
	ds_read_b128 v[152:155], v218 offset:2048
	ds_read_b128 v[156:159], v218 offset:3072
	s_add_u32 s8, s14, 0x10000
	s_addc_u32 s9, s15, 0
	s_mov_b32 m0, s23
	v_lshl_add_u64 v[192:193], s[8:9], 0, v[136:137]
	ds_read_b128 v[160:163], v1 offset:32768
	ds_read_b128 v[164:167], v1 offset:33792
	ds_read_b128 v[168:171], v1 offset:34816
	ds_read_b128 v[172:175], v1 offset:35840
	ds_read_b128 v[176:179], v1 offset:36864
	ds_read_b128 v[180:183], v1 offset:37888
	ds_read_b128 v[184:187], v1 offset:38912
	ds_read_b128 v[188:191], v1 offset:39936
	global_load_lds_dwordx4 v[192:193], off
	v_lshl_add_u64 v[192:193], s[8:9], 0, v[132:133]
	s_mov_b32 m0, s24
	s_nop 0
	global_load_lds_dwordx4 v[192:193], off
	s_waitcnt lgkmcnt(8)
	s_barrier
	s_waitcnt lgkmcnt(0)
	s_waitcnt lgkmcnt(0)
	v_mfma_f32_16x16x32_f16 v[122:125], v[144:147], v[160:163], v[122:125]
	v_mfma_f32_16x16x32_f16 v[126:129], v[152:155], v[160:163], v[126:129]
	v_mfma_f32_16x16x32_f16 v[106:109], v[144:147], v[168:171], v[106:109]
	v_mfma_f32_16x16x32_f16 v[110:113], v[152:155], v[168:171], v[110:113]
	v_mfma_f32_16x16x32_f16 v[90:93], v[144:147], v[176:179], v[90:93]
	v_mfma_f32_16x16x32_f16 v[94:97], v[152:155], v[176:179], v[94:97]
	v_mfma_f32_16x16x32_f16 v[74:77], v[144:147], v[184:187], v[74:77]
	v_mfma_f32_16x16x32_f16 v[78:81], v[152:155], v[184:187], v[78:81]
	v_mfma_f32_16x16x32_f16 v[122:125], v[148:151], v[164:167], v[122:125]
	v_mfma_f32_16x16x32_f16 v[126:129], v[156:159], v[164:167], v[126:129]
	v_mfma_f32_16x16x32_f16 v[106:109], v[148:151], v[172:175], v[106:109]
	v_mfma_f32_16x16x32_f16 v[110:113], v[156:159], v[172:175], v[110:113]
	v_mfma_f32_16x16x32_f16 v[90:93], v[148:151], v[180:183], v[90:93]
	v_mfma_f32_16x16x32_f16 v[94:97], v[156:159], v[180:183], v[94:97]
	v_mfma_f32_16x16x32_f16 v[74:77], v[148:151], v[188:191], v[74:77]
	v_mfma_f32_16x16x32_f16 v[78:81], v[156:159], v[188:191], v[78:81]
	s_barrier
	s_mov_b32 m0, s25
	v_lshl_add_u64 v[208:209], v[208:209], 0, s[86:87]
	ds_read_b128 v[192:195], v219
	ds_read_b128 v[196:199], v219 offset:1024
	ds_read_b128 v[200:203], v219 offset:2048
	ds_read_b128 v[204:207], v219 offset:3072
	global_load_lds_dwordx4 v[208:209], off
	v_lshl_add_u64 v[208:209], v[210:211], 0, s[86:87]
	s_mov_b32 m0, s26
	s_nop 0
	global_load_lds_dwordx4 v[208:209], off
	s_barrier
; #define G_STAGE(bufoff, gbase, v0, v1) do { \
;     __builtin_amdgcn_global_load_lds((const unsigned*)((const char*)(gbase) + (v0)), (LAS unsigned*)(lds + (bufoff) + ldsw), 16, 0, 0); \
;     __builtin_amdgcn_global_load_lds((const unsigned*)((const char*)(gbase) + (v1)), (LAS unsigned*)(lds + (bufoff) + ldsw + 8192), 16, 0, 0); } while (0)
; #define G_LDA(dst, b, h) do { _Pragma("unroll") for (int m = 0; m < 4; ++m) _Pragma("unroll") for (int k = 0; k < 2; ++k) dst[m][k] = *(const LAS h8*)(lds + G_SA(b, h) + aoff + m * 2048 + k * 1024); } while (0)
; #define G_MMA(ai, bj, At, Bt) do { __builtin_amdgcn_s_setprio(1); _Pragma("unroll") for (int m = 0; m < 4; ++m) _Pragma("unroll") for (int n = 0; n < 2; ++n) _Pragma("unroll") for (int k = 0; k < 2; ++k) \
;     acc[ai][bj][m][n] = __builtin_amdgcn_mfma_f32_16x16x32_f16(Bt[n][k], At[m][k], acc[ai][bj][m][n], 0, 0, 0); __builtin_amdgcn_s_setprio(0); } while (0)
; #define G_WAIT_V(n) asm volatile("s_waitcnt vmcnt(" #n ")" ::: "memory")
; #define G_WAIT_L(n) asm volatile("s_waitcnt lgkmcnt(" #n ")" ::: "memory")
; #define G_BAR __builtin_amdgcn_s_barrier()
; #define G_SCHED __builtin_amdgcn_sched_barrier(0)
; template <bool PERM, class Sched, class Epi>
; DI void gemm256(LAS unsigned char* lds, const Sched& S, const Epi& E, int wv_) {
;     ...
;     for (int t = 0; t < nt; t += 2) {
;     ...
;       G_BAR; G_WAIT_L(0); G_MMA(0, 1, At, B1); G_BAR;
;       G_LDA(At, 1, 1); G_STAGE(G_SA(1, 0), a3, cvA0, cvA1);
;       G_BAR; G_WAIT_L(0); G_MMA(1, 0, At, B0); G_BAR; G_SCHED;
;       G_STAGE(G_SB(1, 1), b3 + chB, cvB0, cvB1);
;       G_WAIT_V(6); G_BAR; G_MMA(1, 1, At, B1); G_BAR;
	s_waitcnt lgkmcnt(0)
	s_waitcnt lgkmcnt(0)
	v_mfma_f32_16x16x32_f16 v[114:117], v[192:195], v[160:163], v[114:117]
	v_mfma_f32_16x16x32_f16 v[118:121], v[200:203], v[160:163], v[118:121]
	v_mfma_f32_16x16x32_f16 v[98:101], v[192:195], v[168:171], v[98:101]
	v_mfma_f32_16x16x32_f16 v[102:105], v[200:203], v[168:171], v[102:105]
	v_mfma_f32_16x16x32_f16 v[82:85], v[192:195], v[176:179], v[82:85]
	v_mfma_f32_16x16x32_f16 v[86:89], v[200:203], v[176:179], v[86:89]
	v_mfma_f32_16x16x32_f16 v[66:69], v[192:195], v[184:187], v[66:69]
	v_mfma_f32_16x16x32_f16 v[70:73], v[200:203], v[184:187], v[70:73]
	v_mfma_f32_16x16x32_f16 v[114:117], v[196:199], v[164:167], v[114:117]
	v_mfma_f32_16x16x32_f16 v[118:121], v[204:207], v[164:167], v[118:121]
	v_mfma_f32_16x16x32_f16 v[98:101], v[196:199], v[172:175], v[98:101]
	v_mfma_f32_16x16x32_f16 v[102:105], v[204:207], v[172:175], v[102:105]
	v_mfma_f32_16x16x32_f16 v[82:85], v[196:199], v[180:183], v[82:85]
	v_mfma_f32_16x16x32_f16 v[86:89], v[204:207], v[180:183], v[86:89]
	v_mfma_f32_16x16x32_f16 v[66:69], v[196:199], v[188:191], v[66:69]
	v_mfma_f32_16x16x32_f16 v[70:73], v[204:207], v[188:191], v[70:73]
	s_mov_b32 m0, s27
	v_lshl_add_u64 v[208:209], v[212:213], 0, s[86:87]
	s_barrier
	ds_read_b128 v[160:163], v1 offset:49152
	ds_read_b128 v[164:167], v1 offset:50176
	ds_read_b128 v[168:171], v1 offset:51200
	ds_read_b128 v[172:175], v1 offset:52224
	ds_read_b128 v[176:179], v1 offset:53248
	ds_read_b128 v[180:183], v1 offset:54272
	ds_read_b128 v[184:187], v1 offset:55296
	ds_read_b128 v[188:191], v1 offset:56320
	global_load_lds_dwordx4 v[208:209], off
	v_lshl_add_u64 v[208:209], v[214:215], 0, s[86:87]
	s_mov_b32 m0, s28
	s_nop 0
	global_load_lds_dwordx4 v[208:209], off
	s_barrier
	s_waitcnt lgkmcnt(0)
	s_waitcnt lgkmcnt(0)
	v_mfma_f32_16x16x32_f16 v[58:61], v[144:147], v[160:163], v[58:61]
	v_mfma_f32_16x16x32_f16 v[62:65], v[152:155], v[160:163], v[62:65]
	v_mfma_f32_16x16x32_f16 v[42:45], v[144:147], v[168:171], v[42:45]
	v_mfma_f32_16x16x32_f16 v[46:49], v[152:155], v[168:171], v[46:49]
	v_mfma_f32_16x16x32_f16 v[26:29], v[144:147], v[176:179], v[26:29]
	v_mfma_f32_16x16x32_f16 v[30:33], v[152:155], v[176:179], v[30:33]
	v_mfma_f32_16x16x32_f16 v[10:13], v[144:147], v[184:187], v[10:13]
	v_mfma_f32_16x16x32_f16 v[14:17], v[152:155], v[184:187], v[14:17]
	v_mfma_f32_16x16x32_f16 v[58:61], v[148:151], v[164:167], v[58:61]
	v_mfma_f32_16x16x32_f16 v[62:65], v[156:159], v[164:167], v[62:65]
	v_mfma_f32_16x16x32_f16 v[42:45], v[148:151], v[172:175], v[42:45]
	v_mfma_f32_16x16x32_f16 v[46:49], v[156:159], v[172:175], v[46:49]
	v_mfma_f32_16x16x32_f16 v[26:29], v[148:151], v[180:183], v[26:29]
	v_mfma_f32_16x16x32_f16 v[30:33], v[156:159], v[180:183], v[30:33]
	v_mfma_f32_16x16x32_f16 v[10:13], v[148:151], v[188:191], v[10:13]
	v_mfma_f32_16x16x32_f16 v[14:17], v[156:159], v[188:191], v[14:17]
	s_barrier
	s_add_u32 s8, s12, 0x16080
	s_addc_u32 s9, s13, 0
	s_mov_b32 m0, s29
	v_lshl_add_u64 v[144:145], s[8:9], 0, v[134:135]
	global_load_lds_dwordx4 v[144:145], off
	v_lshl_add_u64 v[144:145], s[8:9], 0, v[130:131]
	s_mov_b32 m0, s30
	s_nop 0
	global_load_lds_dwordx4 v[144:145], off
	s_waitcnt vmcnt(6)
	s_barrier
	v_mfma_f32_16x16x32_f16 v[50:53], v[192:195], v[160:163], v[50:53]
	v_mfma_f32_16x16x32_f16 v[54:57], v[200:203], v[160:163], v[54:57]
	v_mfma_f32_16x16x32_f16 v[34:37], v[192:195], v[168:171], v[34:37]
	v_mfma_f32_16x16x32_f16 v[38:41], v[200:203], v[168:171], v[38:41]
	v_mfma_f32_16x16x32_f16 v[18:21], v[192:195], v[176:179], v[18:21]
	v_mfma_f32_16x16x32_f16 v[22:25], v[200:203], v[176:179], v[22:25]
	v_mfma_f32_16x16x32_f16 v[6:9], v[192:195], v[184:187], v[6:9]
	v_mfma_f32_16x16x32_f16 v[2:5], v[200:203], v[184:187], v[2:5]
	v_mfma_f32_16x16x32_f16 v[50:53], v[196:199], v[164:167], v[50:53]
	v_mfma_f32_16x16x32_f16 v[54:57], v[204:207], v[164:167], v[54:57]
	v_mfma_f32_16x16x32_f16 v[34:37], v[196:199], v[172:175], v[34:37]
	v_mfma_f32_16x16x32_f16 v[38:41], v[204:207], v[172:175], v[38:41]
	v_mfma_f32_16x16x32_f16 v[18:21], v[196:199], v[180:183], v[18:21]
	v_mfma_f32_16x16x32_f16 v[22:25], v[204:207], v[180:183], v[22:25]
	v_mfma_f32_16x16x32_f16 v[6:9], v[196:199], v[188:191], v[6:9]
	v_mfma_f32_16x16x32_f16 v[2:5], v[204:207], v[188:191], v[2:5]
	s_cmp_ge_i32 s60, s46
	s_mov_b64 s[8:9], s[10:11]
	s_mov_b32 s12, s60
	s_barrier
	s_cbranch_scc0 .LBB0_1748
	s_branch .LBB0_1743

;   static DI int bmap(bool perm, int R) { return perm ? ((R & ~31) + perm32(R & 31)) : R; }
; #define G_STAGE(bufoff, gbase, v0, v1) do { \
;     __builtin_amdgcn_global_load_lds((const unsigned*)((const char*)(gbase) + (v0)), (LAS unsigned*)(lds + (bufoff) + ldsw), 16, 0, 0); \
;     __builtin_amdgcn_global_load_lds((const unsigned*)((const char*)(gbase) + (v1)), (LAS unsigned*)(lds + (bufoff) + ldsw + 8192), 16, 0, 0); } while (0)
; #define G_WAIT_V(n) asm volatile("s_waitcnt vmcnt(" #n ")" ::: "memory")
; #define G_BAR __builtin_amdgcn_s_barrier()
;   static DI int bmap(bool, int R) { return ((R >> 4) & 1) * 1024 + (R >> 5) * 16 + (R & 15); }
; template <bool PERM, class Sched, class Epi>
; DI void gemm256(LAS unsigned char* lds, const Sched& S, const Epi& E, int wv_) {
;   const int tid = tid_opaque(wv_), wid = __builtin_amdgcn_readfirstlane(tid >> 6), lane = tid & 63, wr = wid >> 2, wc = wid & 3, fr = lane & 15, fq = lane >> 4;
;   unsigned cvA0, cvA1, cvB0, cvB1;
;   { int R, C;
;     stage_rc(tid * 16, R, C); cvA0 = (unsigned)R * S.lda2 + C * 2; cvB0 = (unsigned)Sched::bmap(PERM, R) * S.ldb2 + C * 2;
;     stage_rc(tid * 16 + 8192, R, C); cvA1 = (unsigned)R * S.lda2 + C * 2; cvB1 = (unsigned)Sched::bmap(PERM, R) * S.ldb2 + C * 2; }
;   const size_t chA = (size_t)HALF * S.lda2, chB = (size_t)Sched::BHALF * S.ldb2;
;   const size_t kstep = (size_t)(BK * 2);
;   const unsigned ldsw = (unsigned)wid * 1024u;
;   const int aoff = lds_byte(wr * 64 + fr, fq * 8), boff = lds_byte(wc * 32 + fr, fq * 8);
;     ...
;   GUnit cur, nxt;
;   int ui = 0;
;   if (!S.next(0, cur)) return;
;   f4 acc[2][2][4][2];
; #pragma unroll
;   for (int a = 0; a < 2; ++a)
; #pragma unroll
;     for (int b = 0; b < 2; ++b)
; #pragma unroll
;       for (int m = 0; m < 4; ++m)
; #pragma unroll
;         for (int n = 0; n < 2; ++n) acc[a][b][m][n] = f4{0.f, 0.f, 0.f, 0.f};
;   h8 At[4][2], B0[2][2], B1[2][2];
;   const char* cA = cur.A;
;   const char* cB = cur.B;
;   G_STAGE(G_SB(0, 0), cB, cvB0, cvB1); G_STAGE(G_SA(0, 0), cA, cvA0, cvA1); G_STAGE(G_SB(0, 1), cB + chB, cvB0, cvB1); G_STAGE(G_SA(0, 1), cA + chA, cvA0, cvA1);
;   if (wr == 1) G_BAR;
;   G_WAIT_V(4); G_BAR;
;   G_STAGE(G_SB(1, 0), cB + kstep, cvB0, cvB1); G_STAGE(G_SA(1, 0), cA + kstep, cvA0, cvA1); G_STAGE(G_SB(1, 1), cB + chB + kstep, cvB0, cvB1);
;   G_WAIT_V(6); G_BAR;
.LBB0_2266:
	v_lshrrev_b32_e32 v17, 1, v1
	v_mov_b32_e32 v133, v0
	v_and_b32_e32 v17, 24, v17
	v_lshl_add_u64 v[8:9], s[14:15], 0, v[132:133]
	v_mov_b32_e32 v137, v0
	v_and_b32_e32 v16, 15, v1
	v_lshlrev_b32_e32 v18, 1, v17
	v_lshlrev_b32_e32 v1, 2, v1
	s_add_i32 s28, s20, 0x18000
	v_lshl_add_u64 v[10:11], s[14:15], 0, v[136:137]
	v_mov_b32_e32 v131, v0
	s_and_b32 s5, s5, 3
	v_lshl_or_b32 v18, v16, 6, v18
	s_lshl_b32 s2, s4, 13
	v_and_b32_e32 v19, 32, v1
	v_lshl_add_u64 v[8:9], v[8:9], 0, s[86:87]
	s_mov_b32 m0, s28
	s_add_i32 s29, s20, 0x1a000
	v_lshl_add_u64 v[12:13], s[12:13], 0, v[130:131]
	v_mov_b32_e32 v135, v0
	s_lshl_b32 s27, s4, 6
	v_bitop3_b32 v1, v18, s2, v19 bitop3:0xde
	s_lshl_b32 s2, s5, 12
	s_waitcnt vmcnt(4)
	s_barrier
	global_load_lds_dwordx4 v[8:9], off
	v_lshl_add_u64 v[8:9], v[10:11], 0, s[86:87]
	s_mov_b32 m0, s29
	s_add_i32 s30, s20, 0x8000
	s_add_i32 s31, s20, 0xa000
	v_lshl_add_u64 v[14:15], s[12:13], 0, v[134:135]
	v_bitop3_b32 v146, v18, s2, v19 bitop3:0xde
	v_add_u32_e32 v239, 0x10000, v146
	v_add_u32_e32 v243, 0x14000, v146
	v_add_u32_e32 v244, 0x18000, v146
	v_add_u32_e32 v246, 0x1c000, v146
	global_load_lds_dwordx4 v[8:9], off
	v_lshl_add_u64 v[8:9], v[12:13], 0, s[86:87]
	s_mov_b32 m0, s30
	s_add_u32 s2, s14, 0x400080
	global_load_lds_dwordx4 v[8:9], off
	v_lshl_add_u64 v[8:9], v[14:15], 0, s[86:87]
	s_mov_b32 m0, s31
	s_addc_u32 s3, s15, 0
	s_add_i32 s34, s20, 0x1c000
	global_load_lds_dwordx4 v[8:9], off
	v_lshl_add_u64 v[8:9], s[2:3], 0, v[132:133]
	s_mov_b32 m0, s34
	s_add_i32 s35, s20, 0x1e000
	global_load_lds_dwordx4 v[8:9], off
	v_lshl_add_u64 v[8:9], s[2:3], 0, v[136:137]
	s_mov_b32 m0, s35
	s_lshl_b32 s4, s5, 4
	global_load_lds_dwordx4 v[8:9], off
	v_lshlrev_b32_e32 v8, 14, v2
	v_and_b32_e32 v8, 0xffff8000, v8
	v_lshl_add_u32 v3, v3, 11, v8
	v_and_b32_e32 v2, 1, v2
	v_lshl_or_b32 v2, v2, 6, v3
	v_lshl_add_u32 v140, v4, 1, v2
	v_lshlrev_b32_e32 v2, 14, v5
	v_and_b32_e32 v2, 0xffff8000, v2
	s_waitcnt vmcnt(6)
	s_and_b64 s[2:3], s[68:69], exec
	v_lshl_add_u32 v2, v6, 11, v2
	v_and_b32_e32 v3, 1, v5
	s_cselect_b32 s52, 7, 5
	s_lshl_b32 s2, s93, 1
	v_lshl_or_b32 v2, v3, 6, v2
	v_lshl_or_b32 v138, v16, 13, v17
	v_mov_b32_e32 v139, v0
	s_or_b32 s53, s2, 1
	v_mov_b32_e32 v141, v0
	v_lshl_add_u32 v142, v7, 1, v2
	v_mov_b32_e32 v143, v0
	s_mov_b32 s60, 0
	s_lshl_b32 s61, s4, 1
	s_mov_b64 s[6:7], s[12:13]
	s_mov_b64 s[8:9], s[14:15]
	s_barrier
	s_branch .LBB0_2269

; #define G_STAGE(bufoff, gbase, v0, v1) do { \
;     __builtin_amdgcn_global_load_lds((const unsigned*)((const char*)(gbase) + (v0)), (LAS unsigned*)(lds + (bufoff) + ldsw), 16, 0, 0); \
;     __builtin_amdgcn_global_load_lds((const unsigned*)((const char*)(gbase) + (v1)), (LAS unsigned*)(lds + (bufoff) + ldsw + 8192), 16, 0, 0); } while (0)
; #define G_LDA(dst, b, h) do { _Pragma("unroll") for (int m = 0; m < 4; ++m) _Pragma("unroll") for (int k = 0; k < 2; ++k) dst[m][k] = *(const LAS h8*)(lds + G_SA(b, h) + aoff + m * 2048 + k * 1024); } while (0)
; #define G_LDB(dst, b, h) do { _Pragma("unroll") for (int n = 0; n < 2; ++n) _Pragma("unroll") for (int k = 0; k < 2; ++k) dst[n][k] = *(const LAS h8*)(lds + G_SB(b, h) + boff + n * 2048 + k * 1024); } while (0)
; #define G_MMA(ai, bj, At, Bt) do { __builtin_amdgcn_s_setprio(1); _Pragma("unroll") for (int m = 0; m < 4; ++m) _Pragma("unroll") for (int n = 0; n < 2; ++n) _Pragma("unroll") for (int k = 0; k < 2; ++k) \
;     acc[ai][bj][m][n] = __builtin_amdgcn_mfma_f32_16x16x32_f16(Bt[n][k], At[m][k], acc[ai][bj][m][n], 0, 0, 0); __builtin_amdgcn_s_setprio(0); } while (0)
; #define G_WAIT_V(n) asm volatile("s_waitcnt vmcnt(" #n ")" ::: "memory")
; #define G_WAIT_L(n) asm volatile("s_waitcnt lgkmcnt(" #n ")" ::: "memory")
; #define G_BAR __builtin_amdgcn_s_barrier()
; #define G_SCHED __builtin_amdgcn_sched_barrier(0)
; template <bool PERM, class Sched, class Epi>
; DI void gemm256(LAS unsigned char* lds, const Sched& S, const Epi& E, int wv_) {
;     ...
;       const bool last = (t == nt - 2);
;       const char* a1 = cA + (size_t)(t + 1) * kstep;
;       const char* a2 = last ? nA : cA + (size_t)(t + 2) * kstep;
;       const char* b2 = last ? nB : cB + (size_t)(t + 2) * kstep;
;       const char* a3 = a2 + kstep;
;       const char* b3 = b2 + kstep;
;       G_LDB(B0, 0, 0); G_SCHED; G_LDA(At, 0, 0); G_STAGE(G_SA(1, 1), a1 + chA, cvA0, cvA1);
;       G_WAIT_L(8); G_BAR; G_WAIT_L(0); G_MMA(0, 0, At, B0); G_BAR; G_SCHED;
;       G_LDB(B1, 0, 1); G_STAGE(G_SB(0, 0), b2, cvB0, cvB1);
;       G_BAR; G_WAIT_L(0); G_MMA(0, 1, At, B1); G_BAR;
;       G_LDA(At, 0, 1); G_STAGE(G_SA(0, 0), a2, cvA0, cvA1);
;       G_BAR; G_WAIT_L(0); G_MMA(1, 0, At, B0); G_BAR; G_SCHED;
;       G_STAGE(G_SB(0, 1), b2 + chB, cvB0, cvB1);
;       G_WAIT_V(6); G_BAR; G_MMA(1, 1, At, B1); G_BAR;
.LBB0_2281:
	ds_read_b128 v[148:151], v239
	ds_read_b128 v[152:155], v239 offset:1024
	s_add_i32 s85, s14, 2
	ds_read_b128 v[156:159], v239 offset:2048
	ds_read_b128 v[160:163], v239 offset:3072
	s_add_u32 s15, s12, 0xfffc0080
	s_addc_u32 s16, s13, -1
	s_cmp_eq_u32 s75, s14
	s_cselect_b32 s14, s8, s46
	s_cselect_b32 s17, s7, s16
	s_cselect_b32 s16, s6, s15
	s_cselect_b32 s15, s9, s74
	v_lshl_add_u64 v[144:145], s[12:13], 0, v[140:141]
	s_add_i32 m0, s20, 0xc000
	ds_read_b128 v[164:167], v1
	ds_read_b128 v[168:171], v1 offset:1024
	ds_read_b128 v[172:175], v1 offset:2048
	ds_read_b128 v[176:179], v1 offset:3072
	ds_read_b128 v[180:183], v1 offset:4096
	ds_read_b128 v[184:187], v1 offset:5120
	ds_read_b128 v[188:191], v1 offset:6144
	ds_read_b128 v[192:195], v1 offset:7168
	global_load_lds_dwordx4 v[144:145], off
	v_lshl_add_u64 v[144:145], s[12:13], 0, v[142:143]
	s_add_i32 m0, s20, 0xe000
	s_nop 0
	global_load_lds_dwordx4 v[144:145], off
	s_waitcnt lgkmcnt(8)
	s_barrier
	s_waitcnt lgkmcnt(0)
	s_waitcnt lgkmcnt(0)
	v_mfma_f32_16x16x32_f16 v[114:117], v[148:151], v[164:167], v[114:117]
	v_mfma_f32_16x16x32_f16 v[126:129], v[156:159], v[164:167], v[126:129]
	v_mfma_f32_16x16x32_f16 v[98:101], v[148:151], v[172:175], v[98:101]
	v_mfma_f32_16x16x32_f16 v[110:113], v[156:159], v[172:175], v[110:113]
	v_mfma_f32_16x16x32_f16 v[82:85], v[148:151], v[180:183], v[82:85]
	v_mfma_f32_16x16x32_f16 v[94:97], v[156:159], v[180:183], v[94:97]
	v_mfma_f32_16x16x32_f16 v[66:69], v[148:151], v[188:191], v[66:69]
	v_mfma_f32_16x16x32_f16 v[78:81], v[156:159], v[188:191], v[78:81]
	v_mfma_f32_16x16x32_f16 v[114:117], v[152:155], v[168:171], v[114:117]
	v_mfma_f32_16x16x32_f16 v[126:129], v[160:163], v[168:171], v[126:129]
	v_mfma_f32_16x16x32_f16 v[98:101], v[152:155], v[176:179], v[98:101]
	v_mfma_f32_16x16x32_f16 v[110:113], v[160:163], v[176:179], v[110:113]
	v_mfma_f32_16x16x32_f16 v[82:85], v[152:155], v[184:187], v[82:85]
	v_mfma_f32_16x16x32_f16 v[94:97], v[160:163], v[184:187], v[94:97]
	v_mfma_f32_16x16x32_f16 v[66:69], v[152:155], v[192:195], v[66:69]
	v_mfma_f32_16x16x32_f16 v[78:81], v[160:163], v[192:195], v[78:81]
	s_barrier
	ds_read_b128 v[196:199], v243
	ds_read_b128 v[200:203], v243 offset:1024
	s_mov_b32 m0, s11
	ds_read_b128 v[204:207], v243 offset:2048
	ds_read_b128 v[208:211], v243 offset:3072
	v_lshl_add_u64 v[144:145], s[14:15], 0, v[132:133]
	global_load_lds_dwordx4 v[144:145], off
	v_lshl_add_u64 v[212:213], s[14:15], 0, v[136:137]
	s_mov_b32 m0, s21
	s_nop 0
	global_load_lds_dwordx4 v[212:213], off
	s_barrier
	s_waitcnt lgkmcnt(0)
	s_waitcnt lgkmcnt(0)
	v_mfma_f32_16x16x32_f16 v[122:125], v[196:199], v[164:167], v[122:125]
	v_mfma_f32_16x16x32_f16 v[118:121], v[204:207], v[164:167], v[118:121]
	v_mfma_f32_16x16x32_f16 v[106:109], v[196:199], v[172:175], v[106:109]
	v_mfma_f32_16x16x32_f16 v[102:105], v[204:207], v[172:175], v[102:105]
	v_mfma_f32_16x16x32_f16 v[90:93], v[196:199], v[180:183], v[90:93]
	v_mfma_f32_16x16x32_f16 v[86:89], v[204:207], v[180:183], v[86:89]
	v_mfma_f32_16x16x32_f16 v[74:77], v[196:199], v[188:191], v[74:77]
	v_mfma_f32_16x16x32_f16 v[70:73], v[204:207], v[188:191], v[70:73]
	v_mfma_f32_16x16x32_f16 v[122:125], v[200:203], v[168:171], v[122:125]
	v_mfma_f32_16x16x32_f16 v[118:121], v[208:211], v[168:171], v[118:121]
	v_mfma_f32_16x16x32_f16 v[106:109], v[200:203], v[176:179], v[106:109]
	v_mfma_f32_16x16x32_f16 v[102:105], v[208:211], v[176:179], v[102:105]
	v_mfma_f32_16x16x32_f16 v[90:93], v[200:203], v[184:187], v[90:93]
	v_mfma_f32_16x16x32_f16 v[86:89], v[208:211], v[184:187], v[86:89]
	v_mfma_f32_16x16x32_f16 v[74:77], v[200:203], v[192:195], v[74:77]
	v_mfma_f32_16x16x32_f16 v[70:73], v[208:211], v[192:195], v[70:73]
	s_mov_b32 m0, s20
	v_lshl_add_u64 v[214:215], s[16:17], 0, v[130:131]
	s_barrier
	ds_read_b128 v[164:167], v1 offset:16384
	ds_read_b128 v[168:171], v1 offset:17408
	ds_read_b128 v[172:175], v1 offset:18432
	ds_read_b128 v[176:179], v1 offset:19456
	ds_read_b128 v[180:183], v1 offset:20480
	ds_read_b128 v[184:187], v1 offset:21504
	ds_read_b128 v[188:191], v1 offset:22528
	ds_read_b128 v[192:195], v1 offset:23552
	global_load_lds_dwordx4 v[214:215], off
	v_lshl_add_u64 v[216:217], s[16:17], 0, v[134:135]
	s_mov_b32 m0, s22
	s_nop 0
	global_load_lds_dwordx4 v[216:217], off
	s_barrier
	s_waitcnt lgkmcnt(0)
	s_waitcnt lgkmcnt(0)
	v_mfma_f32_16x16x32_f16 v[50:53], v[148:151], v[164:167], v[50:53]
	v_mfma_f32_16x16x32_f16 v[62:65], v[156:159], v[164:167], v[62:65]
	v_mfma_f32_16x16x32_f16 v[34:37], v[148:151], v[172:175], v[34:37]
	v_mfma_f32_16x16x32_f16 v[46:49], v[156:159], v[172:175], v[46:49]
	v_mfma_f32_16x16x32_f16 v[18:21], v[148:151], v[180:183], v[18:21]
	v_mfma_f32_16x16x32_f16 v[30:33], v[156:159], v[180:183], v[30:33]
	v_mfma_f32_16x16x32_f16 v[2:5], v[148:151], v[188:191], v[2:5]
	v_mfma_f32_16x16x32_f16 v[14:17], v[156:159], v[188:191], v[14:17]
	v_mfma_f32_16x16x32_f16 v[50:53], v[152:155], v[168:171], v[50:53]
	v_mfma_f32_16x16x32_f16 v[62:65], v[160:163], v[168:171], v[62:65]
	v_mfma_f32_16x16x32_f16 v[34:37], v[152:155], v[176:179], v[34:37]
	v_mfma_f32_16x16x32_f16 v[46:49], v[160:163], v[176:179], v[46:49]
	v_mfma_f32_16x16x32_f16 v[18:21], v[152:155], v[184:187], v[18:21]
	v_mfma_f32_16x16x32_f16 v[30:33], v[160:163], v[184:187], v[30:33]
	v_mfma_f32_16x16x32_f16 v[2:5], v[152:155], v[192:195], v[2:5]
	v_mfma_f32_16x16x32_f16 v[14:17], v[160:163], v[192:195], v[14:17]
	s_barrier
	s_add_u32 s40, s14, 0x400000
	s_addc_u32 s41, s15, 0
	s_mov_b32 m0, s23
	v_lshl_add_u64 v[148:149], s[40:41], 0, v[132:133]
	global_load_lds_dwordx4 v[148:149], off
	v_lshl_add_u64 v[148:149], s[40:41], 0, v[136:137]
	s_mov_b32 m0, s24
	s_nop 0
	global_load_lds_dwordx4 v[148:149], off
	s_waitcnt vmcnt(6)
	s_barrier
; #define G_STAGE(bufoff, gbase, v0, v1) do { \
;     __builtin_amdgcn_global_load_lds((const unsigned*)((const char*)(gbase) + (v0)), (LAS unsigned*)(lds + (bufoff) + ldsw), 16, 0, 0); \
;     __builtin_amdgcn_global_load_lds((const unsigned*)((const char*)(gbase) + (v1)), (LAS unsigned*)(lds + (bufoff) + ldsw + 8192), 16, 0, 0); } while (0)
; #define G_LDA(dst, b, h) do { _Pragma("unroll") for (int m = 0; m < 4; ++m) _Pragma("unroll") for (int k = 0; k < 2; ++k) dst[m][k] = *(const LAS h8*)(lds + G_SA(b, h) + aoff + m * 2048 + k * 1024); } while (0)
; #define G_LDB(dst, b, h) do { _Pragma("unroll") for (int n = 0; n < 2; ++n) _Pragma("unroll") for (int k = 0; k < 2; ++k) dst[n][k] = *(const LAS h8*)(lds + G_SB(b, h) + boff + n * 2048 + k * 1024); } while (0)
; #define G_MMA(ai, bj, At, Bt) do { __builtin_amdgcn_s_setprio(1); _Pragma("unroll") for (int m = 0; m < 4; ++m) _Pragma("unroll") for (int n = 0; n < 2; ++n) _Pragma("unroll") for (int k = 0; k < 2; ++k) \
;     acc[ai][bj][m][n] = __builtin_amdgcn_mfma_f32_16x16x32_f16(Bt[n][k], At[m][k], acc[ai][bj][m][n], 0, 0, 0); __builtin_amdgcn_s_setprio(0); } while (0)
; #define G_WAIT_V(n) asm volatile("s_waitcnt vmcnt(" #n ")" ::: "memory")
; #define G_WAIT_L(n) asm volatile("s_waitcnt lgkmcnt(" #n ")" ::: "memory")
; #define G_BAR __builtin_amdgcn_s_barrier()
; #define G_SCHED __builtin_amdgcn_sched_barrier(0)
; template <bool PERM, class Sched, class Epi>
; DI void gemm256(LAS unsigned char* lds, const Sched& S, const Epi& E, int wv_) {
;     ...
;       G_WAIT_V(6); G_BAR; G_MMA(1, 1, At, B1); G_BAR;
;       G_LDB(B0, 1, 0); G_SCHED; G_LDA(At, 1, 0); G_STAGE(G_SA(0, 1), a2 + chA, cvA0, cvA1);
;       G_WAIT_L(8); G_BAR; G_WAIT_L(0); G_MMA(0, 0, At, B0); G_BAR; G_SCHED;
;       G_LDB(B1, 1, 1); G_STAGE(G_SB(1, 0), b3, cvB0, cvB1);
;       G_BAR; G_WAIT_L(0); G_MMA(0, 1, At, B1); G_BAR;
	v_mfma_f32_16x16x32_f16 v[58:61], v[196:199], v[164:167], v[58:61]
	v_mfma_f32_16x16x32_f16 v[54:57], v[204:207], v[164:167], v[54:57]
	v_mfma_f32_16x16x32_f16 v[42:45], v[196:199], v[172:175], v[42:45]
	v_mfma_f32_16x16x32_f16 v[38:41], v[204:207], v[172:175], v[38:41]
	v_mfma_f32_16x16x32_f16 v[26:29], v[196:199], v[180:183], v[26:29]
	v_mfma_f32_16x16x32_f16 v[22:25], v[204:207], v[180:183], v[22:25]
	v_mfma_f32_16x16x32_f16 v[10:13], v[196:199], v[188:191], v[10:13]
	v_mfma_f32_16x16x32_f16 v[6:9], v[204:207], v[188:191], v[6:9]
	v_mfma_f32_16x16x32_f16 v[58:61], v[200:203], v[168:171], v[58:61]
	v_mfma_f32_16x16x32_f16 v[54:57], v[208:211], v[168:171], v[54:57]
	v_mfma_f32_16x16x32_f16 v[42:45], v[200:203], v[176:179], v[42:45]
	v_mfma_f32_16x16x32_f16 v[38:41], v[208:211], v[176:179], v[38:41]
	v_mfma_f32_16x16x32_f16 v[26:29], v[200:203], v[184:187], v[26:29]
	v_mfma_f32_16x16x32_f16 v[22:25], v[208:211], v[184:187], v[22:25]
	v_mfma_f32_16x16x32_f16 v[10:13], v[200:203], v[192:195], v[10:13]
	v_mfma_f32_16x16x32_f16 v[6:9], v[208:211], v[192:195], v[6:9]
	s_barrier
	ds_read_b128 v[148:151], v244
	ds_read_b128 v[152:155], v244 offset:1024
	ds_read_b128 v[156:159], v244 offset:2048
	ds_read_b128 v[160:163], v244 offset:3072
	s_add_u32 s16, s16, 0x40000
	s_addc_u32 s17, s17, 0
	s_mov_b32 m0, s25
	v_lshl_add_u64 v[196:197], s[16:17], 0, v[130:131]
	ds_read_b128 v[164:167], v1 offset:32768
	ds_read_b128 v[168:171], v1 offset:33792
	ds_read_b128 v[172:175], v1 offset:34816
	ds_read_b128 v[176:179], v1 offset:35840
	ds_read_b128 v[180:183], v1 offset:36864
	ds_read_b128 v[184:187], v1 offset:37888
	ds_read_b128 v[188:191], v1 offset:38912
	ds_read_b128 v[192:195], v1 offset:39936
	global_load_lds_dwordx4 v[196:197], off
	v_lshl_add_u64 v[196:197], s[16:17], 0, v[134:135]
	s_mov_b32 m0, s26
	s_nop 0
	global_load_lds_dwordx4 v[196:197], off
	s_waitcnt lgkmcnt(8)
	s_barrier
	s_waitcnt lgkmcnt(0)
	s_waitcnt lgkmcnt(0)
	v_mfma_f32_16x16x32_f16 v[114:117], v[148:151], v[164:167], v[114:117]
	v_mfma_f32_16x16x32_f16 v[126:129], v[156:159], v[164:167], v[126:129]
	v_mfma_f32_16x16x32_f16 v[98:101], v[148:151], v[172:175], v[98:101]
	v_mfma_f32_16x16x32_f16 v[110:113], v[156:159], v[172:175], v[110:113]
	v_mfma_f32_16x16x32_f16 v[82:85], v[148:151], v[180:183], v[82:85]
	v_mfma_f32_16x16x32_f16 v[94:97], v[156:159], v[180:183], v[94:97]
	v_mfma_f32_16x16x32_f16 v[66:69], v[148:151], v[188:191], v[66:69]
	v_mfma_f32_16x16x32_f16 v[78:81], v[156:159], v[188:191], v[78:81]
	v_mfma_f32_16x16x32_f16 v[114:117], v[152:155], v[168:171], v[114:117]
	v_mfma_f32_16x16x32_f16 v[126:129], v[160:163], v[168:171], v[126:129]
	v_mfma_f32_16x16x32_f16 v[98:101], v[152:155], v[176:179], v[98:101]
	v_mfma_f32_16x16x32_f16 v[110:113], v[160:163], v[176:179], v[110:113]
	v_mfma_f32_16x16x32_f16 v[82:85], v[152:155], v[184:187], v[82:85]
	v_mfma_f32_16x16x32_f16 v[94:97], v[160:163], v[184:187], v[94:97]
	v_mfma_f32_16x16x32_f16 v[66:69], v[152:155], v[192:195], v[66:69]
	v_mfma_f32_16x16x32_f16 v[78:81], v[160:163], v[192:195], v[78:81]
	s_barrier
	s_mov_b32 m0, s28
	ds_read_b128 v[196:199], v246
	ds_read_b128 v[200:203], v246 offset:1024
	v_lshl_add_u64 v[144:145], v[144:145], 0, s[86:87]
	ds_read_b128 v[204:207], v246 offset:2048
	ds_read_b128 v[208:211], v246 offset:3072
	global_load_lds_dwordx4 v[144:145], off
	v_lshl_add_u64 v[144:145], v[212:213], 0, s[86:87]
	s_mov_b32 m0, s29
	s_nop 0
	global_load_lds_dwordx4 v[144:145], off
	s_barrier
; #define G_STAGE(bufoff, gbase, v0, v1) do { \
;     __builtin_amdgcn_global_load_lds((const unsigned*)((const char*)(gbase) + (v0)), (LAS unsigned*)(lds + (bufoff) + ldsw), 16, 0, 0); \
;     __builtin_amdgcn_global_load_lds((const unsigned*)((const char*)(gbase) + (v1)), (LAS unsigned*)(lds + (bufoff) + ldsw + 8192), 16, 0, 0); } while (0)
; #define G_LDA(dst, b, h) do { _Pragma("unroll") for (int m = 0; m < 4; ++m) _Pragma("unroll") for (int k = 0; k < 2; ++k) dst[m][k] = *(const LAS h8*)(lds + G_SA(b, h) + aoff + m * 2048 + k * 1024); } while (0)
; #define G_MMA(ai, bj, At, Bt) do { __builtin_amdgcn_s_setprio(1); _Pragma("unroll") for (int m = 0; m < 4; ++m) _Pragma("unroll") for (int n = 0; n < 2; ++n) _Pragma("unroll") for (int k = 0; k < 2; ++k) \
;     acc[ai][bj][m][n] = __builtin_amdgcn_mfma_f32_16x16x32_f16(Bt[n][k], At[m][k], acc[ai][bj][m][n], 0, 0, 0); __builtin_amdgcn_s_setprio(0); } while (0)
; #define G_WAIT_V(n) asm volatile("s_waitcnt vmcnt(" #n ")" ::: "memory")
; #define G_WAIT_L(n) asm volatile("s_waitcnt lgkmcnt(" #n ")" ::: "memory")
; #define G_BAR __builtin_amdgcn_s_barrier()
; #define G_SCHED __builtin_amdgcn_sched_barrier(0)
; template <bool PERM, class Sched, class Epi>
; DI void gemm256(LAS unsigned char* lds, const Sched& S, const Epi& E, int wv_) {
;     ...
;     for (int t = 0; t < nt; t += 2) {
;     ...
;       G_BAR; G_WAIT_L(0); G_MMA(0, 1, At, B1); G_BAR;
;       G_LDA(At, 1, 1); G_STAGE(G_SA(1, 0), a3, cvA0, cvA1);
;       G_BAR; G_WAIT_L(0); G_MMA(1, 0, At, B0); G_BAR; G_SCHED;
;       G_STAGE(G_SB(1, 1), b3 + chB, cvB0, cvB1);
;       G_WAIT_V(6); G_BAR; G_MMA(1, 1, At, B1); G_BAR;
	s_waitcnt lgkmcnt(0)
	s_waitcnt lgkmcnt(0)
	v_mfma_f32_16x16x32_f16 v[122:125], v[196:199], v[164:167], v[122:125]
	v_mfma_f32_16x16x32_f16 v[118:121], v[204:207], v[164:167], v[118:121]
	v_mfma_f32_16x16x32_f16 v[106:109], v[196:199], v[172:175], v[106:109]
	v_mfma_f32_16x16x32_f16 v[102:105], v[204:207], v[172:175], v[102:105]
	v_mfma_f32_16x16x32_f16 v[90:93], v[196:199], v[180:183], v[90:93]
	v_mfma_f32_16x16x32_f16 v[86:89], v[204:207], v[180:183], v[86:89]
	v_mfma_f32_16x16x32_f16 v[74:77], v[196:199], v[188:191], v[74:77]
	v_mfma_f32_16x16x32_f16 v[70:73], v[204:207], v[188:191], v[70:73]
	v_mfma_f32_16x16x32_f16 v[122:125], v[200:203], v[168:171], v[122:125]
	v_mfma_f32_16x16x32_f16 v[118:121], v[208:211], v[168:171], v[118:121]
	v_mfma_f32_16x16x32_f16 v[106:109], v[200:203], v[176:179], v[106:109]
	v_mfma_f32_16x16x32_f16 v[102:105], v[208:211], v[176:179], v[102:105]
	v_mfma_f32_16x16x32_f16 v[90:93], v[200:203], v[184:187], v[90:93]
	v_mfma_f32_16x16x32_f16 v[86:89], v[208:211], v[184:187], v[86:89]
	v_mfma_f32_16x16x32_f16 v[74:77], v[200:203], v[192:195], v[74:77]
	v_mfma_f32_16x16x32_f16 v[70:73], v[208:211], v[192:195], v[70:73]
	s_mov_b32 m0, s30
	v_lshl_add_u64 v[144:145], v[214:215], 0, s[86:87]
	s_barrier
	ds_read_b128 v[164:167], v1 offset:49152
	ds_read_b128 v[168:171], v1 offset:50176
	ds_read_b128 v[172:175], v1 offset:51200
	ds_read_b128 v[176:179], v1 offset:52224
	ds_read_b128 v[180:183], v1 offset:53248
	ds_read_b128 v[184:187], v1 offset:54272
	ds_read_b128 v[188:191], v1 offset:55296
	ds_read_b128 v[192:195], v1 offset:56320
	global_load_lds_dwordx4 v[144:145], off
	v_lshl_add_u64 v[144:145], v[216:217], 0, s[86:87]
	s_mov_b32 m0, s31
	s_nop 0
	global_load_lds_dwordx4 v[144:145], off
	s_barrier
	s_waitcnt lgkmcnt(0)
	s_waitcnt lgkmcnt(0)
	v_mfma_f32_16x16x32_f16 v[50:53], v[148:151], v[164:167], v[50:53]
	v_mfma_f32_16x16x32_f16 v[62:65], v[156:159], v[164:167], v[62:65]
	v_mfma_f32_16x16x32_f16 v[34:37], v[148:151], v[172:175], v[34:37]
	v_mfma_f32_16x16x32_f16 v[46:49], v[156:159], v[172:175], v[46:49]
	v_mfma_f32_16x16x32_f16 v[18:21], v[148:151], v[180:183], v[18:21]
	v_mfma_f32_16x16x32_f16 v[30:33], v[156:159], v[180:183], v[30:33]
	v_mfma_f32_16x16x32_f16 v[2:5], v[148:151], v[188:191], v[2:5]
	v_mfma_f32_16x16x32_f16 v[14:17], v[156:159], v[188:191], v[14:17]
	v_mfma_f32_16x16x32_f16 v[50:53], v[152:155], v[168:171], v[50:53]
	v_mfma_f32_16x16x32_f16 v[62:65], v[160:163], v[168:171], v[62:65]
	v_mfma_f32_16x16x32_f16 v[34:37], v[152:155], v[176:179], v[34:37]
	v_mfma_f32_16x16x32_f16 v[46:49], v[160:163], v[176:179], v[46:49]
	v_mfma_f32_16x16x32_f16 v[18:21], v[152:155], v[184:187], v[18:21]
	v_mfma_f32_16x16x32_f16 v[30:33], v[160:163], v[184:187], v[30:33]
	v_mfma_f32_16x16x32_f16 v[2:5], v[152:155], v[192:195], v[2:5]
	v_mfma_f32_16x16x32_f16 v[14:17], v[160:163], v[192:195], v[14:17]
	s_barrier
	s_add_u32 s14, s14, 0x400080
	s_addc_u32 s15, s15, 0
	s_mov_b32 m0, s34
	v_lshl_add_u64 v[144:145], s[14:15], 0, v[132:133]
	global_load_lds_dwordx4 v[144:145], off
	v_lshl_add_u64 v[144:145], s[14:15], 0, v[136:137]
	s_mov_b32 m0, s35
	s_nop 0
	global_load_lds_dwordx4 v[144:145], off
	s_waitcnt vmcnt(6)
	s_barrier
	v_mfma_f32_16x16x32_f16 v[58:61], v[196:199], v[164:167], v[58:61]
	v_mfma_f32_16x16x32_f16 v[54:57], v[204:207], v[164:167], v[54:57]
	v_mfma_f32_16x16x32_f16 v[42:45], v[196:199], v[172:175], v[42:45]
	v_mfma_f32_16x16x32_f16 v[38:41], v[204:207], v[172:175], v[38:41]
	v_mfma_f32_16x16x32_f16 v[26:29], v[196:199], v[180:183], v[26:29]
	v_mfma_f32_16x16x32_f16 v[22:25], v[204:207], v[180:183], v[22:25]
	v_mfma_f32_16x16x32_f16 v[10:13], v[196:199], v[188:191], v[10:13]
	v_mfma_f32_16x16x32_f16 v[6:9], v[204:207], v[188:191], v[6:9]
	v_mfma_f32_16x16x32_f16 v[58:61], v[200:203], v[168:171], v[58:61]
	v_mfma_f32_16x16x32_f16 v[54:57], v[208:211], v[168:171], v[54:57]
	v_mfma_f32_16x16x32_f16 v[42:45], v[200:203], v[176:179], v[42:45]
	v_mfma_f32_16x16x32_f16 v[38:41], v[208:211], v[176:179], v[38:41]
	v_mfma_f32_16x16x32_f16 v[26:29], v[200:203], v[184:187], v[26:29]
	v_mfma_f32_16x16x32_f16 v[22:25], v[208:211], v[184:187], v[22:25]
	v_mfma_f32_16x16x32_f16 v[10:13], v[200:203], v[192:195], v[10:13]
	v_mfma_f32_16x16x32_f16 v[6:9], v[208:211], v[192:195], v[6:9]
	s_add_u32 s12, s12, 0x100
	s_addc_u32 s13, s13, 0
	s_add_u32 s46, s46, 0x100
	s_addc_u32 s74, s74, 0
	s_cmp_ge_i32 s85, s5
	s_mov_b32 s14, s85
	s_barrier
	s_cbranch_scc0 .LBB0_2281
	s_branch .LBB0_2268

;   static DI int bmap(bool perm, int R) { return perm ? ((R & ~31) + perm32(R & 31)) : R; }
; #define G_STAGE(bufoff, gbase, v0, v1) do { \
;     __builtin_amdgcn_global_load_lds((const unsigned*)((const char*)(gbase) + (v0)), (LAS unsigned*)(lds + (bufoff) + ldsw), 16, 0, 0); \
;     __builtin_amdgcn_global_load_lds((const unsigned*)((const char*)(gbase) + (v1)), (LAS unsigned*)(lds + (bufoff) + ldsw + 8192), 16, 0, 0); } while (0)
; #define G_WAIT_V(n) asm volatile("s_waitcnt vmcnt(" #n ")" ::: "memory")
; #define G_BAR __builtin_amdgcn_s_barrier()
;   static DI int bmap(bool, int R) { return ((R >> 4) & 1) * 1024 + (R >> 5) * 16 + (R & 15); }
; template <bool PERM, class Sched, class Epi>
; DI void gemm256(LAS unsigned char* lds, const Sched& S, const Epi& E, int wv_) {
;   const int tid = tid_opaque(wv_), wid = __builtin_amdgcn_readfirstlane(tid >> 6), lane = tid & 63, wr = wid >> 2, wc = wid & 3, fr = lane & 15, fq = lane >> 4;
;   unsigned cvA0, cvA1, cvB0, cvB1;
;   { int R, C;
;     stage_rc(tid * 16, R, C); cvA0 = (unsigned)R * S.lda2 + C * 2; cvB0 = (unsigned)Sched::bmap(PERM, R) * S.ldb2 + C * 2;
;     stage_rc(tid * 16 + 8192, R, C); cvA1 = (unsigned)R * S.lda2 + C * 2; cvB1 = (unsigned)Sched::bmap(PERM, R) * S.ldb2 + C * 2; }
;   const size_t chA = (size_t)HALF * S.lda2, chB = (size_t)Sched::BHALF * S.ldb2;
;   const size_t kstep = (size_t)(BK * 2);
;   const unsigned ldsw = (unsigned)wid * 1024u;
;   const int aoff = lds_byte(wr * 64 + fr, fq * 8), boff = lds_byte(wc * 32 + fr, fq * 8);
;     ...
;   GUnit cur, nxt;
;   int ui = 0;
;   if (!S.next(0, cur)) return;
;   f4 acc[2][2][4][2];
; #pragma unroll
;   for (int a = 0; a < 2; ++a)
; #pragma unroll
;     for (int b = 0; b < 2; ++b)
; #pragma unroll
;       for (int m = 0; m < 4; ++m)
; #pragma unroll
;         for (int n = 0; n < 2; ++n) acc[a][b][m][n] = f4{0.f, 0.f, 0.f, 0.f};
;   h8 At[4][2], B0[2][2], B1[2][2];
;   const char* cA = cur.A;
;   const char* cB = cur.B;
;   G_STAGE(G_SB(0, 0), cB, cvB0, cvB1); G_STAGE(G_SA(0, 0), cA, cvA0, cvA1); G_STAGE(G_SB(0, 1), cB + chB, cvB0, cvB1); G_STAGE(G_SA(0, 1), cA + chA, cvA0, cvA1);
;   if (wr == 1) G_BAR;
;   G_WAIT_V(4); G_BAR;
;   G_STAGE(G_SB(1, 0), cB + kstep, cvB0, cvB1); G_STAGE(G_SA(1, 0), cA + kstep, cvA0, cvA1); G_STAGE(G_SB(1, 1), cB + chB + kstep, cvB0, cvB1);
;   G_WAIT_V(6); G_BAR;
.LBB0_2340:
	v_mov_b32_e32 v189, v0
	v_lshl_add_u64 v[8:9], s[10:11], 0, v[188:189]
	v_mov_b32_e32 v193, v0
	s_lshl_b32 s2, s2, 5
	s_add_i32 s26, s16, 0x18000
	v_lshl_add_u64 v[10:11], s[10:11], 0, v[192:193]
	v_mov_b32_e32 v187, v0
	s_and_b32 s25, s2, 0x60
	v_lshl_add_u64 v[8:9], v[8:9], 0, s[86:87]
	s_mov_b32 m0, s26
	s_add_i32 s27, s16, 0x1a000
	v_lshl_add_u64 v[12:13], s[8:9], 0, v[186:187]
	v_mov_b32_e32 v191, v0
	s_lshl_b32 s24, s3, 6
	s_lshl_b32 s4, s3, 13
	s_lshl_b32 s5, s25, 7
	s_waitcnt vmcnt(4)
	s_barrier
	global_load_lds_dwordx4 v[8:9], off
	v_lshl_add_u64 v[8:9], v[10:11], 0, s[86:87]
	s_mov_b32 m0, s27
	s_add_i32 s28, s16, 0x8000
	s_add_i32 s29, s16, 0xa000
	v_lshl_add_u64 v[14:15], s[8:9], 0, v[190:191]
	global_load_lds_dwordx4 v[8:9], off
	v_lshl_add_u64 v[8:9], v[12:13], 0, s[86:87]
	s_mov_b32 m0, s28
	s_add_u32 s2, s10, 0x10080
	global_load_lds_dwordx4 v[8:9], off
	v_lshl_add_u64 v[8:9], v[14:15], 0, s[86:87]
	s_mov_b32 m0, s29
	s_addc_u32 s3, s11, 0
	s_add_i32 s30, s16, 0x1c000
	global_load_lds_dwordx4 v[8:9], off
	v_lshl_add_u64 v[8:9], s[2:3], 0, v[188:189]
	s_mov_b32 m0, s30
	s_add_i32 s31, s16, 0x1e000
	global_load_lds_dwordx4 v[8:9], off
	v_lshl_add_u64 v[8:9], s[2:3], 0, v[192:193]
	s_mov_b32 m0, s31
	s_and_b64 s[2:3], s[68:69], exec
	global_load_lds_dwordx4 v[8:9], off
	v_and_b32_e32 v8, 15, v1
	v_and_b32_e32 v9, 48, v1
	v_lshlrev_b32_e32 v1, 2, v1
	v_lshl_or_b32 v10, v8, 6, v9
	v_and_b32_e32 v1, 32, v1
	v_bitop3_b32 v184, v10, s4, v1 bitop3:0xde
	v_bitop3_b32 v185, s5, v10, v1 bitop3:0xf6
	v_add_u32_e32 v201, 0x10000, v185
	v_add_u32_e32 v239, 0x14000, v185
	v_add_u32_e32 v243, 0x18000, v185
	v_add_u32_e32 v244, 0x1c000, v185
	v_lshlrev_b32_e32 v1, 14, v2
	v_and_b32_e32 v1, 0xffff8000, v1
	v_lshl_add_u32 v1, v3, 11, v1
	v_and_b32_e32 v2, 1, v2
	v_lshl_or_b32 v1, v2, 6, v1
	v_lshl_add_u32 v196, v4, 1, v1
	v_lshlrev_b32_e32 v1, 14, v5
	v_and_b32_e32 v1, 0xffff8000, v1
	v_lshl_add_u32 v1, v6, 11, v1
	v_and_b32_e32 v2, 1, v5
	s_waitcnt vmcnt(6)
	v_lshl_or_b32 v1, v2, 6, v1
	v_mov_b32_e32 v2, v0
	v_mov_b32_e32 v3, v0
	v_lshl_or_b32 v194, v8, 13, v9
	v_lshl_or_b32 v200, v8, 11, v9
	s_cselect_b32 s34, 5, 3
	s_lshr_b32 s2, s93, 1
	v_lshl_add_u32 v198, v7, 1, v1
	v_mov_b32_e32 v1, v0
	v_mov_b64_e32 v[6:7], v[2:3]
	v_mov_b64_e32 v[10:11], v[2:3]
	v_mov_b64_e32 v[14:15], v[2:3]
	v_mov_b64_e32 v[18:19], v[2:3]
	v_mov_b64_e32 v[22:23], v[2:3]
	v_mov_b64_e32 v[26:27], v[2:3]
	v_mov_b64_e32 v[30:31], v[2:3]
	v_mov_b64_e32 v[34:35], v[2:3]
	v_mov_b64_e32 v[38:39], v[2:3]
	v_mov_b64_e32 v[42:43], v[2:3]
	v_mov_b64_e32 v[46:47], v[2:3]
	v_mov_b64_e32 v[50:51], v[2:3]
	v_mov_b64_e32 v[54:55], v[2:3]
	v_mov_b64_e32 v[58:59], v[2:3]
	v_mov_b64_e32 v[62:63], v[2:3]
	v_mov_b64_e32 v[66:67], v[2:3]
	v_mov_b64_e32 v[70:71], v[2:3]
	v_mov_b64_e32 v[74:75], v[2:3]
	v_mov_b64_e32 v[78:79], v[2:3]
	v_mov_b64_e32 v[82:83], v[2:3]
	v_mov_b64_e32 v[86:87], v[2:3]
	v_mov_b64_e32 v[90:91], v[2:3]
	v_mov_b64_e32 v[94:95], v[2:3]
	v_mov_b64_e32 v[98:99], v[2:3]
	v_mov_b64_e32 v[102:103], v[2:3]
	v_mov_b64_e32 v[106:107], v[2:3]
	v_mov_b64_e32 v[110:111], v[2:3]
	v_mov_b64_e32 v[114:115], v[2:3]
	v_mov_b64_e32 v[118:119], v[2:3]
	v_mov_b64_e32 v[122:123], v[2:3]
	v_mov_b64_e32 v[126:127], v[2:3]
	v_mov_b64_e32 v[130:131], v[2:3]
	v_mov_b32_e32 v195, v0
	s_or_b32 s35, s2, 1
	v_mov_b32_e32 v197, v0
	v_mov_b32_e32 v199, v0
	s_mov_b32 s68, 0
	v_mov_b64_e32 v[4:5], v[0:1]
	v_mov_b64_e32 v[8:9], v[0:1]
	v_mov_b64_e32 v[12:13], v[0:1]
	v_mov_b64_e32 v[16:17], v[0:1]
	v_mov_b64_e32 v[20:21], v[0:1]
	v_mov_b64_e32 v[24:25], v[0:1]
	v_mov_b64_e32 v[28:29], v[0:1]
	v_mov_b64_e32 v[32:33], v[0:1]
	v_mov_b64_e32 v[36:37], v[0:1]
	v_mov_b64_e32 v[40:41], v[0:1]
	v_mov_b64_e32 v[44:45], v[0:1]
	v_mov_b64_e32 v[48:49], v[0:1]
	v_mov_b64_e32 v[52:53], v[0:1]
	v_mov_b64_e32 v[56:57], v[0:1]
	v_mov_b64_e32 v[60:61], v[0:1]
	v_mov_b64_e32 v[64:65], v[0:1]
	v_mov_b64_e32 v[68:69], v[0:1]
	v_mov_b64_e32 v[72:73], v[0:1]
	v_mov_b64_e32 v[76:77], v[0:1]
	v_mov_b64_e32 v[80:81], v[0:1]
	v_mov_b64_e32 v[84:85], v[0:1]
	v_mov_b64_e32 v[88:89], v[0:1]
	v_mov_b64_e32 v[92:93], v[0:1]
	v_mov_b64_e32 v[96:97], v[0:1]
	v_mov_b64_e32 v[100:101], v[0:1]
	v_mov_b64_e32 v[104:105], v[0:1]
	v_mov_b64_e32 v[108:109], v[0:1]
	v_mov_b64_e32 v[112:113], v[0:1]
	v_mov_b64_e32 v[116:117], v[0:1]
	v_mov_b64_e32 v[120:121], v[0:1]
	v_mov_b64_e32 v[124:125], v[0:1]
	v_mov_b64_e32 v[128:129], v[0:1]
	s_mov_b32 s52, 0
	s_mov_b64 s[2:3], s[8:9]
	s_mov_b64 s[4:5], s[10:11]
	s_barrier
	s_branch .LBB0_2343

; #define G_STAGE(bufoff, gbase, v0, v1) do { \
;     __builtin_amdgcn_global_load_lds((const unsigned*)((const char*)(gbase) + (v0)), (LAS unsigned*)(lds + (bufoff) + ldsw), 16, 0, 0); \
;     __builtin_amdgcn_global_load_lds((const unsigned*)((const char*)(gbase) + (v1)), (LAS unsigned*)(lds + (bufoff) + ldsw + 8192), 16, 0, 0); } while (0)
; #define G_LDA(dst, b, h) do { _Pragma("unroll") for (int m = 0; m < 4; ++m) _Pragma("unroll") for (int k = 0; k < 2; ++k) dst[m][k] = *(const LAS h8*)(lds + G_SA(b, h) + aoff + m * 2048 + k * 1024); } while (0)
; #define G_LDB(dst, b, h) do { _Pragma("unroll") for (int n = 0; n < 2; ++n) _Pragma("unroll") for (int k = 0; k < 2; ++k) dst[n][k] = *(const LAS h8*)(lds + G_SB(b, h) + boff + n * 2048 + k * 1024); } while (0)
; #define G_MMA(ai, bj, At, Bt) do { __builtin_amdgcn_s_setprio(1); _Pragma("unroll") for (int m = 0; m < 4; ++m) _Pragma("unroll") for (int n = 0; n < 2; ++n) _Pragma("unroll") for (int k = 0; k < 2; ++k) \
;     acc[ai][bj][m][n] = __builtin_amdgcn_mfma_f32_16x16x32_f16(Bt[n][k], At[m][k], acc[ai][bj][m][n], 0, 0, 0); __builtin_amdgcn_s_setprio(0); } while (0)
; #define G_WAIT_V(n) asm volatile("s_waitcnt vmcnt(" #n ")" ::: "memory")
; #define G_WAIT_L(n) asm volatile("s_waitcnt lgkmcnt(" #n ")" ::: "memory")
; #define G_BAR __builtin_amdgcn_s_barrier()
; #define G_SCHED __builtin_amdgcn_sched_barrier(0)
; template <bool PERM, class Sched, class Epi>
; DI void gemm256(LAS unsigned char* lds, const Sched& S, const Epi& E, int wv_) {
;     ...
;       const bool last = (t == nt - 2);
;       const char* a1 = cA + (size_t)(t + 1) * kstep;
;       const char* a2 = last ? nA : cA + (size_t)(t + 2) * kstep;
;       const char* b2 = last ? nB : cB + (size_t)(t + 2) * kstep;
;       const char* a3 = a2 + kstep;
;       const char* b3 = b2 + kstep;
;       G_LDB(B0, 0, 0); G_SCHED; G_LDA(At, 0, 0); G_STAGE(G_SA(1, 1), a1 + chA, cvA0, cvA1);
;       G_WAIT_L(8); G_BAR; G_WAIT_L(0); G_MMA(0, 0, At, B0); G_BAR; G_SCHED;
;       G_LDB(B1, 0, 1); G_STAGE(G_SB(0, 0), b2, cvB0, cvB1);
;       G_BAR; G_WAIT_L(0); G_MMA(0, 1, At, B1); G_BAR;
;       G_LDA(At, 0, 1); G_STAGE(G_SA(0, 0), a2, cvA0, cvA1);
;       G_BAR; G_WAIT_L(0); G_MMA(1, 0, At, B0); G_BAR; G_SCHED;
;       G_STAGE(G_SB(0, 1), b2 + chB, cvB0, cvB1);
;       G_WAIT_V(6); G_BAR; G_MMA(1, 1, At, B1); G_BAR;
.LBB0_2355:
	ds_read_b128 v[132:135], v201
	ds_read_b128 v[136:139], v201 offset:1024
	s_add_i32 s85, s10, 2
	ds_read_b128 v[140:143], v201 offset:2048
	ds_read_b128 v[144:147], v201 offset:3072
	s_add_u32 s11, s8, 0xfffc0080
	s_addc_u32 s12, s9, -1
	s_cmp_eq_u32 s69, s10
	s_cselect_b32 s10, s4, s74
	s_cselect_b32 s13, s3, s12
	s_cselect_b32 s12, s2, s11
	s_cselect_b32 s11, s5, s75
	v_lshl_add_u64 v[2:3], s[8:9], 0, v[196:197]
	s_add_i32 m0, s16, 0xc000
	ds_read_b128 v[148:151], v184
	ds_read_b128 v[152:155], v184 offset:1024
	ds_read_b128 v[156:159], v184 offset:2048
	ds_read_b128 v[160:163], v184 offset:3072
	ds_read_b128 v[164:167], v184 offset:4096
	ds_read_b128 v[168:171], v184 offset:5120
	ds_read_b128 v[172:175], v184 offset:6144
	ds_read_b128 v[176:179], v184 offset:7168
	global_load_lds_dwordx4 v[2:3], off
	v_lshl_add_u64 v[2:3], s[8:9], 0, v[198:199]
	s_add_i32 m0, s16, 0xe000
	s_nop 0
	global_load_lds_dwordx4 v[2:3], off
	s_waitcnt lgkmcnt(8)
	s_barrier
	s_waitcnt lgkmcnt(0)
	s_waitcnt lgkmcnt(0)
	v_mfma_f32_16x16x32_f16 v[128:131], v[132:135], v[148:151], v[128:131]
	v_mfma_f32_16x16x32_f16 v[124:127], v[140:143], v[148:151], v[124:127]
	v_mfma_f32_16x16x32_f16 v[120:123], v[132:135], v[156:159], v[120:123]
	v_mfma_f32_16x16x32_f16 v[116:119], v[140:143], v[156:159], v[116:119]
	v_mfma_f32_16x16x32_f16 v[112:115], v[132:135], v[164:167], v[112:115]
	v_mfma_f32_16x16x32_f16 v[108:111], v[140:143], v[164:167], v[108:111]
	v_mfma_f32_16x16x32_f16 v[104:107], v[132:135], v[172:175], v[104:107]
	v_mfma_f32_16x16x32_f16 v[100:103], v[140:143], v[172:175], v[100:103]
	v_mfma_f32_16x16x32_f16 v[128:131], v[136:139], v[152:155], v[128:131]
	v_mfma_f32_16x16x32_f16 v[124:127], v[144:147], v[152:155], v[124:127]
	v_mfma_f32_16x16x32_f16 v[120:123], v[136:139], v[160:163], v[120:123]
	v_mfma_f32_16x16x32_f16 v[116:119], v[144:147], v[160:163], v[116:119]
	v_mfma_f32_16x16x32_f16 v[112:115], v[136:139], v[168:171], v[112:115]
	v_mfma_f32_16x16x32_f16 v[108:111], v[144:147], v[168:171], v[108:111]
	v_mfma_f32_16x16x32_f16 v[104:107], v[136:139], v[176:179], v[104:107]
	v_mfma_f32_16x16x32_f16 v[100:103], v[144:147], v[176:179], v[100:103]
	s_barrier
	s_mov_b32 m0, s17
	ds_read_b128 v[180:183], v239
	ds_read_b128 v[202:205], v239 offset:1024
	v_lshl_add_u64 v[214:215], s[10:11], 0, v[188:189]
	ds_read_b128 v[206:209], v239 offset:2048
	ds_read_b128 v[210:213], v239 offset:3072
	global_load_lds_dwordx4 v[214:215], off
	v_lshl_add_u64 v[216:217], s[10:11], 0, v[192:193]
	s_mov_b32 m0, s18
	s_nop 0
	global_load_lds_dwordx4 v[216:217], off
	s_barrier
	s_waitcnt lgkmcnt(0)
	s_waitcnt lgkmcnt(0)
	v_mfma_f32_16x16x32_f16 v[96:99], v[180:183], v[148:151], v[96:99]
	v_mfma_f32_16x16x32_f16 v[92:95], v[206:209], v[148:151], v[92:95]
	v_mfma_f32_16x16x32_f16 v[88:91], v[180:183], v[156:159], v[88:91]
	v_mfma_f32_16x16x32_f16 v[84:87], v[206:209], v[156:159], v[84:87]
	v_mfma_f32_16x16x32_f16 v[80:83], v[180:183], v[164:167], v[80:83]
	v_mfma_f32_16x16x32_f16 v[76:79], v[206:209], v[164:167], v[76:79]
	v_mfma_f32_16x16x32_f16 v[72:75], v[180:183], v[172:175], v[72:75]
	v_mfma_f32_16x16x32_f16 v[68:71], v[206:209], v[172:175], v[68:71]
	v_mfma_f32_16x16x32_f16 v[96:99], v[202:205], v[152:155], v[96:99]
	v_mfma_f32_16x16x32_f16 v[92:95], v[210:213], v[152:155], v[92:95]
	v_mfma_f32_16x16x32_f16 v[88:91], v[202:205], v[160:163], v[88:91]
	v_mfma_f32_16x16x32_f16 v[84:87], v[210:213], v[160:163], v[84:87]
	v_mfma_f32_16x16x32_f16 v[80:83], v[202:205], v[168:171], v[80:83]
	v_mfma_f32_16x16x32_f16 v[76:79], v[210:213], v[168:171], v[76:79]
	v_mfma_f32_16x16x32_f16 v[72:75], v[202:205], v[176:179], v[72:75]
	v_mfma_f32_16x16x32_f16 v[68:71], v[210:213], v[176:179], v[68:71]
	s_mov_b32 m0, s16
	v_lshl_add_u64 v[218:219], s[12:13], 0, v[186:187]
	s_barrier
	ds_read_b128 v[148:151], v184 offset:16384
	ds_read_b128 v[152:155], v184 offset:17408
	ds_read_b128 v[156:159], v184 offset:18432
	ds_read_b128 v[160:163], v184 offset:19456
	ds_read_b128 v[164:167], v184 offset:20480
	ds_read_b128 v[168:171], v184 offset:21504
	ds_read_b128 v[172:175], v184 offset:22528
	ds_read_b128 v[176:179], v184 offset:23552
	global_load_lds_dwordx4 v[218:219], off
	v_lshl_add_u64 v[220:221], s[12:13], 0, v[190:191]
	s_mov_b32 m0, s19
	s_nop 0
	global_load_lds_dwordx4 v[220:221], off
	s_barrier
	s_waitcnt lgkmcnt(0)
	s_waitcnt lgkmcnt(0)
	v_mfma_f32_16x16x32_f16 v[64:67], v[132:135], v[148:151], v[64:67]
	v_mfma_f32_16x16x32_f16 v[60:63], v[140:143], v[148:151], v[60:63]
	v_mfma_f32_16x16x32_f16 v[56:59], v[132:135], v[156:159], v[56:59]
	v_mfma_f32_16x16x32_f16 v[52:55], v[140:143], v[156:159], v[52:55]
	v_mfma_f32_16x16x32_f16 v[48:51], v[132:135], v[164:167], v[48:51]
	v_mfma_f32_16x16x32_f16 v[44:47], v[140:143], v[164:167], v[44:47]
	v_mfma_f32_16x16x32_f16 v[40:43], v[132:135], v[172:175], v[40:43]
	v_mfma_f32_16x16x32_f16 v[36:39], v[140:143], v[172:175], v[36:39]
	v_mfma_f32_16x16x32_f16 v[64:67], v[136:139], v[152:155], v[64:67]
	v_mfma_f32_16x16x32_f16 v[60:63], v[144:147], v[152:155], v[60:63]
	v_mfma_f32_16x16x32_f16 v[56:59], v[136:139], v[160:163], v[56:59]
	v_mfma_f32_16x16x32_f16 v[52:55], v[144:147], v[160:163], v[52:55]
	v_mfma_f32_16x16x32_f16 v[48:51], v[136:139], v[168:171], v[48:51]
	v_mfma_f32_16x16x32_f16 v[44:47], v[144:147], v[168:171], v[44:47]
	v_mfma_f32_16x16x32_f16 v[40:43], v[136:139], v[176:179], v[40:43]
	v_mfma_f32_16x16x32_f16 v[36:39], v[144:147], v[176:179], v[36:39]
	s_barrier
	s_add_u32 s40, s10, 0x10000
	s_addc_u32 s41, s11, 0
	s_mov_b32 m0, s20
	v_lshl_add_u64 v[2:3], s[40:41], 0, v[188:189]
	global_load_lds_dwordx4 v[2:3], off
	v_lshl_add_u64 v[2:3], s[40:41], 0, v[192:193]
	s_mov_b32 m0, s21
	s_nop 0
	global_load_lds_dwordx4 v[2:3], off
	s_waitcnt vmcnt(6)
	s_barrier
; #define G_STAGE(bufoff, gbase, v0, v1) do { \
;     __builtin_amdgcn_global_load_lds((const unsigned*)((const char*)(gbase) + (v0)), (LAS unsigned*)(lds + (bufoff) + ldsw), 16, 0, 0); \
;     __builtin_amdgcn_global_load_lds((const unsigned*)((const char*)(gbase) + (v1)), (LAS unsigned*)(lds + (bufoff) + ldsw + 8192), 16, 0, 0); } while (0)
; #define G_LDA(dst, b, h) do { _Pragma("unroll") for (int m = 0; m < 4; ++m) _Pragma("unroll") for (int k = 0; k < 2; ++k) dst[m][k] = *(const LAS h8*)(lds + G_SA(b, h) + aoff + m * 2048 + k * 1024); } while (0)
; #define G_LDB(dst, b, h) do { _Pragma("unroll") for (int n = 0; n < 2; ++n) _Pragma("unroll") for (int k = 0; k < 2; ++k) dst[n][k] = *(const LAS h8*)(lds + G_SB(b, h) + boff + n * 2048 + k * 1024); } while (0)
; #define G_MMA(ai, bj, At, Bt) do { __builtin_amdgcn_s_setprio(1); _Pragma("unroll") for (int m = 0; m < 4; ++m) _Pragma("unroll") for (int n = 0; n < 2; ++n) _Pragma("unroll") for (int k = 0; k < 2; ++k) \
;     acc[ai][bj][m][n] = __builtin_amdgcn_mfma_f32_16x16x32_f16(Bt[n][k], At[m][k], acc[ai][bj][m][n], 0, 0, 0); __builtin_amdgcn_s_setprio(0); } while (0)
; #define G_WAIT_V(n) asm volatile("s_waitcnt vmcnt(" #n ")" ::: "memory")
; #define G_WAIT_L(n) asm volatile("s_waitcnt lgkmcnt(" #n ")" ::: "memory")
; #define G_BAR __builtin_amdgcn_s_barrier()
; #define G_SCHED __builtin_amdgcn_sched_barrier(0)
; template <bool PERM, class Sched, class Epi>
; DI void gemm256(LAS unsigned char* lds, const Sched& S, const Epi& E, int wv_) {
;     ...
;       G_WAIT_V(6); G_BAR; G_MMA(1, 1, At, B1); G_BAR;
;       G_LDB(B0, 1, 0); G_SCHED; G_LDA(At, 1, 0); G_STAGE(G_SA(0, 1), a2 + chA, cvA0, cvA1);
;       G_WAIT_L(8); G_BAR; G_WAIT_L(0); G_MMA(0, 0, At, B0); G_BAR; G_SCHED;
;       G_LDB(B1, 1, 1); G_STAGE(G_SB(1, 0), b3, cvB0, cvB1);
;       G_BAR; G_WAIT_L(0); G_MMA(0, 1, At, B1); G_BAR;
	v_mfma_f32_16x16x32_f16 v[32:35], v[180:183], v[148:151], v[32:35]
	v_mfma_f32_16x16x32_f16 v[28:31], v[206:209], v[148:151], v[28:31]
	v_mfma_f32_16x16x32_f16 v[24:27], v[180:183], v[156:159], v[24:27]
	v_mfma_f32_16x16x32_f16 v[20:23], v[206:209], v[156:159], v[20:23]
	v_mfma_f32_16x16x32_f16 v[16:19], v[180:183], v[164:167], v[16:19]
	v_mfma_f32_16x16x32_f16 v[12:15], v[206:209], v[164:167], v[12:15]
	v_mfma_f32_16x16x32_f16 v[8:11], v[180:183], v[172:175], v[8:11]
	v_mfma_f32_16x16x32_f16 v[2:5], v[206:209], v[172:175], v[4:7]
	v_mfma_f32_16x16x32_f16 v[32:35], v[202:205], v[152:155], v[32:35]
	v_mfma_f32_16x16x32_f16 v[28:31], v[210:213], v[152:155], v[28:31]
	v_mfma_f32_16x16x32_f16 v[24:27], v[202:205], v[160:163], v[24:27]
	v_mfma_f32_16x16x32_f16 v[20:23], v[210:213], v[160:163], v[20:23]
	v_mfma_f32_16x16x32_f16 v[16:19], v[202:205], v[168:171], v[16:19]
	v_mfma_f32_16x16x32_f16 v[12:15], v[210:213], v[168:171], v[12:15]
	v_mfma_f32_16x16x32_f16 v[8:11], v[202:205], v[176:179], v[8:11]
	v_mfma_f32_16x16x32_f16 v[2:5], v[210:213], v[176:179], v[2:5]
	s_barrier
	ds_read_b128 v[132:135], v243
	ds_read_b128 v[136:139], v243 offset:1024
	ds_read_b128 v[140:143], v243 offset:2048
	ds_read_b128 v[144:147], v243 offset:3072
	s_add_u32 s12, s12, 0x40000
	s_addc_u32 s13, s13, 0
	s_mov_b32 m0, s22
	v_lshl_add_u64 v[6:7], s[12:13], 0, v[186:187]
	ds_read_b128 v[148:151], v184 offset:32768
	ds_read_b128 v[152:155], v184 offset:33792
	ds_read_b128 v[156:159], v184 offset:34816
	ds_read_b128 v[160:163], v184 offset:35840
	ds_read_b128 v[164:167], v184 offset:36864
	ds_read_b128 v[168:171], v184 offset:37888
	ds_read_b128 v[172:175], v184 offset:38912
	ds_read_b128 v[176:179], v184 offset:39936
	global_load_lds_dwordx4 v[6:7], off
	v_lshl_add_u64 v[6:7], s[12:13], 0, v[190:191]
	s_mov_b32 m0, s23
	s_nop 0
	global_load_lds_dwordx4 v[6:7], off
	s_waitcnt lgkmcnt(8)
	s_barrier
	s_waitcnt lgkmcnt(0)
	s_waitcnt lgkmcnt(0)
	v_mfma_f32_16x16x32_f16 v[128:131], v[132:135], v[148:151], v[128:131]
	v_mfma_f32_16x16x32_f16 v[124:127], v[140:143], v[148:151], v[124:127]
	v_mfma_f32_16x16x32_f16 v[120:123], v[132:135], v[156:159], v[120:123]
	v_mfma_f32_16x16x32_f16 v[116:119], v[140:143], v[156:159], v[116:119]
	v_mfma_f32_16x16x32_f16 v[112:115], v[132:135], v[164:167], v[112:115]
	v_mfma_f32_16x16x32_f16 v[108:111], v[140:143], v[164:167], v[108:111]
	v_mfma_f32_16x16x32_f16 v[104:107], v[132:135], v[172:175], v[104:107]
	v_mfma_f32_16x16x32_f16 v[100:103], v[140:143], v[172:175], v[100:103]
	v_mfma_f32_16x16x32_f16 v[128:131], v[136:139], v[152:155], v[128:131]
	v_mfma_f32_16x16x32_f16 v[124:127], v[144:147], v[152:155], v[124:127]
	v_mfma_f32_16x16x32_f16 v[120:123], v[136:139], v[160:163], v[120:123]
	v_mfma_f32_16x16x32_f16 v[116:119], v[144:147], v[160:163], v[116:119]
	v_mfma_f32_16x16x32_f16 v[112:115], v[136:139], v[168:171], v[112:115]
	v_mfma_f32_16x16x32_f16 v[108:111], v[144:147], v[168:171], v[108:111]
	v_mfma_f32_16x16x32_f16 v[104:107], v[136:139], v[176:179], v[104:107]
	v_mfma_f32_16x16x32_f16 v[100:103], v[144:147], v[176:179], v[100:103]
	s_barrier
	ds_read_b128 v[180:183], v244
	ds_read_b128 v[202:205], v244 offset:1024
	s_mov_b32 m0, s26
	ds_read_b128 v[206:209], v244 offset:2048
	ds_read_b128 v[210:213], v244 offset:3072
	v_lshl_add_u64 v[6:7], v[214:215], 0, s[86:87]
	global_load_lds_dwordx4 v[6:7], off
	v_lshl_add_u64 v[6:7], v[216:217], 0, s[86:87]
	s_mov_b32 m0, s27
	s_nop 0
	global_load_lds_dwordx4 v[6:7], off
	s_barrier
; #define G_STAGE(bufoff, gbase, v0, v1) do { \
;     __builtin_amdgcn_global_load_lds((const unsigned*)((const char*)(gbase) + (v0)), (LAS unsigned*)(lds + (bufoff) + ldsw), 16, 0, 0); \
;     __builtin_amdgcn_global_load_lds((const unsigned*)((const char*)(gbase) + (v1)), (LAS unsigned*)(lds + (bufoff) + ldsw + 8192), 16, 0, 0); } while (0)
; #define G_LDA(dst, b, h) do { _Pragma("unroll") for (int m = 0; m < 4; ++m) _Pragma("unroll") for (int k = 0; k < 2; ++k) dst[m][k] = *(const LAS h8*)(lds + G_SA(b, h) + aoff + m * 2048 + k * 1024); } while (0)
; #define G_MMA(ai, bj, At, Bt) do { __builtin_amdgcn_s_setprio(1); _Pragma("unroll") for (int m = 0; m < 4; ++m) _Pragma("unroll") for (int n = 0; n < 2; ++n) _Pragma("unroll") for (int k = 0; k < 2; ++k) \
;     acc[ai][bj][m][n] = __builtin_amdgcn_mfma_f32_16x16x32_f16(Bt[n][k], At[m][k], acc[ai][bj][m][n], 0, 0, 0); __builtin_amdgcn_s_setprio(0); } while (0)
; #define G_WAIT_V(n) asm volatile("s_waitcnt vmcnt(" #n ")" ::: "memory")
; #define G_WAIT_L(n) asm volatile("s_waitcnt lgkmcnt(" #n ")" ::: "memory")
; #define G_BAR __builtin_amdgcn_s_barrier()
; #define G_SCHED __builtin_amdgcn_sched_barrier(0)
; template <bool PERM, class Sched, class Epi>
; DI void gemm256(LAS unsigned char* lds, const Sched& S, const Epi& E, int wv_) {
;     ...
;     for (int t = 0; t < nt; t += 2) {
;     ...
;       G_BAR; G_WAIT_L(0); G_MMA(0, 1, At, B1); G_BAR;
;       G_LDA(At, 1, 1); G_STAGE(G_SA(1, 0), a3, cvA0, cvA1);
;       G_BAR; G_WAIT_L(0); G_MMA(1, 0, At, B0); G_BAR; G_SCHED;
;       G_STAGE(G_SB(1, 1), b3 + chB, cvB0, cvB1);
;       G_WAIT_V(6); G_BAR; G_MMA(1, 1, At, B1); G_BAR;
	s_waitcnt lgkmcnt(0)
	s_waitcnt lgkmcnt(0)
	v_mfma_f32_16x16x32_f16 v[96:99], v[180:183], v[148:151], v[96:99]
	v_mfma_f32_16x16x32_f16 v[92:95], v[206:209], v[148:151], v[92:95]
	v_mfma_f32_16x16x32_f16 v[88:91], v[180:183], v[156:159], v[88:91]
	v_mfma_f32_16x16x32_f16 v[84:87], v[206:209], v[156:159], v[84:87]
	v_mfma_f32_16x16x32_f16 v[80:83], v[180:183], v[164:167], v[80:83]
	v_mfma_f32_16x16x32_f16 v[76:79], v[206:209], v[164:167], v[76:79]
	v_mfma_f32_16x16x32_f16 v[72:75], v[180:183], v[172:175], v[72:75]
	v_mfma_f32_16x16x32_f16 v[68:71], v[206:209], v[172:175], v[68:71]
	v_mfma_f32_16x16x32_f16 v[96:99], v[202:205], v[152:155], v[96:99]
	v_mfma_f32_16x16x32_f16 v[92:95], v[210:213], v[152:155], v[92:95]
	v_mfma_f32_16x16x32_f16 v[88:91], v[202:205], v[160:163], v[88:91]
	v_mfma_f32_16x16x32_f16 v[84:87], v[210:213], v[160:163], v[84:87]
	v_mfma_f32_16x16x32_f16 v[80:83], v[202:205], v[168:171], v[80:83]
	v_mfma_f32_16x16x32_f16 v[76:79], v[210:213], v[168:171], v[76:79]
	v_mfma_f32_16x16x32_f16 v[72:75], v[202:205], v[176:179], v[72:75]
	v_mfma_f32_16x16x32_f16 v[68:71], v[210:213], v[176:179], v[68:71]
	s_mov_b32 m0, s28
	v_lshl_add_u64 v[6:7], v[218:219], 0, s[86:87]
	s_barrier
	ds_read_b128 v[148:151], v184 offset:49152
	ds_read_b128 v[152:155], v184 offset:50176
	ds_read_b128 v[156:159], v184 offset:51200
	ds_read_b128 v[160:163], v184 offset:52224
	ds_read_b128 v[164:167], v184 offset:53248
	ds_read_b128 v[168:171], v184 offset:54272
	ds_read_b128 v[172:175], v184 offset:55296
	ds_read_b128 v[176:179], v184 offset:56320
	global_load_lds_dwordx4 v[6:7], off
	v_lshl_add_u64 v[6:7], v[220:221], 0, s[86:87]
	s_mov_b32 m0, s29
	s_nop 0
	global_load_lds_dwordx4 v[6:7], off
	s_barrier
	s_waitcnt lgkmcnt(0)
	s_waitcnt lgkmcnt(0)
	v_mfma_f32_16x16x32_f16 v[64:67], v[132:135], v[148:151], v[64:67]
	v_mfma_f32_16x16x32_f16 v[60:63], v[140:143], v[148:151], v[60:63]
	v_mfma_f32_16x16x32_f16 v[56:59], v[132:135], v[156:159], v[56:59]
	v_mfma_f32_16x16x32_f16 v[52:55], v[140:143], v[156:159], v[52:55]
	v_mfma_f32_16x16x32_f16 v[48:51], v[132:135], v[164:167], v[48:51]
	v_mfma_f32_16x16x32_f16 v[44:47], v[140:143], v[164:167], v[44:47]
	v_mfma_f32_16x16x32_f16 v[40:43], v[132:135], v[172:175], v[40:43]
	v_mfma_f32_16x16x32_f16 v[36:39], v[140:143], v[172:175], v[36:39]
	v_mfma_f32_16x16x32_f16 v[64:67], v[136:139], v[152:155], v[64:67]
	v_mfma_f32_16x16x32_f16 v[60:63], v[144:147], v[152:155], v[60:63]
	v_mfma_f32_16x16x32_f16 v[56:59], v[136:139], v[160:163], v[56:59]
	v_mfma_f32_16x16x32_f16 v[52:55], v[144:147], v[160:163], v[52:55]
	v_mfma_f32_16x16x32_f16 v[48:51], v[136:139], v[168:171], v[48:51]
	v_mfma_f32_16x16x32_f16 v[44:47], v[144:147], v[168:171], v[44:47]
	v_mfma_f32_16x16x32_f16 v[40:43], v[136:139], v[176:179], v[40:43]
	v_mfma_f32_16x16x32_f16 v[36:39], v[144:147], v[176:179], v[36:39]
	s_barrier
	s_add_u32 s10, s10, 0x10080
	s_addc_u32 s11, s11, 0
	s_mov_b32 m0, s30
	v_lshl_add_u64 v[6:7], s[10:11], 0, v[188:189]
	global_load_lds_dwordx4 v[6:7], off
	v_lshl_add_u64 v[6:7], s[10:11], 0, v[192:193]
	s_mov_b32 m0, s31
	s_nop 0
	global_load_lds_dwordx4 v[6:7], off
	s_waitcnt vmcnt(6)
	s_barrier
	v_mfma_f32_16x16x32_f16 v[32:35], v[180:183], v[148:151], v[32:35]
	v_mfma_f32_16x16x32_f16 v[28:31], v[206:209], v[148:151], v[28:31]
	v_mfma_f32_16x16x32_f16 v[24:27], v[180:183], v[156:159], v[24:27]
	v_mfma_f32_16x16x32_f16 v[20:23], v[206:209], v[156:159], v[20:23]
	v_mfma_f32_16x16x32_f16 v[16:19], v[180:183], v[164:167], v[16:19]
	v_mfma_f32_16x16x32_f16 v[12:15], v[206:209], v[164:167], v[12:15]
	v_mfma_f32_16x16x32_f16 v[6:9], v[180:183], v[172:175], v[8:11]
	v_mfma_f32_16x16x32_f16 v[2:5], v[206:209], v[172:175], v[2:5]
	v_mfma_f32_16x16x32_f16 v[32:35], v[202:205], v[152:155], v[32:35]
	v_mfma_f32_16x16x32_f16 v[28:31], v[210:213], v[152:155], v[28:31]
	v_mfma_f32_16x16x32_f16 v[24:27], v[202:205], v[160:163], v[24:27]
	v_mfma_f32_16x16x32_f16 v[20:23], v[210:213], v[160:163], v[20:23]
	v_mfma_f32_16x16x32_f16 v[16:19], v[202:205], v[168:171], v[16:19]
	v_mfma_f32_16x16x32_f16 v[12:15], v[210:213], v[168:171], v[12:15]
	v_mfma_f32_16x16x32_f16 v[8:11], v[202:205], v[176:179], v[6:9]
	v_mfma_f32_16x16x32_f16 v[4:7], v[210:213], v[176:179], v[2:5]
	s_add_u32 s8, s8, 0x100
	s_addc_u32 s9, s9, 0
	s_add_u32 s74, s74, 0x100
	s_addc_u32 s75, s75, 0
	s_cmp_ge_i32 s85, s46
	s_mov_b32 s10, s85
	s_barrier
	s_cbranch_scc0 .LBB0_2355

;   static DI int bmap(bool perm, int R) { return perm ? ((R & ~31) + perm32(R & 31)) : R; }
; #define G_STAGE(bufoff, gbase, v0, v1) do { \
;     __builtin_amdgcn_global_load_lds((const unsigned*)((const char*)(gbase) + (v0)), (LAS unsigned*)(lds + (bufoff) + ldsw), 16, 0, 0); \
;     __builtin_amdgcn_global_load_lds((const unsigned*)((const char*)(gbase) + (v1)), (LAS unsigned*)(lds + (bufoff) + ldsw + 8192), 16, 0, 0); } while (0)
; #define G_WAIT_V(n) asm volatile("s_waitcnt vmcnt(" #n ")" ::: "memory")
; #define G_BAR __builtin_amdgcn_s_barrier()
;   static DI int bmap(bool, int R) { return ((R >> 4) & 1) * 1024 + (R >> 5) * 16 + (R & 15); }
; template <bool PERM, class Sched, class Epi>
; DI void gemm256(LAS unsigned char* lds, const Sched& S, const Epi& E, int wv_) {
;   const int tid = tid_opaque(wv_), wid = __builtin_amdgcn_readfirstlane(tid >> 6), lane = tid & 63, wr = wid >> 2, wc = wid & 3, fr = lane & 15, fq = lane >> 4;
;   unsigned cvA0, cvA1, cvB0, cvB1;
;   { int R, C;
;     stage_rc(tid * 16, R, C); cvA0 = (unsigned)R * S.lda2 + C * 2; cvB0 = (unsigned)Sched::bmap(PERM, R) * S.ldb2 + C * 2;
;     stage_rc(tid * 16 + 8192, R, C); cvA1 = (unsigned)R * S.lda2 + C * 2; cvB1 = (unsigned)Sched::bmap(PERM, R) * S.ldb2 + C * 2; }
;   const size_t chA = (size_t)HALF * S.lda2, chB = (size_t)Sched::BHALF * S.ldb2;
;   const size_t kstep = (size_t)(BK * 2);
;   const unsigned ldsw = (unsigned)wid * 1024u;
;   const int aoff = lds_byte(wr * 64 + fr, fq * 8), boff = lds_byte(wc * 32 + fr, fq * 8);
;     ...
;   GUnit cur, nxt;
;   int ui = 0;
;   if (!S.next(0, cur)) return;
;   f4 acc[2][2][4][2];
; #pragma unroll
;   for (int a = 0; a < 2; ++a)
; #pragma unroll
;     for (int b = 0; b < 2; ++b)
; #pragma unroll
;       for (int m = 0; m < 4; ++m)
; #pragma unroll
;         for (int n = 0; n < 2; ++n) acc[a][b][m][n] = f4{0.f, 0.f, 0.f, 0.f};
;   h8 At[4][2], B0[2][2], B1[2][2];
;   const char* cA = cur.A;
;   const char* cB = cur.B;
;   G_STAGE(G_SB(0, 0), cB, cvB0, cvB1); G_STAGE(G_SA(0, 0), cA, cvA0, cvA1); G_STAGE(G_SB(0, 1), cB + chB, cvB0, cvB1); G_STAGE(G_SA(0, 1), cA + chA, cvA0, cvA1);
;   if (wr == 1) G_BAR;
;   G_WAIT_V(4); G_BAR;
;   G_STAGE(G_SB(1, 0), cB + kstep, cvB0, cvB1); G_STAGE(G_SA(1, 0), cA + kstep, cvA0, cvA1); G_STAGE(G_SB(1, 1), cB + chB + kstep, cvB0, cvB1);
;   G_WAIT_V(6); G_BAR;
.LBB0_2420:
	v_mov_b32_e32 v151, v0
	v_lshl_add_u64 v[8:9], s[20:21], 0, v[150:151]
	v_mov_b32_e32 v153, v0
	s_lshl_b32 s5, s5, 5
	s_add_i32 s69, s31, 0x18000
	v_lshl_add_u64 v[10:11], s[20:21], 0, v[152:153]
	s_and_b32 s68, s5, 0x60
	v_lshl_add_u64 v[8:9], v[8:9], 0, s[86:87]
	s_mov_b32 m0, s69
	s_add_i32 s78, s31, 0x1a000
	v_lshl_add_u64 v[12:13], s[18:19], 0, v[150:151]
	s_lshl_b32 s4, s6, 6
	s_lshl_b32 s8, s6, 13
	s_lshl_b32 s5, s68, 7
	s_waitcnt vmcnt(4)
	s_barrier
	global_load_lds_dwordx4 v[8:9], off
	v_lshl_add_u64 v[8:9], v[10:11], 0, s[86:87]
	s_mov_b32 m0, s78
	s_add_i32 s79, s31, 0x8000
	s_add_i32 s83, s31, 0xa000
	v_lshl_add_u64 v[14:15], s[18:19], 0, v[152:153]
	global_load_lds_dwordx4 v[8:9], off
	v_lshl_add_u64 v[8:9], v[12:13], 0, s[86:87]
	s_mov_b32 m0, s79
	s_add_u32 s6, s20, 0x40080
	global_load_lds_dwordx4 v[8:9], off
	v_lshl_add_u64 v[8:9], v[14:15], 0, s[86:87]
	s_mov_b32 m0, s83
	s_addc_u32 s7, s21, 0
	s_add_i32 s90, s31, 0x1c000
	global_load_lds_dwordx4 v[8:9], off
	v_lshl_add_u64 v[8:9], s[6:7], 0, v[150:151]
	s_mov_b32 m0, s90
	s_add_i32 s93, s31, 0x1e000
	global_load_lds_dwordx4 v[8:9], off
	v_lshl_add_u64 v[8:9], s[6:7], 0, v[152:153]
	s_mov_b32 m0, s93
	v_and_b32_e32 v154, 48, v1
	global_load_lds_dwordx4 v[8:9], off
	v_and_b32_e32 v8, 15, v1
	v_lshl_or_b32 v9, v8, 6, v154
	v_lshl_or_b32 v156, v8, 12, v154
	v_lshlrev_b32_e32 v8, 14, v2
	v_and_b32_e32 v8, 0xffff8000, v8
	v_lshl_add_u32 v3, v3, 11, v8
	v_and_b32_e32 v2, 1, v2
	v_lshl_or_b32 v2, v2, 6, v3
	v_lshl_add_u32 v158, v4, 1, v2
	v_lshlrev_b32_e32 v2, 14, v5
	v_lshlrev_b32_e32 v1, 2, v1
	v_and_b32_e32 v2, 0xffff8000, v2
	v_and_b32_e32 v10, 32, v1
	s_waitcnt vmcnt(6)
	v_lshl_add_u32 v2, v6, 11, v2
	v_and_b32_e32 v3, 1, v5
	v_bitop3_b32 v1, v9, s8, v10 bitop3:0xde
	v_bitop3_b32 v162, s5, v9, v10 bitop3:0xf6
	v_add_u32_e32 v216, 0x10000, v162
	v_add_u32_e32 v217, 0x14000, v162
	v_add_u32_e32 v218, 0x18000, v162
	v_add_u32_e32 v219, 0x1c000, v162
	s_ashr_i32 s5, s4, 31
	v_lshl_or_b32 v2, v3, 6, v2
	v_readlane_b32 s8, v254, 24
	v_mov_b32_e32 v155, v0
	s_lshl_b64 s[6:7], s[4:5], 10
	v_mov_b32_e32 v157, v0
	v_writelane_b32 v255, s60, 1
	s_lshl_b32 s60, s60, 4
	v_mov_b32_e32 v159, v0
	v_lshl_add_u32 v160, v7, 1, v2
	v_mov_b32_e32 v161, v0
	s_mov_b32 s30, 0
	s_mov_b32 s16, s8
	s_barrier
	s_branch .LBB0_2422

; #define G_STAGE(bufoff, gbase, v0, v1) do { \
;     __builtin_amdgcn_global_load_lds((const unsigned*)((const char*)(gbase) + (v0)), (LAS unsigned*)(lds + (bufoff) + ldsw), 16, 0, 0); \
;     __builtin_amdgcn_global_load_lds((const unsigned*)((const char*)(gbase) + (v1)), (LAS unsigned*)(lds + (bufoff) + ldsw + 8192), 16, 0, 0); } while (0)
; #define G_LDA(dst, b, h) do { _Pragma("unroll") for (int m = 0; m < 4; ++m) _Pragma("unroll") for (int k = 0; k < 2; ++k) dst[m][k] = *(const LAS h8*)(lds + G_SA(b, h) + aoff + m * 2048 + k * 1024); } while (0)
; #define G_LDB(dst, b, h) do { _Pragma("unroll") for (int n = 0; n < 2; ++n) _Pragma("unroll") for (int k = 0; k < 2; ++k) dst[n][k] = *(const LAS h8*)(lds + G_SB(b, h) + boff + n * 2048 + k * 1024); } while (0)
; #define G_MMA(ai, bj, At, Bt) do { __builtin_amdgcn_s_setprio(1); _Pragma("unroll") for (int m = 0; m < 4; ++m) _Pragma("unroll") for (int n = 0; n < 2; ++n) _Pragma("unroll") for (int k = 0; k < 2; ++k) \
;     acc[ai][bj][m][n] = __builtin_amdgcn_mfma_f32_16x16x32_f16(Bt[n][k], At[m][k], acc[ai][bj][m][n], 0, 0, 0); __builtin_amdgcn_s_setprio(0); } while (0)
; #define G_WAIT_V(n) asm volatile("s_waitcnt vmcnt(" #n ")" ::: "memory")
; #define G_WAIT_L(n) asm volatile("s_waitcnt lgkmcnt(" #n ")" ::: "memory")
; #define G_BAR __builtin_amdgcn_s_barrier()
; #define G_SCHED __builtin_amdgcn_sched_barrier(0)
; template <bool PERM, class Sched, class Epi>
; DI void gemm256(LAS unsigned char* lds, const Sched& S, const Epi& E, int wv_) {
;     ...
;       const bool last = (t == nt - 2);
;       const char* a1 = cA + (size_t)(t + 1) * kstep;
;       const char* a2 = last ? nA : cA + (size_t)(t + 2) * kstep;
;       const char* b2 = last ? nB : cB + (size_t)(t + 2) * kstep;
;       const char* a3 = a2 + kstep;
;       const char* b3 = b2 + kstep;
;       G_LDB(B0, 0, 0); G_SCHED; G_LDA(At, 0, 0); G_STAGE(G_SA(1, 1), a1 + chA, cvA0, cvA1);
;       G_WAIT_L(8); G_BAR; G_WAIT_L(0); G_MMA(0, 0, At, B0); G_BAR; G_SCHED;
;       G_LDB(B1, 0, 1); G_STAGE(G_SB(0, 0), b2, cvB0, cvB1);
;       G_BAR; G_WAIT_L(0); G_MMA(0, 1, At, B1); G_BAR;
;       G_LDA(At, 0, 1); G_STAGE(G_SA(0, 0), a2, cvA0, cvA1);
;       G_BAR; G_WAIT_L(0); G_MMA(1, 0, At, B0); G_BAR; G_SCHED;
;       G_STAGE(G_SB(0, 1), b2 + chB, cvB0, cvB1);
;       G_WAIT_V(6); G_BAR; G_MMA(1, 1, At, B1); G_BAR;
.LBB0_2433:
	s_waitcnt vmcnt(0)
	s_add_i32 s74, s20, 2
	ds_read_b128 v[130:133], v216
	ds_read_b128 v[134:137], v216 offset:1024
	ds_read_b128 v[138:141], v216 offset:2048
	ds_read_b128 v[142:145], v216 offset:3072
	s_add_u32 s21, s18, 0xfffc0080
	s_addc_u32 s22, s19, -1
	s_cmp_eq_u32 vcc_lo, s20
	s_cselect_b32 s20, s85, s75
	s_cselect_b32 s23, s9, s22
	s_cselect_b32 s22, s27, s21
	s_cselect_b32 s21, s56, s46
	v_lshl_add_u64 v[192:193], s[18:19], 0, v[158:159]
	s_add_i32 m0, s31, 0xc000
	ds_read_b128 v[146:149], v1
	ds_read_b128 v[164:167], v1 offset:1024
	ds_read_b128 v[168:171], v1 offset:2048
	ds_read_b128 v[172:175], v1 offset:3072
	ds_read_b128 v[176:179], v1 offset:4096
	ds_read_b128 v[180:183], v1 offset:5120
	ds_read_b128 v[184:187], v1 offset:6144
	ds_read_b128 v[188:191], v1 offset:7168
	global_load_lds_dwordx4 v[192:193], off
	v_lshl_add_u64 v[192:193], s[18:19], 0, v[160:161]
	s_add_i32 m0, s31, 0xe000
	s_nop 0
	global_load_lds_dwordx4 v[192:193], off
	s_waitcnt lgkmcnt(8)
	s_barrier
	s_waitcnt lgkmcnt(0)
	s_waitcnt lgkmcnt(0)
	v_mfma_f32_16x16x32_f16 v[126:129], v[130:133], v[146:149], v[126:129]
	v_mfma_f32_16x16x32_f16 v[122:125], v[138:141], v[146:149], v[122:125]
	v_mfma_f32_16x16x32_f16 v[110:113], v[130:133], v[168:171], v[110:113]
	v_mfma_f32_16x16x32_f16 v[106:109], v[138:141], v[168:171], v[106:109]
	v_mfma_f32_16x16x32_f16 v[94:97], v[130:133], v[176:179], v[94:97]
	v_mfma_f32_16x16x32_f16 v[90:93], v[138:141], v[176:179], v[90:93]
	v_mfma_f32_16x16x32_f16 v[78:81], v[130:133], v[184:187], v[78:81]
	v_mfma_f32_16x16x32_f16 v[74:77], v[138:141], v[184:187], v[74:77]
	v_mfma_f32_16x16x32_f16 v[126:129], v[134:137], v[164:167], v[126:129]
	v_mfma_f32_16x16x32_f16 v[122:125], v[142:145], v[164:167], v[122:125]
	v_mfma_f32_16x16x32_f16 v[110:113], v[134:137], v[172:175], v[110:113]
	v_mfma_f32_16x16x32_f16 v[106:109], v[142:145], v[172:175], v[106:109]
	v_mfma_f32_16x16x32_f16 v[94:97], v[134:137], v[180:183], v[94:97]
	v_mfma_f32_16x16x32_f16 v[90:93], v[142:145], v[180:183], v[90:93]
	v_mfma_f32_16x16x32_f16 v[78:81], v[134:137], v[188:191], v[78:81]
	v_mfma_f32_16x16x32_f16 v[74:77], v[142:145], v[188:191], v[74:77]
	s_barrier
	s_mov_b32 m0, s34
	ds_read_b128 v[192:195], v217
	ds_read_b128 v[196:199], v217 offset:1024
	v_lshl_add_u64 v[208:209], s[20:21], 0, v[150:151]
	ds_read_b128 v[200:203], v217 offset:2048
	ds_read_b128 v[204:207], v217 offset:3072
	global_load_lds_dwordx4 v[208:209], off
	v_lshl_add_u64 v[210:211], s[20:21], 0, v[152:153]
	s_mov_b32 m0, s35
	s_nop 0
	global_load_lds_dwordx4 v[210:211], off
	s_barrier
	s_waitcnt lgkmcnt(0)
	s_waitcnt lgkmcnt(0)
	v_mfma_f32_16x16x32_f16 v[118:121], v[192:195], v[146:149], v[118:121]
	v_mfma_f32_16x16x32_f16 v[114:117], v[200:203], v[146:149], v[114:117]
	v_mfma_f32_16x16x32_f16 v[102:105], v[192:195], v[168:171], v[102:105]
	v_mfma_f32_16x16x32_f16 v[98:101], v[200:203], v[168:171], v[98:101]
	v_mfma_f32_16x16x32_f16 v[86:89], v[192:195], v[176:179], v[86:89]
	v_mfma_f32_16x16x32_f16 v[82:85], v[200:203], v[176:179], v[82:85]
	v_mfma_f32_16x16x32_f16 v[70:73], v[192:195], v[184:187], v[70:73]
	v_mfma_f32_16x16x32_f16 v[66:69], v[200:203], v[184:187], v[66:69]
	v_mfma_f32_16x16x32_f16 v[118:121], v[196:199], v[164:167], v[118:121]
	v_mfma_f32_16x16x32_f16 v[114:117], v[204:207], v[164:167], v[114:117]
	v_mfma_f32_16x16x32_f16 v[102:105], v[196:199], v[172:175], v[102:105]
	v_mfma_f32_16x16x32_f16 v[98:101], v[204:207], v[172:175], v[98:101]
	v_mfma_f32_16x16x32_f16 v[86:89], v[196:199], v[180:183], v[86:89]
	v_mfma_f32_16x16x32_f16 v[82:85], v[204:207], v[180:183], v[82:85]
	v_mfma_f32_16x16x32_f16 v[70:73], v[196:199], v[188:191], v[70:73]
	v_mfma_f32_16x16x32_f16 v[66:69], v[204:207], v[188:191], v[66:69]
	s_mov_b32 m0, s31
	v_lshl_add_u64 v[212:213], s[22:23], 0, v[150:151]
	s_barrier
	ds_read_b128 v[146:149], v1 offset:16384
	ds_read_b128 v[164:167], v1 offset:17408
	ds_read_b128 v[168:171], v1 offset:18432
	ds_read_b128 v[172:175], v1 offset:19456
	ds_read_b128 v[176:179], v1 offset:20480
	ds_read_b128 v[180:183], v1 offset:21504
	ds_read_b128 v[184:187], v1 offset:22528
	ds_read_b128 v[188:191], v1 offset:23552
	global_load_lds_dwordx4 v[212:213], off
	v_lshl_add_u64 v[214:215], s[22:23], 0, v[152:153]
	s_mov_b32 m0, s36
	s_nop 0
	global_load_lds_dwordx4 v[214:215], off
	s_barrier
	s_waitcnt lgkmcnt(0)
	s_waitcnt lgkmcnt(0)
	v_mfma_f32_16x16x32_f16 v[62:65], v[130:133], v[146:149], v[62:65]
	v_mfma_f32_16x16x32_f16 v[58:61], v[138:141], v[146:149], v[58:61]
	v_mfma_f32_16x16x32_f16 v[46:49], v[130:133], v[168:171], v[46:49]
	v_mfma_f32_16x16x32_f16 v[42:45], v[138:141], v[168:171], v[42:45]
	v_mfma_f32_16x16x32_f16 v[30:33], v[130:133], v[176:179], v[30:33]
	v_mfma_f32_16x16x32_f16 v[26:29], v[138:141], v[176:179], v[26:29]
	v_mfma_f32_16x16x32_f16 v[14:17], v[130:133], v[184:187], v[14:17]
	v_mfma_f32_16x16x32_f16 v[10:13], v[138:141], v[184:187], v[10:13]
	v_mfma_f32_16x16x32_f16 v[62:65], v[134:137], v[164:167], v[62:65]
	v_mfma_f32_16x16x32_f16 v[58:61], v[142:145], v[164:167], v[58:61]
	v_mfma_f32_16x16x32_f16 v[46:49], v[134:137], v[172:175], v[46:49]
	v_mfma_f32_16x16x32_f16 v[42:45], v[142:145], v[172:175], v[42:45]
	v_mfma_f32_16x16x32_f16 v[30:33], v[134:137], v[180:183], v[30:33]
	v_mfma_f32_16x16x32_f16 v[26:29], v[142:145], v[180:183], v[26:29]
	v_mfma_f32_16x16x32_f16 v[14:17], v[134:137], v[188:191], v[14:17]
	v_mfma_f32_16x16x32_f16 v[10:13], v[142:145], v[188:191], v[10:13]
	s_barrier
; #define G_STAGE(bufoff, gbase, v0, v1) do { \
;     __builtin_amdgcn_global_load_lds((const unsigned*)((const char*)(gbase) + (v0)), (LAS unsigned*)(lds + (bufoff) + ldsw), 16, 0, 0); \
;     __builtin_amdgcn_global_load_lds((const unsigned*)((const char*)(gbase) + (v1)), (LAS unsigned*)(lds + (bufoff) + ldsw + 8192), 16, 0, 0); } while (0)
; #define G_LDA(dst, b, h) do { _Pragma("unroll") for (int m = 0; m < 4; ++m) _Pragma("unroll") for (int k = 0; k < 2; ++k) dst[m][k] = *(const LAS h8*)(lds + G_SA(b, h) + aoff + m * 2048 + k * 1024); } while (0)
; #define G_LDB(dst, b, h) do { _Pragma("unroll") for (int n = 0; n < 2; ++n) _Pragma("unroll") for (int k = 0; k < 2; ++k) dst[n][k] = *(const LAS h8*)(lds + G_SB(b, h) + boff + n * 2048 + k * 1024); } while (0)
; #define G_MMA(ai, bj, At, Bt) do { __builtin_amdgcn_s_setprio(1); _Pragma("unroll") for (int m = 0; m < 4; ++m) _Pragma("unroll") for (int n = 0; n < 2; ++n) _Pragma("unroll") for (int k = 0; k < 2; ++k) \
;     acc[ai][bj][m][n] = __builtin_amdgcn_mfma_f32_16x16x32_f16(Bt[n][k], At[m][k], acc[ai][bj][m][n], 0, 0, 0); __builtin_amdgcn_s_setprio(0); } while (0)
; #define G_WAIT_V(n) asm volatile("s_waitcnt vmcnt(" #n ")" ::: "memory")
; #define G_WAIT_L(n) asm volatile("s_waitcnt lgkmcnt(" #n ")" ::: "memory")
; #define G_BAR __builtin_amdgcn_s_barrier()
; #define G_SCHED __builtin_amdgcn_sched_barrier(0)
; template <bool PERM, class Sched, class Epi>
; DI void gemm256(LAS unsigned char* lds, const Sched& S, const Epi& E, int wv_) {
;     ...
;       G_WAIT_V(6); G_BAR; G_MMA(1, 1, At, B1); G_BAR;
;       G_LDB(B0, 1, 0); G_SCHED; G_LDA(At, 1, 0); G_STAGE(G_SA(0, 1), a2 + chA, cvA0, cvA1);
;       G_WAIT_L(8); G_BAR; G_WAIT_L(0); G_MMA(0, 0, At, B0); G_BAR; G_SCHED;
;       G_LDB(B1, 1, 1); G_STAGE(G_SB(1, 0), b3, cvB0, cvB1);
;       G_BAR; G_WAIT_L(0); G_MMA(0, 1, At, B1); G_BAR;
	s_add_u32 s40, s20, 0x40000
	s_addc_u32 s41, s21, 0
	s_mov_b32 m0, s37
	v_lshl_add_u64 v[130:131], s[40:41], 0, v[150:151]
	global_load_lds_dwordx4 v[130:131], off
	v_lshl_add_u64 v[130:131], s[40:41], 0, v[152:153]
	s_mov_b32 m0, s58
	s_nop 0
	global_load_lds_dwordx4 v[130:131], off
	s_waitcnt vmcnt(6)
	s_barrier
	v_mfma_f32_16x16x32_f16 v[54:57], v[192:195], v[146:149], v[54:57]
	v_mfma_f32_16x16x32_f16 v[50:53], v[200:203], v[146:149], v[50:53]
	v_mfma_f32_16x16x32_f16 v[38:41], v[192:195], v[168:171], v[38:41]
	v_mfma_f32_16x16x32_f16 v[34:37], v[200:203], v[168:171], v[34:37]
	v_mfma_f32_16x16x32_f16 v[22:25], v[192:195], v[176:179], v[22:25]
	v_mfma_f32_16x16x32_f16 v[18:21], v[200:203], v[176:179], v[18:21]
	v_mfma_f32_16x16x32_f16 v[6:9], v[192:195], v[184:187], v[6:9]
	v_mfma_f32_16x16x32_f16 v[2:5], v[200:203], v[184:187], v[2:5]
	v_mfma_f32_16x16x32_f16 v[54:57], v[196:199], v[164:167], v[54:57]
	v_mfma_f32_16x16x32_f16 v[50:53], v[204:207], v[164:167], v[50:53]
	v_mfma_f32_16x16x32_f16 v[38:41], v[196:199], v[172:175], v[38:41]
	v_mfma_f32_16x16x32_f16 v[34:37], v[204:207], v[172:175], v[34:37]
	v_mfma_f32_16x16x32_f16 v[22:25], v[196:199], v[180:183], v[22:25]
	v_mfma_f32_16x16x32_f16 v[18:21], v[204:207], v[180:183], v[18:21]
	v_mfma_f32_16x16x32_f16 v[6:9], v[196:199], v[188:191], v[6:9]
	v_mfma_f32_16x16x32_f16 v[2:5], v[204:207], v[188:191], v[2:5]
	s_barrier
	ds_read_b128 v[130:133], v218
	ds_read_b128 v[134:137], v218 offset:1024
	ds_read_b128 v[138:141], v218 offset:2048
	ds_read_b128 v[142:145], v218 offset:3072
	s_add_u32 s22, s22, 0x40000
	s_addc_u32 s23, s23, 0
	s_mov_b32 m0, s59
	v_lshl_add_u64 v[192:193], s[22:23], 0, v[150:151]
	ds_read_b128 v[146:149], v1 offset:32768
	ds_read_b128 v[164:167], v1 offset:33792
	ds_read_b128 v[168:171], v1 offset:34816
	ds_read_b128 v[172:175], v1 offset:35840
	ds_read_b128 v[176:179], v1 offset:36864
	ds_read_b128 v[180:183], v1 offset:37888
	ds_read_b128 v[184:187], v1 offset:38912
	ds_read_b128 v[188:191], v1 offset:39936
	global_load_lds_dwordx4 v[192:193], off
	v_lshl_add_u64 v[192:193], s[22:23], 0, v[152:153]
	s_mov_b32 m0, s61
	s_nop 0
	global_load_lds_dwordx4 v[192:193], off
	s_waitcnt lgkmcnt(8)
	s_barrier
	s_waitcnt lgkmcnt(0)
	s_waitcnt lgkmcnt(0)
	v_mfma_f32_16x16x32_f16 v[126:129], v[130:133], v[146:149], v[126:129]
	v_mfma_f32_16x16x32_f16 v[122:125], v[138:141], v[146:149], v[122:125]
	v_mfma_f32_16x16x32_f16 v[110:113], v[130:133], v[168:171], v[110:113]
	v_mfma_f32_16x16x32_f16 v[106:109], v[138:141], v[168:171], v[106:109]
	v_mfma_f32_16x16x32_f16 v[94:97], v[130:133], v[176:179], v[94:97]
	v_mfma_f32_16x16x32_f16 v[90:93], v[138:141], v[176:179], v[90:93]
	v_mfma_f32_16x16x32_f16 v[78:81], v[130:133], v[184:187], v[78:81]
	v_mfma_f32_16x16x32_f16 v[74:77], v[138:141], v[184:187], v[74:77]
	v_mfma_f32_16x16x32_f16 v[126:129], v[134:137], v[164:167], v[126:129]
	v_mfma_f32_16x16x32_f16 v[122:125], v[142:145], v[164:167], v[122:125]
	v_mfma_f32_16x16x32_f16 v[110:113], v[134:137], v[172:175], v[110:113]
	v_mfma_f32_16x16x32_f16 v[106:109], v[142:145], v[172:175], v[106:109]
	v_mfma_f32_16x16x32_f16 v[94:97], v[134:137], v[180:183], v[94:97]
	v_mfma_f32_16x16x32_f16 v[90:93], v[142:145], v[180:183], v[90:93]
	v_mfma_f32_16x16x32_f16 v[78:81], v[134:137], v[188:191], v[78:81]
	v_mfma_f32_16x16x32_f16 v[74:77], v[142:145], v[188:191], v[74:77]
	s_barrier
	s_mov_b32 m0, s69
	ds_read_b128 v[192:195], v219
	ds_read_b128 v[196:199], v219 offset:1024
	v_lshl_add_u64 v[208:209], v[208:209], 0, s[86:87]
	ds_read_b128 v[200:203], v219 offset:2048
	ds_read_b128 v[204:207], v219 offset:3072
	global_load_lds_dwordx4 v[208:209], off
	v_lshl_add_u64 v[208:209], v[210:211], 0, s[86:87]
	s_mov_b32 m0, s78
	s_nop 0
	global_load_lds_dwordx4 v[208:209], off
	s_barrier
; #define G_STAGE(bufoff, gbase, v0, v1) do { \
;     __builtin_amdgcn_global_load_lds((const unsigned*)((const char*)(gbase) + (v0)), (LAS unsigned*)(lds + (bufoff) + ldsw), 16, 0, 0); \
;     __builtin_amdgcn_global_load_lds((const unsigned*)((const char*)(gbase) + (v1)), (LAS unsigned*)(lds + (bufoff) + ldsw + 8192), 16, 0, 0); } while (0)
; #define G_LDA(dst, b, h) do { _Pragma("unroll") for (int m = 0; m < 4; ++m) _Pragma("unroll") for (int k = 0; k < 2; ++k) dst[m][k] = *(const LAS h8*)(lds + G_SA(b, h) + aoff + m * 2048 + k * 1024); } while (0)
; #define G_MMA(ai, bj, At, Bt) do { __builtin_amdgcn_s_setprio(1); _Pragma("unroll") for (int m = 0; m < 4; ++m) _Pragma("unroll") for (int n = 0; n < 2; ++n) _Pragma("unroll") for (int k = 0; k < 2; ++k) \
;     acc[ai][bj][m][n] = __builtin_amdgcn_mfma_f32_16x16x32_f16(Bt[n][k], At[m][k], acc[ai][bj][m][n], 0, 0, 0); __builtin_amdgcn_s_setprio(0); } while (0)
; #define G_WAIT_V(n) asm volatile("s_waitcnt vmcnt(" #n ")" ::: "memory")
; #define G_WAIT_L(n) asm volatile("s_waitcnt lgkmcnt(" #n ")" ::: "memory")
; #define G_BAR __builtin_amdgcn_s_barrier()
; #define G_SCHED __builtin_amdgcn_sched_barrier(0)
; template <bool PERM, class Sched, class Epi>
; DI void gemm256(LAS unsigned char* lds, const Sched& S, const Epi& E, int wv_) {
;     ...
;     for (int t = 0; t < nt; t += 2) {
;     ...
;       G_BAR; G_WAIT_L(0); G_MMA(0, 1, At, B1); G_BAR;
;       G_LDA(At, 1, 1); G_STAGE(G_SA(1, 0), a3, cvA0, cvA1);
;       G_BAR; G_WAIT_L(0); G_MMA(1, 0, At, B0); G_BAR; G_SCHED;
;       G_STAGE(G_SB(1, 1), b3 + chB, cvB0, cvB1);
;       G_WAIT_V(6); G_BAR; G_MMA(1, 1, At, B1); G_BAR;
	s_waitcnt lgkmcnt(0)
	s_waitcnt lgkmcnt(0)
	v_mfma_f32_16x16x32_f16 v[118:121], v[192:195], v[146:149], v[118:121]
	v_mfma_f32_16x16x32_f16 v[114:117], v[200:203], v[146:149], v[114:117]
	v_mfma_f32_16x16x32_f16 v[102:105], v[192:195], v[168:171], v[102:105]
	v_mfma_f32_16x16x32_f16 v[98:101], v[200:203], v[168:171], v[98:101]
	v_mfma_f32_16x16x32_f16 v[86:89], v[192:195], v[176:179], v[86:89]
	v_mfma_f32_16x16x32_f16 v[82:85], v[200:203], v[176:179], v[82:85]
	v_mfma_f32_16x16x32_f16 v[70:73], v[192:195], v[184:187], v[70:73]
	v_mfma_f32_16x16x32_f16 v[66:69], v[200:203], v[184:187], v[66:69]
	v_mfma_f32_16x16x32_f16 v[118:121], v[196:199], v[164:167], v[118:121]
	v_mfma_f32_16x16x32_f16 v[114:117], v[204:207], v[164:167], v[114:117]
	v_mfma_f32_16x16x32_f16 v[102:105], v[196:199], v[172:175], v[102:105]
	v_mfma_f32_16x16x32_f16 v[98:101], v[204:207], v[172:175], v[98:101]
	v_mfma_f32_16x16x32_f16 v[86:89], v[196:199], v[180:183], v[86:89]
	v_mfma_f32_16x16x32_f16 v[82:85], v[204:207], v[180:183], v[82:85]
	v_mfma_f32_16x16x32_f16 v[70:73], v[196:199], v[188:191], v[70:73]
	v_mfma_f32_16x16x32_f16 v[66:69], v[204:207], v[188:191], v[66:69]
	s_mov_b32 m0, s79
	v_lshl_add_u64 v[208:209], v[212:213], 0, s[86:87]
	s_barrier
	ds_read_b128 v[146:149], v1 offset:49152
	ds_read_b128 v[164:167], v1 offset:50176
	ds_read_b128 v[168:171], v1 offset:51200
	ds_read_b128 v[172:175], v1 offset:52224
	ds_read_b128 v[176:179], v1 offset:53248
	ds_read_b128 v[180:183], v1 offset:54272
	ds_read_b128 v[184:187], v1 offset:55296
	ds_read_b128 v[188:191], v1 offset:56320
	global_load_lds_dwordx4 v[208:209], off
	v_lshl_add_u64 v[208:209], v[214:215], 0, s[86:87]
	s_mov_b32 m0, s83
	s_nop 0
	global_load_lds_dwordx4 v[208:209], off
	s_barrier
	s_waitcnt lgkmcnt(0)
	s_waitcnt lgkmcnt(0)
	v_mfma_f32_16x16x32_f16 v[62:65], v[130:133], v[146:149], v[62:65]
	v_mfma_f32_16x16x32_f16 v[58:61], v[138:141], v[146:149], v[58:61]
	v_mfma_f32_16x16x32_f16 v[46:49], v[130:133], v[168:171], v[46:49]
	v_mfma_f32_16x16x32_f16 v[42:45], v[138:141], v[168:171], v[42:45]
	v_mfma_f32_16x16x32_f16 v[30:33], v[130:133], v[176:179], v[30:33]
	v_mfma_f32_16x16x32_f16 v[26:29], v[138:141], v[176:179], v[26:29]
	v_mfma_f32_16x16x32_f16 v[14:17], v[130:133], v[184:187], v[14:17]
	v_mfma_f32_16x16x32_f16 v[10:13], v[138:141], v[184:187], v[10:13]
	v_mfma_f32_16x16x32_f16 v[62:65], v[134:137], v[164:167], v[62:65]
	v_mfma_f32_16x16x32_f16 v[58:61], v[142:145], v[164:167], v[58:61]
	v_mfma_f32_16x16x32_f16 v[46:49], v[134:137], v[172:175], v[46:49]
	v_mfma_f32_16x16x32_f16 v[42:45], v[142:145], v[172:175], v[42:45]
	v_mfma_f32_16x16x32_f16 v[30:33], v[134:137], v[180:183], v[30:33]
	v_mfma_f32_16x16x32_f16 v[26:29], v[142:145], v[180:183], v[26:29]
	v_mfma_f32_16x16x32_f16 v[14:17], v[134:137], v[188:191], v[14:17]
	v_mfma_f32_16x16x32_f16 v[10:13], v[142:145], v[188:191], v[10:13]
	s_barrier
	s_add_u32 s20, s20, 0x40080
	s_addc_u32 s21, s21, 0
	s_mov_b32 m0, s90
	v_lshl_add_u64 v[130:131], s[20:21], 0, v[150:151]
	global_load_lds_dwordx4 v[130:131], off
	v_lshl_add_u64 v[130:131], s[20:21], 0, v[152:153]
	s_mov_b32 m0, s93
	s_nop 0
	global_load_lds_dwordx4 v[130:131], off
	s_waitcnt vmcnt(6)
	s_barrier
	v_mfma_f32_16x16x32_f16 v[54:57], v[192:195], v[146:149], v[54:57]
	v_mfma_f32_16x16x32_f16 v[50:53], v[200:203], v[146:149], v[50:53]
	v_mfma_f32_16x16x32_f16 v[38:41], v[192:195], v[168:171], v[38:41]
	v_mfma_f32_16x16x32_f16 v[34:37], v[200:203], v[168:171], v[34:37]
	v_mfma_f32_16x16x32_f16 v[22:25], v[192:195], v[176:179], v[22:25]
	v_mfma_f32_16x16x32_f16 v[18:21], v[200:203], v[176:179], v[18:21]
	v_mfma_f32_16x16x32_f16 v[6:9], v[192:195], v[184:187], v[6:9]
	v_mfma_f32_16x16x32_f16 v[2:5], v[200:203], v[184:187], v[2:5]
	v_mfma_f32_16x16x32_f16 v[54:57], v[196:199], v[164:167], v[54:57]
	v_mfma_f32_16x16x32_f16 v[50:53], v[204:207], v[164:167], v[50:53]
	v_mfma_f32_16x16x32_f16 v[38:41], v[196:199], v[172:175], v[38:41]
	v_mfma_f32_16x16x32_f16 v[34:37], v[204:207], v[172:175], v[34:37]
	v_mfma_f32_16x16x32_f16 v[22:25], v[196:199], v[180:183], v[22:25]
	v_mfma_f32_16x16x32_f16 v[18:21], v[204:207], v[180:183], v[18:21]
	v_mfma_f32_16x16x32_f16 v[6:9], v[196:199], v[188:191], v[6:9]
	v_mfma_f32_16x16x32_f16 v[2:5], v[204:207], v[188:191], v[2:5]
	s_add_u32 s18, s18, 0x100
	s_addc_u32 s19, s19, 0
	s_add_u32 s75, s75, 0x100
	s_addc_u32 s46, s46, 0
	s_cmp_ge_i32 s74, s25
	s_mov_b32 s20, s74
	s_barrier
	s_cbranch_scc0 .LBB0_2433
	s_mov_b32 s56, 0x8fff
	s_branch .LBB0_2436

;   static DI int bmap(bool perm, int R) { return perm ? ((R & ~31) + perm32(R & 31)) : R; }
; #define G_STAGE(bufoff, gbase, v0, v1) do { \
;     __builtin_amdgcn_global_load_lds((const unsigned*)((const char*)(gbase) + (v0)), (LAS unsigned*)(lds + (bufoff) + ldsw), 16, 0, 0); \
;     __builtin_amdgcn_global_load_lds((const unsigned*)((const char*)(gbase) + (v1)), (LAS unsigned*)(lds + (bufoff) + ldsw + 8192), 16, 0, 0); } while (0)
; #define G_WAIT_V(n) asm volatile("s_waitcnt vmcnt(" #n ")" ::: "memory")
; #define G_BAR __builtin_amdgcn_s_barrier()
;   static DI int bmap(bool, int R) { return ((R >> 4) & 1) * 1024 + (R >> 5) * 16 + (R & 15); }
; template <bool PERM, class Sched, class Epi>
; DI void gemm256(LAS unsigned char* lds, const Sched& S, const Epi& E, int wv_) {
;   const int tid = tid_opaque(wv_), wid = __builtin_amdgcn_readfirstlane(tid >> 6), lane = tid & 63, wr = wid >> 2, wc = wid & 3, fr = lane & 15, fq = lane >> 4;
;   unsigned cvA0, cvA1, cvB0, cvB1;
;   { int R, C;
;     stage_rc(tid * 16, R, C); cvA0 = (unsigned)R * S.lda2 + C * 2; cvB0 = (unsigned)Sched::bmap(PERM, R) * S.ldb2 + C * 2;
;     stage_rc(tid * 16 + 8192, R, C); cvA1 = (unsigned)R * S.lda2 + C * 2; cvB1 = (unsigned)Sched::bmap(PERM, R) * S.ldb2 + C * 2; }
;   const size_t chA = (size_t)HALF * S.lda2, chB = (size_t)Sched::BHALF * S.ldb2;
;   const size_t kstep = (size_t)(BK * 2);
;   const unsigned ldsw = (unsigned)wid * 1024u;
;   const int aoff = lds_byte(wr * 64 + fr, fq * 8), boff = lds_byte(wc * 32 + fr, fq * 8);
;     ...
;   GUnit cur, nxt;
;   int ui = 0;
;   if (!S.next(0, cur)) return;
;   f4 acc[2][2][4][2];
; #pragma unroll
;   for (int a = 0; a < 2; ++a)
; #pragma unroll
;     for (int b = 0; b < 2; ++b)
; #pragma unroll
;       for (int m = 0; m < 4; ++m)
; #pragma unroll
;         for (int n = 0; n < 2; ++n) acc[a][b][m][n] = f4{0.f, 0.f, 0.f, 0.f};
;   h8 At[4][2], B0[2][2], B1[2][2];
;   const char* cA = cur.A;
;   const char* cB = cur.B;
;   G_STAGE(G_SB(0, 0), cB, cvB0, cvB1); G_STAGE(G_SA(0, 0), cA, cvA0, cvA1); G_STAGE(G_SB(0, 1), cB + chB, cvB0, cvB1); G_STAGE(G_SA(0, 1), cA + chA, cvA0, cvA1);
;   if (wr == 1) G_BAR;
;   G_WAIT_V(4); G_BAR;
;   G_STAGE(G_SB(1, 0), cB + kstep, cvB0, cvB1); G_STAGE(G_SA(1, 0), cA + kstep, cvA0, cvA1); G_STAGE(G_SB(1, 1), cB + chB + kstep, cvB0, cvB1);
;   G_WAIT_V(6); G_BAR;
.LBB0_2571:
	v_mov_b32_e32 v133, v0
	v_lshl_add_u64 v[8:9], s[14:15], 0, v[132:133]
	v_mov_b32_e32 v137, v0
	s_lshl_b32 s2, s2, 5
	s_add_i32 s35, s24, 0x18000
	v_lshl_add_u64 v[10:11], s[14:15], 0, v[136:137]
	v_mov_b32_e32 v131, v0
	v_and_b32_e32 v16, 15, v1
	v_and_b32_e32 v17, 48, v1
	v_lshlrev_b32_e32 v1, 2, v1
	s_and_b32 s4, s2, 0x60
	v_lshl_add_u64 v[8:9], v[8:9], 0, s[86:87]
	s_mov_b32 m0, s35
	s_add_i32 s36, s24, 0x1a000
	v_lshl_add_u64 v[12:13], s[12:13], 0, v[130:131]
	v_mov_b32_e32 v135, v0
	s_lshl_b32 s34, s3, 6
	s_lshl_b32 s3, s3, 13
	v_lshl_or_b32 v18, v16, 6, v17
	v_and_b32_e32 v19, 32, v1
	s_lshl_b32 s2, s4, 7
	s_waitcnt vmcnt(4)
	s_barrier
	global_load_lds_dwordx4 v[8:9], off
	v_lshl_add_u64 v[8:9], v[10:11], 0, s[86:87]
	s_mov_b32 m0, s36
	s_add_i32 s37, s24, 0x8000
	s_add_i32 s52, s24, 0xa000
	v_lshl_add_u64 v[14:15], s[12:13], 0, v[134:135]
	v_bitop3_b32 v142, s2, v18, v19 bitop3:0xf6
	v_add_u32_e32 v216, 0x10000, v142
	v_add_u32_e32 v217, 0x14000, v142
	v_add_u32_e32 v218, 0x18000, v142
	v_add_u32_e32 v219, 0x1c000, v142
	global_load_lds_dwordx4 v[8:9], off
	v_lshl_add_u64 v[8:9], v[12:13], 0, s[86:87]
	s_mov_b32 m0, s37
	s_add_u32 s2, s14, 0x40080
	v_bitop3_b32 v1, v18, s3, v19 bitop3:0xde
	global_load_lds_dwordx4 v[8:9], off
	v_lshl_add_u64 v[8:9], v[14:15], 0, s[86:87]
	s_mov_b32 m0, s52
	s_addc_u32 s3, s15, 0
	s_add_i32 s53, s24, 0x1c000
	global_load_lds_dwordx4 v[8:9], off
	v_lshl_add_u64 v[8:9], s[2:3], 0, v[132:133]
	s_mov_b32 m0, s53
	s_add_i32 s56, s24, 0x1e000
	global_load_lds_dwordx4 v[8:9], off
	v_lshl_add_u64 v[8:9], s[2:3], 0, v[136:137]
	s_mov_b32 m0, s56
	v_lshl_or_b32 v143, v16, 13, v17
	global_load_lds_dwordx4 v[8:9], off
	v_lshlrev_b32_e32 v8, 14, v2
	v_and_b32_e32 v8, 0xffff8000, v8
	v_lshl_add_u32 v3, v3, 11, v8
	v_and_b32_e32 v2, 1, v2
	v_lshl_or_b32 v2, v2, 6, v3
	v_lshl_add_u32 v138, v4, 1, v2
	v_lshlrev_b32_e32 v2, 14, v5
	v_and_b32_e32 v2, 0xffff8000, v2
	s_waitcnt vmcnt(6)
	v_lshl_add_u32 v2, v6, 11, v2
	v_and_b32_e32 v3, 1, v5
	v_lshl_or_b32 v2, v3, 6, v2
	v_mov_b32_e32 v139, v0
	v_lshl_add_u32 v140, v7, 1, v2
	v_mov_b32_e32 v141, v0
	s_mov_b32 s58, 0
	s_lshl_b32 s59, s4, 1
	s_mov_b64 s[6:7], s[12:13]
	s_mov_b64 s[8:9], s[14:15]
	s_barrier
	s_branch .LBB0_2573

; #define G_STAGE(bufoff, gbase, v0, v1) do { \
;     __builtin_amdgcn_global_load_lds((const unsigned*)((const char*)(gbase) + (v0)), (LAS unsigned*)(lds + (bufoff) + ldsw), 16, 0, 0); \
;     __builtin_amdgcn_global_load_lds((const unsigned*)((const char*)(gbase) + (v1)), (LAS unsigned*)(lds + (bufoff) + ldsw + 8192), 16, 0, 0); } while (0)
; #define G_LDA(dst, b, h) do { _Pragma("unroll") for (int m = 0; m < 4; ++m) _Pragma("unroll") for (int k = 0; k < 2; ++k) dst[m][k] = *(const LAS h8*)(lds + G_SA(b, h) + aoff + m * 2048 + k * 1024); } while (0)
; #define G_LDB(dst, b, h) do { _Pragma("unroll") for (int n = 0; n < 2; ++n) _Pragma("unroll") for (int k = 0; k < 2; ++k) dst[n][k] = *(const LAS h8*)(lds + G_SB(b, h) + boff + n * 2048 + k * 1024); } while (0)
; #define G_MMA(ai, bj, At, Bt) do { __builtin_amdgcn_s_setprio(1); _Pragma("unroll") for (int m = 0; m < 4; ++m) _Pragma("unroll") for (int n = 0; n < 2; ++n) _Pragma("unroll") for (int k = 0; k < 2; ++k) \
;     acc[ai][bj][m][n] = __builtin_amdgcn_mfma_f32_16x16x32_f16(Bt[n][k], At[m][k], acc[ai][bj][m][n], 0, 0, 0); __builtin_amdgcn_s_setprio(0); } while (0)
; #define G_WAIT_V(n) asm volatile("s_waitcnt vmcnt(" #n ")" ::: "memory")
; #define G_WAIT_L(n) asm volatile("s_waitcnt lgkmcnt(" #n ")" ::: "memory")
; #define G_BAR __builtin_amdgcn_s_barrier()
; #define G_SCHED __builtin_amdgcn_sched_barrier(0)
; template <bool PERM, class Sched, class Epi>
; DI void gemm256(LAS unsigned char* lds, const Sched& S, const Epi& E, int wv_) {
;     ...
;       const bool last = (t == nt - 2);
;       const char* a1 = cA + (size_t)(t + 1) * kstep;
;       const char* a2 = last ? nA : cA + (size_t)(t + 2) * kstep;
;       const char* b2 = last ? nB : cB + (size_t)(t + 2) * kstep;
;       const char* a3 = a2 + kstep;
;       const char* b3 = b2 + kstep;
;       G_LDB(B0, 0, 0); G_SCHED; G_LDA(At, 0, 0); G_STAGE(G_SA(1, 1), a1 + chA, cvA0, cvA1);
;       G_WAIT_L(8); G_BAR; G_WAIT_L(0); G_MMA(0, 0, At, B0); G_BAR; G_SCHED;
;       G_LDB(B1, 0, 1); G_STAGE(G_SB(0, 0), b2, cvB0, cvB1);
;       G_BAR; G_WAIT_L(0); G_MMA(0, 1, At, B1); G_BAR;
;       G_LDA(At, 0, 1); G_STAGE(G_SA(0, 0), a2, cvA0, cvA1);
;       G_BAR; G_WAIT_L(0); G_MMA(1, 0, At, B0); G_BAR; G_SCHED;
;       G_STAGE(G_SB(0, 1), b2 + chB, cvB0, cvB1);
;       G_WAIT_V(6); G_BAR; G_MMA(1, 1, At, B1); G_BAR;
.LBB0_2581:
	s_add_i32 s68, s14, 2
	ds_read_b128 v[144:147], v216
	ds_read_b128 v[148:151], v216 offset:1024
	ds_read_b128 v[152:155], v216 offset:2048
	ds_read_b128 v[156:159], v216 offset:3072
	s_add_u32 s15, s12, 0xfffc0080
	s_addc_u32 s16, s13, -1
	s_cmp_eq_u32 s11, s14
	s_cselect_b32 s14, s8, s66
	s_cselect_b32 s17, s7, s16
	s_cselect_b32 s16, s6, s15
	s_cselect_b32 s15, s9, s46
	v_lshl_add_u64 v[192:193], s[12:13], 0, v[138:139]
	s_add_i32 m0, s24, 0xc000
	ds_read_b128 v[160:163], v1
	ds_read_b128 v[164:167], v1 offset:1024
	ds_read_b128 v[168:171], v1 offset:2048
	ds_read_b128 v[172:175], v1 offset:3072
	ds_read_b128 v[176:179], v1 offset:4096
	ds_read_b128 v[180:183], v1 offset:5120
	ds_read_b128 v[184:187], v1 offset:6144
	ds_read_b128 v[188:191], v1 offset:7168
	global_load_lds_dwordx4 v[192:193], off
	v_lshl_add_u64 v[192:193], s[12:13], 0, v[140:141]
	s_add_i32 m0, s24, 0xe000
	s_nop 0
	global_load_lds_dwordx4 v[192:193], off
	s_waitcnt lgkmcnt(8)
	s_barrier
	s_waitcnt lgkmcnt(0)
	s_waitcnt lgkmcnt(0)
	v_mfma_f32_16x16x32_f16 v[126:129], v[144:147], v[160:163], v[126:129]
	v_mfma_f32_16x16x32_f16 v[122:125], v[152:155], v[160:163], v[122:125]
	v_mfma_f32_16x16x32_f16 v[110:113], v[144:147], v[168:171], v[110:113]
	v_mfma_f32_16x16x32_f16 v[106:109], v[152:155], v[168:171], v[106:109]
	v_mfma_f32_16x16x32_f16 v[94:97], v[144:147], v[176:179], v[94:97]
	v_mfma_f32_16x16x32_f16 v[90:93], v[152:155], v[176:179], v[90:93]
	v_mfma_f32_16x16x32_f16 v[78:81], v[144:147], v[184:187], v[78:81]
	v_mfma_f32_16x16x32_f16 v[74:77], v[152:155], v[184:187], v[74:77]
	v_mfma_f32_16x16x32_f16 v[126:129], v[148:151], v[164:167], v[126:129]
	v_mfma_f32_16x16x32_f16 v[122:125], v[156:159], v[164:167], v[122:125]
	v_mfma_f32_16x16x32_f16 v[110:113], v[148:151], v[172:175], v[110:113]
	v_mfma_f32_16x16x32_f16 v[106:109], v[156:159], v[172:175], v[106:109]
	v_mfma_f32_16x16x32_f16 v[94:97], v[148:151], v[180:183], v[94:97]
	v_mfma_f32_16x16x32_f16 v[90:93], v[156:159], v[180:183], v[90:93]
	v_mfma_f32_16x16x32_f16 v[78:81], v[148:151], v[188:191], v[78:81]
	v_mfma_f32_16x16x32_f16 v[74:77], v[156:159], v[188:191], v[74:77]
	s_barrier
	s_mov_b32 m0, s25
	v_lshl_add_u64 v[208:209], s[14:15], 0, v[132:133]
	ds_read_b128 v[192:195], v217
	ds_read_b128 v[196:199], v217 offset:1024
	ds_read_b128 v[200:203], v217 offset:2048
	ds_read_b128 v[204:207], v217 offset:3072
	global_load_lds_dwordx4 v[208:209], off
	v_lshl_add_u64 v[210:211], s[14:15], 0, v[136:137]
	s_mov_b32 m0, s26
	s_nop 0
	global_load_lds_dwordx4 v[210:211], off
	s_barrier
	s_waitcnt lgkmcnt(0)
	s_waitcnt lgkmcnt(0)
	v_mfma_f32_16x16x32_f16 v[118:121], v[192:195], v[160:163], v[118:121]
	v_mfma_f32_16x16x32_f16 v[114:117], v[200:203], v[160:163], v[114:117]
	v_mfma_f32_16x16x32_f16 v[102:105], v[192:195], v[168:171], v[102:105]
	v_mfma_f32_16x16x32_f16 v[98:101], v[200:203], v[168:171], v[98:101]
	v_mfma_f32_16x16x32_f16 v[86:89], v[192:195], v[176:179], v[86:89]
	v_mfma_f32_16x16x32_f16 v[82:85], v[200:203], v[176:179], v[82:85]
	v_mfma_f32_16x16x32_f16 v[70:73], v[192:195], v[184:187], v[70:73]
	v_mfma_f32_16x16x32_f16 v[66:69], v[200:203], v[184:187], v[66:69]
	v_mfma_f32_16x16x32_f16 v[118:121], v[196:199], v[164:167], v[118:121]
	v_mfma_f32_16x16x32_f16 v[114:117], v[204:207], v[164:167], v[114:117]
	v_mfma_f32_16x16x32_f16 v[102:105], v[196:199], v[172:175], v[102:105]
	v_mfma_f32_16x16x32_f16 v[98:101], v[204:207], v[172:175], v[98:101]
	v_mfma_f32_16x16x32_f16 v[86:89], v[196:199], v[180:183], v[86:89]
	v_mfma_f32_16x16x32_f16 v[82:85], v[204:207], v[180:183], v[82:85]
	v_mfma_f32_16x16x32_f16 v[70:73], v[196:199], v[188:191], v[70:73]
	v_mfma_f32_16x16x32_f16 v[66:69], v[204:207], v[188:191], v[66:69]
	s_mov_b32 m0, s24
	v_lshl_add_u64 v[212:213], s[16:17], 0, v[130:131]
	s_barrier
	ds_read_b128 v[160:163], v1 offset:16384
	ds_read_b128 v[164:167], v1 offset:17408
	ds_read_b128 v[168:171], v1 offset:18432
	ds_read_b128 v[172:175], v1 offset:19456
	ds_read_b128 v[176:179], v1 offset:20480
	ds_read_b128 v[180:183], v1 offset:21504
	ds_read_b128 v[184:187], v1 offset:22528
	ds_read_b128 v[188:191], v1 offset:23552
	global_load_lds_dwordx4 v[212:213], off
	v_lshl_add_u64 v[214:215], s[16:17], 0, v[134:135]
	s_mov_b32 m0, s27
	s_nop 0
	global_load_lds_dwordx4 v[214:215], off
	s_barrier
	s_waitcnt lgkmcnt(0)
	s_waitcnt lgkmcnt(0)
	v_mfma_f32_16x16x32_f16 v[62:65], v[144:147], v[160:163], v[62:65]
	v_mfma_f32_16x16x32_f16 v[58:61], v[152:155], v[160:163], v[58:61]
	v_mfma_f32_16x16x32_f16 v[46:49], v[144:147], v[168:171], v[46:49]
	v_mfma_f32_16x16x32_f16 v[42:45], v[152:155], v[168:171], v[42:45]
	v_mfma_f32_16x16x32_f16 v[30:33], v[144:147], v[176:179], v[30:33]
	v_mfma_f32_16x16x32_f16 v[26:29], v[152:155], v[176:179], v[26:29]
	v_mfma_f32_16x16x32_f16 v[14:17], v[144:147], v[184:187], v[14:17]
	v_mfma_f32_16x16x32_f16 v[10:13], v[152:155], v[184:187], v[10:13]
	v_mfma_f32_16x16x32_f16 v[62:65], v[148:151], v[164:167], v[62:65]
	v_mfma_f32_16x16x32_f16 v[58:61], v[156:159], v[164:167], v[58:61]
	v_mfma_f32_16x16x32_f16 v[46:49], v[148:151], v[172:175], v[46:49]
	v_mfma_f32_16x16x32_f16 v[42:45], v[156:159], v[172:175], v[42:45]
	v_mfma_f32_16x16x32_f16 v[30:33], v[148:151], v[180:183], v[30:33]
	v_mfma_f32_16x16x32_f16 v[26:29], v[156:159], v[180:183], v[26:29]
	v_mfma_f32_16x16x32_f16 v[14:17], v[148:151], v[188:191], v[14:17]
	v_mfma_f32_16x16x32_f16 v[10:13], v[156:159], v[188:191], v[10:13]
	s_barrier
	s_add_u32 s40, s14, 0x40000
	s_addc_u32 s41, s15, 0
	s_mov_b32 m0, s28
	v_lshl_add_u64 v[144:145], s[40:41], 0, v[132:133]
	global_load_lds_dwordx4 v[144:145], off
	v_lshl_add_u64 v[144:145], s[40:41], 0, v[136:137]
	s_mov_b32 m0, s29
	s_nop 0
	global_load_lds_dwordx4 v[144:145], off
	s_waitcnt vmcnt(6)
	s_barrier
; #define G_STAGE(bufoff, gbase, v0, v1) do { \
;     __builtin_amdgcn_global_load_lds((const unsigned*)((const char*)(gbase) + (v0)), (LAS unsigned*)(lds + (bufoff) + ldsw), 16, 0, 0); \
;     __builtin_amdgcn_global_load_lds((const unsigned*)((const char*)(gbase) + (v1)), (LAS unsigned*)(lds + (bufoff) + ldsw + 8192), 16, 0, 0); } while (0)
; #define G_LDA(dst, b, h) do { _Pragma("unroll") for (int m = 0; m < 4; ++m) _Pragma("unroll") for (int k = 0; k < 2; ++k) dst[m][k] = *(const LAS h8*)(lds + G_SA(b, h) + aoff + m * 2048 + k * 1024); } while (0)
; #define G_LDB(dst, b, h) do { _Pragma("unroll") for (int n = 0; n < 2; ++n) _Pragma("unroll") for (int k = 0; k < 2; ++k) dst[n][k] = *(const LAS h8*)(lds + G_SB(b, h) + boff + n * 2048 + k * 1024); } while (0)
; #define G_MMA(ai, bj, At, Bt) do { __builtin_amdgcn_s_setprio(1); _Pragma("unroll") for (int m = 0; m < 4; ++m) _Pragma("unroll") for (int n = 0; n < 2; ++n) _Pragma("unroll") for (int k = 0; k < 2; ++k) \
;     acc[ai][bj][m][n] = __builtin_amdgcn_mfma_f32_16x16x32_f16(Bt[n][k], At[m][k], acc[ai][bj][m][n], 0, 0, 0); __builtin_amdgcn_s_setprio(0); } while (0)
; #define G_WAIT_V(n) asm volatile("s_waitcnt vmcnt(" #n ")" ::: "memory")
; #define G_WAIT_L(n) asm volatile("s_waitcnt lgkmcnt(" #n ")" ::: "memory")
; #define G_BAR __builtin_amdgcn_s_barrier()
; #define G_SCHED __builtin_amdgcn_sched_barrier(0)
; template <bool PERM, class Sched, class Epi>
; DI void gemm256(LAS unsigned char* lds, const Sched& S, const Epi& E, int wv_) {
;     ...
;       G_WAIT_V(6); G_BAR; G_MMA(1, 1, At, B1); G_BAR;
;       G_LDB(B0, 1, 0); G_SCHED; G_LDA(At, 1, 0); G_STAGE(G_SA(0, 1), a2 + chA, cvA0, cvA1);
;       G_WAIT_L(8); G_BAR; G_WAIT_L(0); G_MMA(0, 0, At, B0); G_BAR; G_SCHED;
;       G_LDB(B1, 1, 1); G_STAGE(G_SB(1, 0), b3, cvB0, cvB1);
;       G_BAR; G_WAIT_L(0); G_MMA(0, 1, At, B1); G_BAR;
	v_mfma_f32_16x16x32_f16 v[54:57], v[192:195], v[160:163], v[54:57]
	v_mfma_f32_16x16x32_f16 v[50:53], v[200:203], v[160:163], v[50:53]
	v_mfma_f32_16x16x32_f16 v[38:41], v[192:195], v[168:171], v[38:41]
	v_mfma_f32_16x16x32_f16 v[34:37], v[200:203], v[168:171], v[34:37]
	v_mfma_f32_16x16x32_f16 v[22:25], v[192:195], v[176:179], v[22:25]
	v_mfma_f32_16x16x32_f16 v[18:21], v[200:203], v[176:179], v[18:21]
	v_mfma_f32_16x16x32_f16 v[6:9], v[192:195], v[184:187], v[6:9]
	v_mfma_f32_16x16x32_f16 v[2:5], v[200:203], v[184:187], v[2:5]
	v_mfma_f32_16x16x32_f16 v[54:57], v[196:199], v[164:167], v[54:57]
	v_mfma_f32_16x16x32_f16 v[50:53], v[204:207], v[164:167], v[50:53]
	v_mfma_f32_16x16x32_f16 v[38:41], v[196:199], v[172:175], v[38:41]
	v_mfma_f32_16x16x32_f16 v[34:37], v[204:207], v[172:175], v[34:37]
	v_mfma_f32_16x16x32_f16 v[22:25], v[196:199], v[180:183], v[22:25]
	v_mfma_f32_16x16x32_f16 v[18:21], v[204:207], v[180:183], v[18:21]
	v_mfma_f32_16x16x32_f16 v[6:9], v[196:199], v[188:191], v[6:9]
	v_mfma_f32_16x16x32_f16 v[2:5], v[204:207], v[188:191], v[2:5]
	s_barrier
	ds_read_b128 v[144:147], v218
	ds_read_b128 v[148:151], v218 offset:1024
	ds_read_b128 v[152:155], v218 offset:2048
	ds_read_b128 v[156:159], v218 offset:3072
	s_add_u32 s16, s16, 0x40000
	s_addc_u32 s17, s17, 0
	s_mov_b32 m0, s30
	v_lshl_add_u64 v[192:193], s[16:17], 0, v[130:131]
	ds_read_b128 v[160:163], v1 offset:32768
	ds_read_b128 v[164:167], v1 offset:33792
	ds_read_b128 v[168:171], v1 offset:34816
	ds_read_b128 v[172:175], v1 offset:35840
	ds_read_b128 v[176:179], v1 offset:36864
	ds_read_b128 v[180:183], v1 offset:37888
	ds_read_b128 v[184:187], v1 offset:38912
	ds_read_b128 v[188:191], v1 offset:39936
	global_load_lds_dwordx4 v[192:193], off
	v_lshl_add_u64 v[192:193], s[16:17], 0, v[134:135]
	s_mov_b32 m0, s31
	s_nop 0
	global_load_lds_dwordx4 v[192:193], off
	s_waitcnt lgkmcnt(8)
	s_barrier
	s_waitcnt lgkmcnt(0)
	s_waitcnt lgkmcnt(0)
	v_mfma_f32_16x16x32_f16 v[126:129], v[144:147], v[160:163], v[126:129]
	v_mfma_f32_16x16x32_f16 v[122:125], v[152:155], v[160:163], v[122:125]
	v_mfma_f32_16x16x32_f16 v[110:113], v[144:147], v[168:171], v[110:113]
	v_mfma_f32_16x16x32_f16 v[106:109], v[152:155], v[168:171], v[106:109]
	v_mfma_f32_16x16x32_f16 v[94:97], v[144:147], v[176:179], v[94:97]
	v_mfma_f32_16x16x32_f16 v[90:93], v[152:155], v[176:179], v[90:93]
	v_mfma_f32_16x16x32_f16 v[78:81], v[144:147], v[184:187], v[78:81]
	v_mfma_f32_16x16x32_f16 v[74:77], v[152:155], v[184:187], v[74:77]
	v_mfma_f32_16x16x32_f16 v[126:129], v[148:151], v[164:167], v[126:129]
	v_mfma_f32_16x16x32_f16 v[122:125], v[156:159], v[164:167], v[122:125]
	v_mfma_f32_16x16x32_f16 v[110:113], v[148:151], v[172:175], v[110:113]
	v_mfma_f32_16x16x32_f16 v[106:109], v[156:159], v[172:175], v[106:109]
	v_mfma_f32_16x16x32_f16 v[94:97], v[148:151], v[180:183], v[94:97]
	v_mfma_f32_16x16x32_f16 v[90:93], v[156:159], v[180:183], v[90:93]
	v_mfma_f32_16x16x32_f16 v[78:81], v[148:151], v[188:191], v[78:81]
	v_mfma_f32_16x16x32_f16 v[74:77], v[156:159], v[188:191], v[74:77]
	s_barrier
	s_mov_b32 m0, s35
	v_lshl_add_u64 v[208:209], v[208:209], 0, s[86:87]
	ds_read_b128 v[192:195], v219
	ds_read_b128 v[196:199], v219 offset:1024
	ds_read_b128 v[200:203], v219 offset:2048
	ds_read_b128 v[204:207], v219 offset:3072
	global_load_lds_dwordx4 v[208:209], off
	v_lshl_add_u64 v[208:209], v[210:211], 0, s[86:87]
	s_mov_b32 m0, s36
	s_nop 0
	global_load_lds_dwordx4 v[208:209], off
	s_barrier
; #define G_STAGE(bufoff, gbase, v0, v1) do { \
;     __builtin_amdgcn_global_load_lds((const unsigned*)((const char*)(gbase) + (v0)), (LAS unsigned*)(lds + (bufoff) + ldsw), 16, 0, 0); \
;     __builtin_amdgcn_global_load_lds((const unsigned*)((const char*)(gbase) + (v1)), (LAS unsigned*)(lds + (bufoff) + ldsw + 8192), 16, 0, 0); } while (0)
; #define G_LDA(dst, b, h) do { _Pragma("unroll") for (int m = 0; m < 4; ++m) _Pragma("unroll") for (int k = 0; k < 2; ++k) dst[m][k] = *(const LAS h8*)(lds + G_SA(b, h) + aoff + m * 2048 + k * 1024); } while (0)
; #define G_MMA(ai, bj, At, Bt) do { __builtin_amdgcn_s_setprio(1); _Pragma("unroll") for (int m = 0; m < 4; ++m) _Pragma("unroll") for (int n = 0; n < 2; ++n) _Pragma("unroll") for (int k = 0; k < 2; ++k) \
;     acc[ai][bj][m][n] = __builtin_amdgcn_mfma_f32_16x16x32_f16(Bt[n][k], At[m][k], acc[ai][bj][m][n], 0, 0, 0); __builtin_amdgcn_s_setprio(0); } while (0)
; #define G_WAIT_V(n) asm volatile("s_waitcnt vmcnt(" #n ")" ::: "memory")
; #define G_WAIT_L(n) asm volatile("s_waitcnt lgkmcnt(" #n ")" ::: "memory")
; #define G_BAR __builtin_amdgcn_s_barrier()
; #define G_SCHED __builtin_amdgcn_sched_barrier(0)
; template <bool PERM, class Sched, class Epi>
; DI void gemm256(LAS unsigned char* lds, const Sched& S, const Epi& E, int wv_) {
;     ...
;     for (int t = 0; t < nt; t += 2) {
;     ...
;       G_BAR; G_WAIT_L(0); G_MMA(0, 1, At, B1); G_BAR;
;       G_LDA(At, 1, 1); G_STAGE(G_SA(1, 0), a3, cvA0, cvA1);
;       G_BAR; G_WAIT_L(0); G_MMA(1, 0, At, B0); G_BAR; G_SCHED;
;       G_STAGE(G_SB(1, 1), b3 + chB, cvB0, cvB1);
;       G_WAIT_V(6); G_BAR; G_MMA(1, 1, At, B1); G_BAR;
	s_waitcnt lgkmcnt(0)
	s_waitcnt lgkmcnt(0)
	v_mfma_f32_16x16x32_f16 v[118:121], v[192:195], v[160:163], v[118:121]
	v_mfma_f32_16x16x32_f16 v[114:117], v[200:203], v[160:163], v[114:117]
	v_mfma_f32_16x16x32_f16 v[102:105], v[192:195], v[168:171], v[102:105]
	v_mfma_f32_16x16x32_f16 v[98:101], v[200:203], v[168:171], v[98:101]
	v_mfma_f32_16x16x32_f16 v[86:89], v[192:195], v[176:179], v[86:89]
	v_mfma_f32_16x16x32_f16 v[82:85], v[200:203], v[176:179], v[82:85]
	v_mfma_f32_16x16x32_f16 v[70:73], v[192:195], v[184:187], v[70:73]
	v_mfma_f32_16x16x32_f16 v[66:69], v[200:203], v[184:187], v[66:69]
	v_mfma_f32_16x16x32_f16 v[118:121], v[196:199], v[164:167], v[118:121]
	v_mfma_f32_16x16x32_f16 v[114:117], v[204:207], v[164:167], v[114:117]
	v_mfma_f32_16x16x32_f16 v[102:105], v[196:199], v[172:175], v[102:105]
	v_mfma_f32_16x16x32_f16 v[98:101], v[204:207], v[172:175], v[98:101]
	v_mfma_f32_16x16x32_f16 v[86:89], v[196:199], v[180:183], v[86:89]
	v_mfma_f32_16x16x32_f16 v[82:85], v[204:207], v[180:183], v[82:85]
	v_mfma_f32_16x16x32_f16 v[70:73], v[196:199], v[188:191], v[70:73]
	v_mfma_f32_16x16x32_f16 v[66:69], v[204:207], v[188:191], v[66:69]
	s_mov_b32 m0, s37
	v_lshl_add_u64 v[208:209], v[212:213], 0, s[86:87]
	s_barrier
	ds_read_b128 v[160:163], v1 offset:49152
	ds_read_b128 v[164:167], v1 offset:50176
	ds_read_b128 v[168:171], v1 offset:51200
	ds_read_b128 v[172:175], v1 offset:52224
	ds_read_b128 v[176:179], v1 offset:53248
	ds_read_b128 v[180:183], v1 offset:54272
	ds_read_b128 v[184:187], v1 offset:55296
	ds_read_b128 v[188:191], v1 offset:56320
	global_load_lds_dwordx4 v[208:209], off
	v_lshl_add_u64 v[208:209], v[214:215], 0, s[86:87]
	s_mov_b32 m0, s52
	s_nop 0
	global_load_lds_dwordx4 v[208:209], off
	s_barrier
	s_waitcnt lgkmcnt(0)
	s_waitcnt lgkmcnt(0)
	v_mfma_f32_16x16x32_f16 v[62:65], v[144:147], v[160:163], v[62:65]
	v_mfma_f32_16x16x32_f16 v[58:61], v[152:155], v[160:163], v[58:61]
	v_mfma_f32_16x16x32_f16 v[46:49], v[144:147], v[168:171], v[46:49]
	v_mfma_f32_16x16x32_f16 v[42:45], v[152:155], v[168:171], v[42:45]
	v_mfma_f32_16x16x32_f16 v[30:33], v[144:147], v[176:179], v[30:33]
	v_mfma_f32_16x16x32_f16 v[26:29], v[152:155], v[176:179], v[26:29]
	v_mfma_f32_16x16x32_f16 v[14:17], v[144:147], v[184:187], v[14:17]
	v_mfma_f32_16x16x32_f16 v[10:13], v[152:155], v[184:187], v[10:13]
	v_mfma_f32_16x16x32_f16 v[62:65], v[148:151], v[164:167], v[62:65]
	v_mfma_f32_16x16x32_f16 v[58:61], v[156:159], v[164:167], v[58:61]
	v_mfma_f32_16x16x32_f16 v[46:49], v[148:151], v[172:175], v[46:49]
	v_mfma_f32_16x16x32_f16 v[42:45], v[156:159], v[172:175], v[42:45]
	v_mfma_f32_16x16x32_f16 v[30:33], v[148:151], v[180:183], v[30:33]
	v_mfma_f32_16x16x32_f16 v[26:29], v[156:159], v[180:183], v[26:29]
	v_mfma_f32_16x16x32_f16 v[14:17], v[148:151], v[188:191], v[14:17]
	v_mfma_f32_16x16x32_f16 v[10:13], v[156:159], v[188:191], v[10:13]
	s_barrier
	s_add_u32 s14, s14, 0x40080
	s_addc_u32 s15, s15, 0
	s_mov_b32 m0, s53
	v_lshl_add_u64 v[144:145], s[14:15], 0, v[132:133]
	global_load_lds_dwordx4 v[144:145], off
	v_lshl_add_u64 v[144:145], s[14:15], 0, v[136:137]
	s_mov_b32 m0, s56
	s_nop 0
	global_load_lds_dwordx4 v[144:145], off
	s_waitcnt vmcnt(6)
	s_barrier
	v_mfma_f32_16x16x32_f16 v[54:57], v[192:195], v[160:163], v[54:57]
	v_mfma_f32_16x16x32_f16 v[50:53], v[200:203], v[160:163], v[50:53]
	v_mfma_f32_16x16x32_f16 v[38:41], v[192:195], v[168:171], v[38:41]
	v_mfma_f32_16x16x32_f16 v[34:37], v[200:203], v[168:171], v[34:37]
	v_mfma_f32_16x16x32_f16 v[22:25], v[192:195], v[176:179], v[22:25]
	v_mfma_f32_16x16x32_f16 v[18:21], v[200:203], v[176:179], v[18:21]
	v_mfma_f32_16x16x32_f16 v[6:9], v[192:195], v[184:187], v[6:9]
	v_mfma_f32_16x16x32_f16 v[2:5], v[200:203], v[184:187], v[2:5]
	v_mfma_f32_16x16x32_f16 v[54:57], v[196:199], v[164:167], v[54:57]
	v_mfma_f32_16x16x32_f16 v[50:53], v[204:207], v[164:167], v[50:53]
	v_mfma_f32_16x16x32_f16 v[38:41], v[196:199], v[172:175], v[38:41]
	v_mfma_f32_16x16x32_f16 v[34:37], v[204:207], v[172:175], v[34:37]
	v_mfma_f32_16x16x32_f16 v[22:25], v[196:199], v[180:183], v[22:25]
	v_mfma_f32_16x16x32_f16 v[18:21], v[204:207], v[180:183], v[18:21]
	v_mfma_f32_16x16x32_f16 v[6:9], v[196:199], v[188:191], v[6:9]
	v_mfma_f32_16x16x32_f16 v[2:5], v[204:207], v[188:191], v[2:5]
	s_add_u32 s12, s12, 0x100
	s_addc_u32 s13, s13, 0
	s_add_u32 s66, s66, 0x100
	s_addc_u32 s46, s46, 0
	s_cmp_ge_i32 s68, s5
	s_mov_b32 s14, s68
	s_barrier
	s_cbranch_scc0 .LBB0_2581
	s_branch .LBB0_2583

;   static DI int bmap(bool perm, int R) { return perm ? ((R & ~31) + perm32(R & 31)) : R; }
; #define G_STAGE(bufoff, gbase, v0, v1) do { \
;     __builtin_amdgcn_global_load_lds((const unsigned*)((const char*)(gbase) + (v0)), (LAS unsigned*)(lds + (bufoff) + ldsw), 16, 0, 0); \
;     __builtin_amdgcn_global_load_lds((const unsigned*)((const char*)(gbase) + (v1)), (LAS unsigned*)(lds + (bufoff) + ldsw + 8192), 16, 0, 0); } while (0)
; #define G_WAIT_V(n) asm volatile("s_waitcnt vmcnt(" #n ")" ::: "memory")
; #define G_BAR __builtin_amdgcn_s_barrier()
;   static DI int bmap(bool, int R) { return ((R >> 4) & 1) * 1024 + (R >> 5) * 16 + (R & 15); }
; template <bool PERM, class Sched, class Epi>
; DI void gemm256(LAS unsigned char* lds, const Sched& S, const Epi& E, int wv_) {
;   const int tid = tid_opaque(wv_), wid = __builtin_amdgcn_readfirstlane(tid >> 6), lane = tid & 63, wr = wid >> 2, wc = wid & 3, fr = lane & 15, fq = lane >> 4;
;   unsigned cvA0, cvA1, cvB0, cvB1;
;   { int R, C;
;     stage_rc(tid * 16, R, C); cvA0 = (unsigned)R * S.lda2 + C * 2; cvB0 = (unsigned)Sched::bmap(PERM, R) * S.ldb2 + C * 2;
;     stage_rc(tid * 16 + 8192, R, C); cvA1 = (unsigned)R * S.lda2 + C * 2; cvB1 = (unsigned)Sched::bmap(PERM, R) * S.ldb2 + C * 2; }
;   const size_t chA = (size_t)HALF * S.lda2, chB = (size_t)Sched::BHALF * S.ldb2;
;   const size_t kstep = (size_t)(BK * 2);
;   const unsigned ldsw = (unsigned)wid * 1024u;
;   const int aoff = lds_byte(wr * 64 + fr, fq * 8), boff = lds_byte(wc * 32 + fr, fq * 8);
;     ...
;   GUnit cur, nxt;
;   int ui = 0;
;   if (!S.next(0, cur)) return;
;   f4 acc[2][2][4][2];
; #pragma unroll
;   for (int a = 0; a < 2; ++a)
; #pragma unroll
;     for (int b = 0; b < 2; ++b)
; #pragma unroll
;       for (int m = 0; m < 4; ++m)
; #pragma unroll
;         for (int n = 0; n < 2; ++n) acc[a][b][m][n] = f4{0.f, 0.f, 0.f, 0.f};
;   h8 At[4][2], B0[2][2], B1[2][2];
;   const char* cA = cur.A;
;   const char* cB = cur.B;
;   G_STAGE(G_SB(0, 0), cB, cvB0, cvB1); G_STAGE(G_SA(0, 0), cA, cvA0, cvA1); G_STAGE(G_SB(0, 1), cB + chB, cvB0, cvB1); G_STAGE(G_SA(0, 1), cA + chA, cvA0, cvA1);
;   if (wr == 1) G_BAR;
;   G_WAIT_V(4); G_BAR;
;   G_STAGE(G_SB(1, 0), cB + kstep, cvB0, cvB1); G_STAGE(G_SA(1, 0), cA + kstep, cvA0, cvA1); G_STAGE(G_SB(1, 1), cB + chB + kstep, cvB0, cvB1);
;   G_WAIT_V(6); G_BAR;
.LBB0_2643:
	v_mov_b32_e32 v151, v0
	v_lshl_add_u64 v[8:9], s[22:23], 0, v[150:151]
	v_mov_b32_e32 v153, v0
	s_lshl_b32 s7, s7, 5
	s_add_i32 s69, s35, 0x18000
	v_lshl_add_u64 v[10:11], s[22:23], 0, v[152:153]
	s_and_b32 s68, s7, 0x60
	v_lshl_add_u64 v[8:9], v[8:9], 0, s[86:87]
	s_mov_b32 m0, s69
	s_add_i32 s78, s35, 0x1a000
	v_lshl_add_u64 v[12:13], s[20:21], 0, v[150:151]
	s_lshl_b32 s6, s8, 6
	s_lshl_b32 s10, s8, 13
	s_lshl_b32 s7, s68, 7
	s_waitcnt vmcnt(4)
	s_barrier
	global_load_lds_dwordx4 v[8:9], off
	v_lshl_add_u64 v[8:9], v[10:11], 0, s[86:87]
	s_mov_b32 m0, s78
	s_add_i32 s79, s35, 0x8000
	s_add_i32 s83, s35, 0xa000
	v_lshl_add_u64 v[14:15], s[20:21], 0, v[152:153]
	global_load_lds_dwordx4 v[8:9], off
	v_lshl_add_u64 v[8:9], v[12:13], 0, s[86:87]
	s_mov_b32 m0, s79
	s_add_u32 s8, s22, 0x100080
	global_load_lds_dwordx4 v[8:9], off
	v_lshl_add_u64 v[8:9], v[14:15], 0, s[86:87]
	s_mov_b32 m0, s83
	s_addc_u32 s9, s23, 0
	s_add_i32 s84, s35, 0x1c000
	global_load_lds_dwordx4 v[8:9], off
	v_lshl_add_u64 v[8:9], s[8:9], 0, v[150:151]
	s_mov_b32 m0, s84
	s_add_i32 s85, s35, 0x1e000
	global_load_lds_dwordx4 v[8:9], off
	v_lshl_add_u64 v[8:9], s[8:9], 0, v[152:153]
	s_mov_b32 m0, s85
	v_and_b32_e32 v154, 48, v1
	global_load_lds_dwordx4 v[8:9], off
	v_and_b32_e32 v8, 15, v1
	v_lshl_or_b32 v9, v8, 6, v154
	v_lshl_or_b32 v156, v8, 12, v154
	v_lshlrev_b32_e32 v8, 16, v2
	v_and_b32_e32 v8, 0xfffe0000, v8
	v_lshl_add_u32 v3, v3, 13, v8
	v_and_b32_e32 v2, 1, v2
	v_lshl_or_b32 v2, v2, 6, v3
	v_lshl_add_u32 v158, v4, 1, v2
	v_lshlrev_b32_e32 v2, 16, v5
	v_lshlrev_b32_e32 v1, 2, v1
	v_and_b32_e32 v2, 0xfffe0000, v2
	v_and_b32_e32 v10, 32, v1
	s_waitcnt vmcnt(6)
	v_lshl_add_u32 v2, v6, 13, v2
	v_and_b32_e32 v3, 1, v5
	v_bitop3_b32 v1, v9, s10, v10 bitop3:0xde
	v_bitop3_b32 v162, s7, v9, v10 bitop3:0xf6
	v_add_u32_e32 v216, 0x10000, v162
	v_add_u32_e32 v217, 0x14000, v162
	v_add_u32_e32 v218, 0x18000, v162
	v_add_u32_e32 v219, 0x1c000, v162
	s_ashr_i32 s7, s6, 31
	v_lshl_or_b32 v2, v3, 6, v2
	v_readlane_b32 s10, v254, 24
	v_mov_b32_e32 v155, v0
	s_lshl_b64 s[8:9], s[6:7], 10
	v_mov_b32_e32 v157, v0
	s_lshl_b32 s60, s60, 4
	v_mov_b32_e32 v159, v0
	v_lshl_add_u32 v160, v7, 1, v2
	v_mov_b32_e32 v161, v0
	s_mov_b32 s90, 0
	s_mov_b32 s18, s10
	s_barrier
	s_branch .LBB0_2645

; #define G_STAGE(bufoff, gbase, v0, v1) do { \
;     __builtin_amdgcn_global_load_lds((const unsigned*)((const char*)(gbase) + (v0)), (LAS unsigned*)(lds + (bufoff) + ldsw), 16, 0, 0); \
;     __builtin_amdgcn_global_load_lds((const unsigned*)((const char*)(gbase) + (v1)), (LAS unsigned*)(lds + (bufoff) + ldsw + 8192), 16, 0, 0); } while (0)
; #define G_LDA(dst, b, h) do { _Pragma("unroll") for (int m = 0; m < 4; ++m) _Pragma("unroll") for (int k = 0; k < 2; ++k) dst[m][k] = *(const LAS h8*)(lds + G_SA(b, h) + aoff + m * 2048 + k * 1024); } while (0)
; #define G_LDB(dst, b, h) do { _Pragma("unroll") for (int n = 0; n < 2; ++n) _Pragma("unroll") for (int k = 0; k < 2; ++k) dst[n][k] = *(const LAS h8*)(lds + G_SB(b, h) + boff + n * 2048 + k * 1024); } while (0)
; #define G_MMA(ai, bj, At, Bt) do { __builtin_amdgcn_s_setprio(1); _Pragma("unroll") for (int m = 0; m < 4; ++m) _Pragma("unroll") for (int n = 0; n < 2; ++n) _Pragma("unroll") for (int k = 0; k < 2; ++k) \
;     acc[ai][bj][m][n] = __builtin_amdgcn_mfma_f32_16x16x32_f16(Bt[n][k], At[m][k], acc[ai][bj][m][n], 0, 0, 0); __builtin_amdgcn_s_setprio(0); } while (0)
; #define G_WAIT_V(n) asm volatile("s_waitcnt vmcnt(" #n ")" ::: "memory")
; #define G_WAIT_L(n) asm volatile("s_waitcnt lgkmcnt(" #n ")" ::: "memory")
; #define G_BAR __builtin_amdgcn_s_barrier()
; #define G_SCHED __builtin_amdgcn_sched_barrier(0)
; template <bool PERM, class Sched, class Epi>
; DI void gemm256(LAS unsigned char* lds, const Sched& S, const Epi& E, int wv_) {
;     ...
;       const bool last = (t == nt - 2);
;       const char* a1 = cA + (size_t)(t + 1) * kstep;
;       const char* a2 = last ? nA : cA + (size_t)(t + 2) * kstep;
;       const char* b2 = last ? nB : cB + (size_t)(t + 2) * kstep;
;       const char* a3 = a2 + kstep;
;       const char* b3 = b2 + kstep;
;       G_LDB(B0, 0, 0); G_SCHED; G_LDA(At, 0, 0); G_STAGE(G_SA(1, 1), a1 + chA, cvA0, cvA1);
;       G_WAIT_L(8); G_BAR; G_WAIT_L(0); G_MMA(0, 0, At, B0); G_BAR; G_SCHED;
;       G_LDB(B1, 0, 1); G_STAGE(G_SB(0, 0), b2, cvB0, cvB1);
;       G_BAR; G_WAIT_L(0); G_MMA(0, 1, At, B1); G_BAR;
;       G_LDA(At, 0, 1); G_STAGE(G_SA(0, 0), a2, cvA0, cvA1);
;       G_BAR; G_WAIT_L(0); G_MMA(1, 0, At, B0); G_BAR; G_SCHED;
;       G_STAGE(G_SB(0, 1), b2 + chB, cvB0, cvB1);
;       G_WAIT_V(6); G_BAR; G_MMA(1, 1, At, B1); G_BAR;
.LBB0_2656:
	s_waitcnt vmcnt(0)
	s_add_i32 s91, s22, 2
	ds_read_b128 v[130:133], v216
	ds_read_b128 v[134:137], v216 offset:1024
	ds_read_b128 v[138:141], v216 offset:2048
	ds_read_b128 v[142:145], v216 offset:3072
	s_add_u32 s23, s20, 0xfff00080
	s_addc_u32 s24, s21, -1
	s_cmp_eq_u32 s27, s22
	s_cselect_b32 s22, vcc_hi, s46
	s_cselect_b32 s25, s29, s24
	s_cselect_b32 s24, s56, s23
	s_cselect_b32 s23, vcc_lo, s74
	v_lshl_add_u64 v[192:193], s[20:21], 0, v[158:159]
	s_add_i32 m0, s35, 0xc000
	ds_read_b128 v[146:149], v1
	ds_read_b128 v[164:167], v1 offset:1024
	ds_read_b128 v[168:171], v1 offset:2048
	ds_read_b128 v[172:175], v1 offset:3072
	ds_read_b128 v[176:179], v1 offset:4096
	ds_read_b128 v[180:183], v1 offset:5120
	ds_read_b128 v[184:187], v1 offset:6144
	ds_read_b128 v[188:191], v1 offset:7168
	global_load_lds_dwordx4 v[192:193], off
	v_lshl_add_u64 v[192:193], s[20:21], 0, v[160:161]
	s_add_i32 m0, s35, 0xe000
	s_nop 0
	global_load_lds_dwordx4 v[192:193], off
	s_waitcnt lgkmcnt(8)
	s_barrier
	s_waitcnt lgkmcnt(0)
	s_waitcnt lgkmcnt(0)
	v_mfma_f32_16x16x32_f16 v[126:129], v[130:133], v[146:149], v[126:129]
	v_mfma_f32_16x16x32_f16 v[122:125], v[138:141], v[146:149], v[122:125]
	v_mfma_f32_16x16x32_f16 v[110:113], v[130:133], v[168:171], v[110:113]
	v_mfma_f32_16x16x32_f16 v[106:109], v[138:141], v[168:171], v[106:109]
	v_mfma_f32_16x16x32_f16 v[94:97], v[130:133], v[176:179], v[94:97]
	v_mfma_f32_16x16x32_f16 v[90:93], v[138:141], v[176:179], v[90:93]
	v_mfma_f32_16x16x32_f16 v[78:81], v[130:133], v[184:187], v[78:81]
	v_mfma_f32_16x16x32_f16 v[74:77], v[138:141], v[184:187], v[74:77]
	v_mfma_f32_16x16x32_f16 v[126:129], v[134:137], v[164:167], v[126:129]
	v_mfma_f32_16x16x32_f16 v[122:125], v[142:145], v[164:167], v[122:125]
	v_mfma_f32_16x16x32_f16 v[110:113], v[134:137], v[172:175], v[110:113]
	v_mfma_f32_16x16x32_f16 v[106:109], v[142:145], v[172:175], v[106:109]
	v_mfma_f32_16x16x32_f16 v[94:97], v[134:137], v[180:183], v[94:97]
	v_mfma_f32_16x16x32_f16 v[90:93], v[142:145], v[180:183], v[90:93]
	v_mfma_f32_16x16x32_f16 v[78:81], v[134:137], v[188:191], v[78:81]
	v_mfma_f32_16x16x32_f16 v[74:77], v[142:145], v[188:191], v[74:77]
	s_barrier
	s_mov_b32 m0, s36
	ds_read_b128 v[192:195], v217
	ds_read_b128 v[196:199], v217 offset:1024
	v_lshl_add_u64 v[208:209], s[22:23], 0, v[150:151]
	ds_read_b128 v[200:203], v217 offset:2048
	ds_read_b128 v[204:207], v217 offset:3072
	global_load_lds_dwordx4 v[208:209], off
	v_lshl_add_u64 v[210:211], s[22:23], 0, v[152:153]
	s_mov_b32 m0, s37
	s_nop 0
	global_load_lds_dwordx4 v[210:211], off
	s_barrier
	s_waitcnt lgkmcnt(0)
	s_waitcnt lgkmcnt(0)
	v_mfma_f32_16x16x32_f16 v[118:121], v[192:195], v[146:149], v[118:121]
	v_mfma_f32_16x16x32_f16 v[114:117], v[200:203], v[146:149], v[114:117]
	v_mfma_f32_16x16x32_f16 v[102:105], v[192:195], v[168:171], v[102:105]
	v_mfma_f32_16x16x32_f16 v[98:101], v[200:203], v[168:171], v[98:101]
	v_mfma_f32_16x16x32_f16 v[86:89], v[192:195], v[176:179], v[86:89]
	v_mfma_f32_16x16x32_f16 v[82:85], v[200:203], v[176:179], v[82:85]
	v_mfma_f32_16x16x32_f16 v[70:73], v[192:195], v[184:187], v[70:73]
	v_mfma_f32_16x16x32_f16 v[66:69], v[200:203], v[184:187], v[66:69]
	v_mfma_f32_16x16x32_f16 v[118:121], v[196:199], v[164:167], v[118:121]
	v_mfma_f32_16x16x32_f16 v[114:117], v[204:207], v[164:167], v[114:117]
	v_mfma_f32_16x16x32_f16 v[102:105], v[196:199], v[172:175], v[102:105]
	v_mfma_f32_16x16x32_f16 v[98:101], v[204:207], v[172:175], v[98:101]
	v_mfma_f32_16x16x32_f16 v[86:89], v[196:199], v[180:183], v[86:89]
	v_mfma_f32_16x16x32_f16 v[82:85], v[204:207], v[180:183], v[82:85]
	v_mfma_f32_16x16x32_f16 v[70:73], v[196:199], v[188:191], v[70:73]
	v_mfma_f32_16x16x32_f16 v[66:69], v[204:207], v[188:191], v[66:69]
	s_mov_b32 m0, s35
	v_lshl_add_u64 v[212:213], s[24:25], 0, v[150:151]
	s_barrier
	ds_read_b128 v[146:149], v1 offset:16384
	ds_read_b128 v[164:167], v1 offset:17408
	ds_read_b128 v[168:171], v1 offset:18432
	ds_read_b128 v[172:175], v1 offset:19456
	ds_read_b128 v[176:179], v1 offset:20480
	ds_read_b128 v[180:183], v1 offset:21504
	ds_read_b128 v[184:187], v1 offset:22528
	ds_read_b128 v[188:191], v1 offset:23552
	global_load_lds_dwordx4 v[212:213], off
	v_lshl_add_u64 v[214:215], s[24:25], 0, v[152:153]
	s_mov_b32 m0, s52
	s_nop 0
	global_load_lds_dwordx4 v[214:215], off
	s_barrier
	s_waitcnt lgkmcnt(0)
	s_waitcnt lgkmcnt(0)
	v_mfma_f32_16x16x32_f16 v[62:65], v[130:133], v[146:149], v[62:65]
	v_mfma_f32_16x16x32_f16 v[58:61], v[138:141], v[146:149], v[58:61]
	v_mfma_f32_16x16x32_f16 v[46:49], v[130:133], v[168:171], v[46:49]
	v_mfma_f32_16x16x32_f16 v[42:45], v[138:141], v[168:171], v[42:45]
	v_mfma_f32_16x16x32_f16 v[30:33], v[130:133], v[176:179], v[30:33]
	v_mfma_f32_16x16x32_f16 v[26:29], v[138:141], v[176:179], v[26:29]
	v_mfma_f32_16x16x32_f16 v[14:17], v[130:133], v[184:187], v[14:17]
	v_mfma_f32_16x16x32_f16 v[10:13], v[138:141], v[184:187], v[10:13]
	v_mfma_f32_16x16x32_f16 v[62:65], v[134:137], v[164:167], v[62:65]
	v_mfma_f32_16x16x32_f16 v[58:61], v[142:145], v[164:167], v[58:61]
	v_mfma_f32_16x16x32_f16 v[46:49], v[134:137], v[172:175], v[46:49]
	v_mfma_f32_16x16x32_f16 v[42:45], v[142:145], v[172:175], v[42:45]
	v_mfma_f32_16x16x32_f16 v[30:33], v[134:137], v[180:183], v[30:33]
	v_mfma_f32_16x16x32_f16 v[26:29], v[142:145], v[180:183], v[26:29]
	v_mfma_f32_16x16x32_f16 v[14:17], v[134:137], v[188:191], v[14:17]
	v_mfma_f32_16x16x32_f16 v[10:13], v[142:145], v[188:191], v[10:13]
	s_barrier
; #define G_STAGE(bufoff, gbase, v0, v1) do { \
;     __builtin_amdgcn_global_load_lds((const unsigned*)((const char*)(gbase) + (v0)), (LAS unsigned*)(lds + (bufoff) + ldsw), 16, 0, 0); \
;     __builtin_amdgcn_global_load_lds((const unsigned*)((const char*)(gbase) + (v1)), (LAS unsigned*)(lds + (bufoff) + ldsw + 8192), 16, 0, 0); } while (0)
; #define G_LDA(dst, b, h) do { _Pragma("unroll") for (int m = 0; m < 4; ++m) _Pragma("unroll") for (int k = 0; k < 2; ++k) dst[m][k] = *(const LAS h8*)(lds + G_SA(b, h) + aoff + m * 2048 + k * 1024); } while (0)
; #define G_LDB(dst, b, h) do { _Pragma("unroll") for (int n = 0; n < 2; ++n) _Pragma("unroll") for (int k = 0; k < 2; ++k) dst[n][k] = *(const LAS h8*)(lds + G_SB(b, h) + boff + n * 2048 + k * 1024); } while (0)
; #define G_MMA(ai, bj, At, Bt) do { __builtin_amdgcn_s_setprio(1); _Pragma("unroll") for (int m = 0; m < 4; ++m) _Pragma("unroll") for (int n = 0; n < 2; ++n) _Pragma("unroll") for (int k = 0; k < 2; ++k) \
;     acc[ai][bj][m][n] = __builtin_amdgcn_mfma_f32_16x16x32_f16(Bt[n][k], At[m][k], acc[ai][bj][m][n], 0, 0, 0); __builtin_amdgcn_s_setprio(0); } while (0)
; #define G_WAIT_V(n) asm volatile("s_waitcnt vmcnt(" #n ")" ::: "memory")
; #define G_WAIT_L(n) asm volatile("s_waitcnt lgkmcnt(" #n ")" ::: "memory")
; #define G_BAR __builtin_amdgcn_s_barrier()
; #define G_SCHED __builtin_amdgcn_sched_barrier(0)
; template <bool PERM, class Sched, class Epi>
; DI void gemm256(LAS unsigned char* lds, const Sched& S, const Epi& E, int wv_) {
;     ...
;       G_WAIT_V(6); G_BAR; G_MMA(1, 1, At, B1); G_BAR;
;       G_LDB(B0, 1, 0); G_SCHED; G_LDA(At, 1, 0); G_STAGE(G_SA(0, 1), a2 + chA, cvA0, cvA1);
;       G_WAIT_L(8); G_BAR; G_WAIT_L(0); G_MMA(0, 0, At, B0); G_BAR; G_SCHED;
;       G_LDB(B1, 1, 1); G_STAGE(G_SB(1, 0), b3, cvB0, cvB1);
;       G_BAR; G_WAIT_L(0); G_MMA(0, 1, At, B1); G_BAR;
	s_add_u32 s40, s22, 0x100000
	s_addc_u32 s41, s23, 0
	s_mov_b32 m0, s53
	v_lshl_add_u64 v[130:131], s[40:41], 0, v[150:151]
	global_load_lds_dwordx4 v[130:131], off
	v_lshl_add_u64 v[130:131], s[40:41], 0, v[152:153]
	s_mov_b32 m0, s58
	s_nop 0
	global_load_lds_dwordx4 v[130:131], off
	s_waitcnt vmcnt(6)
	s_barrier
	v_mfma_f32_16x16x32_f16 v[54:57], v[192:195], v[146:149], v[54:57]
	v_mfma_f32_16x16x32_f16 v[50:53], v[200:203], v[146:149], v[50:53]
	v_mfma_f32_16x16x32_f16 v[38:41], v[192:195], v[168:171], v[38:41]
	v_mfma_f32_16x16x32_f16 v[34:37], v[200:203], v[168:171], v[34:37]
	v_mfma_f32_16x16x32_f16 v[22:25], v[192:195], v[176:179], v[22:25]
	v_mfma_f32_16x16x32_f16 v[18:21], v[200:203], v[176:179], v[18:21]
	v_mfma_f32_16x16x32_f16 v[6:9], v[192:195], v[184:187], v[6:9]
	v_mfma_f32_16x16x32_f16 v[2:5], v[200:203], v[184:187], v[2:5]
	v_mfma_f32_16x16x32_f16 v[54:57], v[196:199], v[164:167], v[54:57]
	v_mfma_f32_16x16x32_f16 v[50:53], v[204:207], v[164:167], v[50:53]
	v_mfma_f32_16x16x32_f16 v[38:41], v[196:199], v[172:175], v[38:41]
	v_mfma_f32_16x16x32_f16 v[34:37], v[204:207], v[172:175], v[34:37]
	v_mfma_f32_16x16x32_f16 v[22:25], v[196:199], v[180:183], v[22:25]
	v_mfma_f32_16x16x32_f16 v[18:21], v[204:207], v[180:183], v[18:21]
	v_mfma_f32_16x16x32_f16 v[6:9], v[196:199], v[188:191], v[6:9]
	v_mfma_f32_16x16x32_f16 v[2:5], v[204:207], v[188:191], v[2:5]
	s_barrier
	ds_read_b128 v[130:133], v218
	ds_read_b128 v[134:137], v218 offset:1024
	ds_read_b128 v[138:141], v218 offset:2048
	ds_read_b128 v[142:145], v218 offset:3072
	s_add_u32 s24, s24, 0x100000
	s_addc_u32 s25, s25, 0
	s_mov_b32 m0, s59
	v_lshl_add_u64 v[192:193], s[24:25], 0, v[150:151]
	ds_read_b128 v[146:149], v1 offset:32768
	ds_read_b128 v[164:167], v1 offset:33792
	ds_read_b128 v[168:171], v1 offset:34816
	ds_read_b128 v[172:175], v1 offset:35840
	ds_read_b128 v[176:179], v1 offset:36864
	ds_read_b128 v[180:183], v1 offset:37888
	ds_read_b128 v[184:187], v1 offset:38912
	ds_read_b128 v[188:191], v1 offset:39936
	global_load_lds_dwordx4 v[192:193], off
	v_lshl_add_u64 v[192:193], s[24:25], 0, v[152:153]
	s_mov_b32 m0, s61
	s_nop 0
	global_load_lds_dwordx4 v[192:193], off
	s_waitcnt lgkmcnt(8)
	s_barrier
	s_waitcnt lgkmcnt(0)
	s_waitcnt lgkmcnt(0)
	v_mfma_f32_16x16x32_f16 v[126:129], v[130:133], v[146:149], v[126:129]
	v_mfma_f32_16x16x32_f16 v[122:125], v[138:141], v[146:149], v[122:125]
	v_mfma_f32_16x16x32_f16 v[110:113], v[130:133], v[168:171], v[110:113]
	v_mfma_f32_16x16x32_f16 v[106:109], v[138:141], v[168:171], v[106:109]
	v_mfma_f32_16x16x32_f16 v[94:97], v[130:133], v[176:179], v[94:97]
	v_mfma_f32_16x16x32_f16 v[90:93], v[138:141], v[176:179], v[90:93]
	v_mfma_f32_16x16x32_f16 v[78:81], v[130:133], v[184:187], v[78:81]
	v_mfma_f32_16x16x32_f16 v[74:77], v[138:141], v[184:187], v[74:77]
	v_mfma_f32_16x16x32_f16 v[126:129], v[134:137], v[164:167], v[126:129]
	v_mfma_f32_16x16x32_f16 v[122:125], v[142:145], v[164:167], v[122:125]
	v_mfma_f32_16x16x32_f16 v[110:113], v[134:137], v[172:175], v[110:113]
	v_mfma_f32_16x16x32_f16 v[106:109], v[142:145], v[172:175], v[106:109]
	v_mfma_f32_16x16x32_f16 v[94:97], v[134:137], v[180:183], v[94:97]
	v_mfma_f32_16x16x32_f16 v[90:93], v[142:145], v[180:183], v[90:93]
	v_mfma_f32_16x16x32_f16 v[78:81], v[134:137], v[188:191], v[78:81]
	v_mfma_f32_16x16x32_f16 v[74:77], v[142:145], v[188:191], v[74:77]
	s_barrier
	s_mov_b32 m0, s69
	ds_read_b128 v[192:195], v219
	ds_read_b128 v[196:199], v219 offset:1024
	v_lshl_add_u64 v[208:209], v[208:209], 0, s[86:87]
	ds_read_b128 v[200:203], v219 offset:2048
	ds_read_b128 v[204:207], v219 offset:3072
	global_load_lds_dwordx4 v[208:209], off
	v_lshl_add_u64 v[208:209], v[210:211], 0, s[86:87]
	s_mov_b32 m0, s78
	s_nop 0
	global_load_lds_dwordx4 v[208:209], off
	s_barrier
; #define G_STAGE(bufoff, gbase, v0, v1) do { \
;     __builtin_amdgcn_global_load_lds((const unsigned*)((const char*)(gbase) + (v0)), (LAS unsigned*)(lds + (bufoff) + ldsw), 16, 0, 0); \
;     __builtin_amdgcn_global_load_lds((const unsigned*)((const char*)(gbase) + (v1)), (LAS unsigned*)(lds + (bufoff) + ldsw + 8192), 16, 0, 0); } while (0)
; #define G_LDA(dst, b, h) do { _Pragma("unroll") for (int m = 0; m < 4; ++m) _Pragma("unroll") for (int k = 0; k < 2; ++k) dst[m][k] = *(const LAS h8*)(lds + G_SA(b, h) + aoff + m * 2048 + k * 1024); } while (0)
; #define G_MMA(ai, bj, At, Bt) do { __builtin_amdgcn_s_setprio(1); _Pragma("unroll") for (int m = 0; m < 4; ++m) _Pragma("unroll") for (int n = 0; n < 2; ++n) _Pragma("unroll") for (int k = 0; k < 2; ++k) \
;     acc[ai][bj][m][n] = __builtin_amdgcn_mfma_f32_16x16x32_f16(Bt[n][k], At[m][k], acc[ai][bj][m][n], 0, 0, 0); __builtin_amdgcn_s_setprio(0); } while (0)
; #define G_WAIT_V(n) asm volatile("s_waitcnt vmcnt(" #n ")" ::: "memory")
; #define G_WAIT_L(n) asm volatile("s_waitcnt lgkmcnt(" #n ")" ::: "memory")
; #define G_BAR __builtin_amdgcn_s_barrier()
; #define G_SCHED __builtin_amdgcn_sched_barrier(0)
; template <bool PERM, class Sched, class Epi>
; DI void gemm256(LAS unsigned char* lds, const Sched& S, const Epi& E, int wv_) {
;     ...
;     for (int t = 0; t < nt; t += 2) {
;     ...
;       G_BAR; G_WAIT_L(0); G_MMA(0, 1, At, B1); G_BAR;
;       G_LDA(At, 1, 1); G_STAGE(G_SA(1, 0), a3, cvA0, cvA1);
;       G_BAR; G_WAIT_L(0); G_MMA(1, 0, At, B0); G_BAR; G_SCHED;
;       G_STAGE(G_SB(1, 1), b3 + chB, cvB0, cvB1);
;       G_WAIT_V(6); G_BAR; G_MMA(1, 1, At, B1); G_BAR;
	s_waitcnt lgkmcnt(0)
	s_waitcnt lgkmcnt(0)
	v_mfma_f32_16x16x32_f16 v[118:121], v[192:195], v[146:149], v[118:121]
	v_mfma_f32_16x16x32_f16 v[114:117], v[200:203], v[146:149], v[114:117]
	v_mfma_f32_16x16x32_f16 v[102:105], v[192:195], v[168:171], v[102:105]
	v_mfma_f32_16x16x32_f16 v[98:101], v[200:203], v[168:171], v[98:101]
	v_mfma_f32_16x16x32_f16 v[86:89], v[192:195], v[176:179], v[86:89]
	v_mfma_f32_16x16x32_f16 v[82:85], v[200:203], v[176:179], v[82:85]
	v_mfma_f32_16x16x32_f16 v[70:73], v[192:195], v[184:187], v[70:73]
	v_mfma_f32_16x16x32_f16 v[66:69], v[200:203], v[184:187], v[66:69]
	v_mfma_f32_16x16x32_f16 v[118:121], v[196:199], v[164:167], v[118:121]
	v_mfma_f32_16x16x32_f16 v[114:117], v[204:207], v[164:167], v[114:117]
	v_mfma_f32_16x16x32_f16 v[102:105], v[196:199], v[172:175], v[102:105]
	v_mfma_f32_16x16x32_f16 v[98:101], v[204:207], v[172:175], v[98:101]
	v_mfma_f32_16x16x32_f16 v[86:89], v[196:199], v[180:183], v[86:89]
	v_mfma_f32_16x16x32_f16 v[82:85], v[204:207], v[180:183], v[82:85]
	v_mfma_f32_16x16x32_f16 v[70:73], v[196:199], v[188:191], v[70:73]
	v_mfma_f32_16x16x32_f16 v[66:69], v[204:207], v[188:191], v[66:69]
	s_mov_b32 m0, s79
	v_lshl_add_u64 v[208:209], v[212:213], 0, s[86:87]
	s_barrier
	ds_read_b128 v[146:149], v1 offset:49152
	ds_read_b128 v[164:167], v1 offset:50176
	ds_read_b128 v[168:171], v1 offset:51200
	ds_read_b128 v[172:175], v1 offset:52224
	ds_read_b128 v[176:179], v1 offset:53248
	ds_read_b128 v[180:183], v1 offset:54272
	ds_read_b128 v[184:187], v1 offset:55296
	ds_read_b128 v[188:191], v1 offset:56320
	global_load_lds_dwordx4 v[208:209], off
	v_lshl_add_u64 v[208:209], v[214:215], 0, s[86:87]
	s_mov_b32 m0, s83
	s_nop 0
	global_load_lds_dwordx4 v[208:209], off
	s_barrier
	s_waitcnt lgkmcnt(0)
	s_waitcnt lgkmcnt(0)
	v_mfma_f32_16x16x32_f16 v[62:65], v[130:133], v[146:149], v[62:65]
	v_mfma_f32_16x16x32_f16 v[58:61], v[138:141], v[146:149], v[58:61]
	v_mfma_f32_16x16x32_f16 v[46:49], v[130:133], v[168:171], v[46:49]
	v_mfma_f32_16x16x32_f16 v[42:45], v[138:141], v[168:171], v[42:45]
	v_mfma_f32_16x16x32_f16 v[30:33], v[130:133], v[176:179], v[30:33]
	v_mfma_f32_16x16x32_f16 v[26:29], v[138:141], v[176:179], v[26:29]
	v_mfma_f32_16x16x32_f16 v[14:17], v[130:133], v[184:187], v[14:17]
	v_mfma_f32_16x16x32_f16 v[10:13], v[138:141], v[184:187], v[10:13]
	v_mfma_f32_16x16x32_f16 v[62:65], v[134:137], v[164:167], v[62:65]
	v_mfma_f32_16x16x32_f16 v[58:61], v[142:145], v[164:167], v[58:61]
	v_mfma_f32_16x16x32_f16 v[46:49], v[134:137], v[172:175], v[46:49]
	v_mfma_f32_16x16x32_f16 v[42:45], v[142:145], v[172:175], v[42:45]
	v_mfma_f32_16x16x32_f16 v[30:33], v[134:137], v[180:183], v[30:33]
	v_mfma_f32_16x16x32_f16 v[26:29], v[142:145], v[180:183], v[26:29]
	v_mfma_f32_16x16x32_f16 v[14:17], v[134:137], v[188:191], v[14:17]
	v_mfma_f32_16x16x32_f16 v[10:13], v[142:145], v[188:191], v[10:13]
	s_barrier
	s_add_u32 s22, s22, 0x100080
	s_addc_u32 s23, s23, 0
	s_mov_b32 m0, s84
	v_lshl_add_u64 v[130:131], s[22:23], 0, v[150:151]
	global_load_lds_dwordx4 v[130:131], off
	v_lshl_add_u64 v[130:131], s[22:23], 0, v[152:153]
	s_mov_b32 m0, s85
	s_nop 0
	global_load_lds_dwordx4 v[130:131], off
	s_waitcnt vmcnt(6)
	s_barrier
	v_mfma_f32_16x16x32_f16 v[54:57], v[192:195], v[146:149], v[54:57]
	v_mfma_f32_16x16x32_f16 v[50:53], v[200:203], v[146:149], v[50:53]
	v_mfma_f32_16x16x32_f16 v[38:41], v[192:195], v[168:171], v[38:41]
	v_mfma_f32_16x16x32_f16 v[34:37], v[200:203], v[168:171], v[34:37]
	v_mfma_f32_16x16x32_f16 v[22:25], v[192:195], v[176:179], v[22:25]
	v_mfma_f32_16x16x32_f16 v[18:21], v[200:203], v[176:179], v[18:21]
	v_mfma_f32_16x16x32_f16 v[6:9], v[192:195], v[184:187], v[6:9]
	v_mfma_f32_16x16x32_f16 v[2:5], v[200:203], v[184:187], v[2:5]
	v_mfma_f32_16x16x32_f16 v[54:57], v[196:199], v[164:167], v[54:57]
	v_mfma_f32_16x16x32_f16 v[50:53], v[204:207], v[164:167], v[50:53]
	v_mfma_f32_16x16x32_f16 v[38:41], v[196:199], v[172:175], v[38:41]
	v_mfma_f32_16x16x32_f16 v[34:37], v[204:207], v[172:175], v[34:37]
	v_mfma_f32_16x16x32_f16 v[22:25], v[196:199], v[180:183], v[22:25]
	v_mfma_f32_16x16x32_f16 v[18:21], v[204:207], v[180:183], v[18:21]
	v_mfma_f32_16x16x32_f16 v[6:9], v[196:199], v[188:191], v[6:9]
	v_mfma_f32_16x16x32_f16 v[2:5], v[204:207], v[188:191], v[2:5]
	s_add_u32 s20, s20, 0x100
	s_addc_u32 s21, s21, 0
	s_add_u32 s46, s46, 0x100
	s_addc_u32 s74, s74, 0
	s_cmp_ge_i32 s91, s75
	s_mov_b32 s22, s91
	s_barrier
	s_cbranch_scc0 .LBB0_2656
	v_readlane_b32 s91, v254, 47
	s_mov_b32 s56, 0x8fff
	s_branch .LBB0_2659
